# k-loop hand-pipelining extended to the peerq and inproj GEMM loops (fragments of both k-steps prefetched, LDS-DMA issue interleaved 1 per 2 MFMAs, m0 from SALU)
# speedup vs baseline: 1.1511x; 1.0115x over previous
.LBB0_20:
	s_and_b32 s0, s19, 7
	s_mulk_i32 s0, 0x108
	s_ashr_i32 s26, s19, 3
	s_add_i32 s0, s0, s26
	v_mov_b32_e32 v26, v220
	s_ashr_i32 s16, s0, 4
	s_ashr_i32 s17, s16, 31
	v_lshlrev_b32_e32 v105, 4, v26
	v_and_b32_e32 v0, 32, v26
	v_bitop3_b32 v0, v105, v0, 48 bitop3:0x6c
	s_lshl_b32 s21, s2, 3
	s_and_b32 s20, s0, 15
	s_lshl_b64 s[0:1], s[16:17], 18
	v_lshrrev_b32_e32 v16, 2, v26
	v_lshrrev_b32_e32 v1, 1, v26
	v_lshrrev_b32_e32 v0, 1, v0
	v_ashrrev_i32_e32 v4, 3, v26
	s_add_u32 s22, s8, s0
	v_and_or_b32 v0, v1, 32, v0
	v_bfi_b32 v4, 15, v16, v4
	s_addc_u32 s23, s9, s1
	s_lshl_b32 s17, s20, 18
	v_lshlrev_b32_e32 v0, 1, v0
	v_mov_b32_e32 v1, v80
	v_ashrrev_i32_e32 v5, 31, v4
	v_add_u32_e32 v12, 0x1000, v105
	s_add_u32 s24, s3, s17
	v_lshl_add_u64 v[2:3], s[22:23], 0, v[0:1]
	v_lshlrev_b64 v[4:5], 11, v[4:5]
	v_readfirstlane_b32 s17, v105
	v_ashrrev_i32_e32 v8, 7, v12
	v_add_u32_e32 v17, 0x2000, v105
	v_lshl_add_u64 v[6:7], v[2:3], 0, v[4:5]
	s_mov_b32 m0, s17
	v_bfi_b32 v8, -16, v8, v16
	v_readfirstlane_b32 s17, v12
	v_ashrrev_i32_e32 v12, 7, v17
	v_add_u32_e32 v18, 0x3000, v105
	global_load_lds_dwordx4 v[6:7], off
	v_ashrrev_i32_e32 v9, 31, v8
	s_mov_b32 m0, s17
	v_bfi_b32 v12, -16, v12, v16
	v_readfirstlane_b32 s17, v17
	v_ashrrev_i32_e32 v17, 7, v18
	v_lshlrev_b64 v[8:9], 11, v[8:9]
	v_ashrrev_i32_e32 v13, 31, v12
	v_bfi_b32 v16, -16, v17, v16
	s_addc_u32 s25, s18, 0
	v_lshl_add_u64 v[10:11], v[2:3], 0, v[8:9]
	v_lshlrev_b64 v[12:13], 11, v[12:13]
	v_ashrrev_i32_e32 v17, 31, v16
	global_load_lds_dwordx4 v[10:11], off
	v_lshl_add_u64 v[14:15], v[2:3], 0, v[12:13]
	s_mov_b32 m0, s17
	v_lshlrev_b64 v[16:17], 11, v[16:17]
	v_readfirstlane_b32 s17, v18
	v_lshl_add_u64 v[18:19], s[24:25], 0, v[0:1]
	v_add_u32_e32 v1, 0x4000, v105
	global_load_lds_dwordx4 v[14:15], off
	v_lshl_add_u64 v[2:3], v[2:3], 0, v[16:17]
	s_mov_b32 m0, s17
	v_readfirstlane_b32 s17, v1
	v_add_u32_e32 v1, 0x5000, v105
	global_load_lds_dwordx4 v[2:3], off
	v_lshl_add_u64 v[20:21], v[18:19], 0, v[4:5]
	s_mov_b32 m0, s17
	v_readfirstlane_b32 s17, v1
	v_add_u32_e32 v1, 0x6000, v105
	global_load_lds_dwordx4 v[20:21], off
	v_lshl_add_u64 v[22:23], v[18:19], 0, v[8:9]
	s_mov_b32 m0, s17
	v_readfirstlane_b32 s17, v1
	v_add_u32_e32 v1, 0x7000, v105
	global_load_lds_dwordx4 v[22:23], off
	v_lshl_add_u64 v[24:25], v[18:19], 0, v[12:13]
	s_mov_b32 m0, s17
	v_readfirstlane_b32 s17, v1
	v_add_u32_e32 v1, 0x8000, v105
	global_load_lds_dwordx4 v[24:25], off
	v_lshl_add_u64 v[18:19], v[18:19], 0, v[16:17]
	s_mov_b32 m0, s17
	s_mov_b64 s[22:23], 0x80
	v_readfirstlane_b32 s17, v1
	v_add_u32_e32 v1, 0x9000, v105
	global_load_lds_dwordx4 v[18:19], off
	v_lshl_add_u64 v[6:7], v[6:7], 0, s[22:23]
	s_mov_b32 m0, s17
	v_readfirstlane_b32 s17, v1
	v_add_u32_e32 v1, 0xa000, v105
	global_load_lds_dwordx4 v[6:7], off
	v_lshl_add_u64 v[6:7], v[10:11], 0, s[22:23]
	s_mov_b32 m0, s17
	v_readfirstlane_b32 s17, v1
	v_add_u32_e32 v1, 0xb000, v105
	global_load_lds_dwordx4 v[6:7], off
	v_lshl_add_u64 v[6:7], v[14:15], 0, s[22:23]
	s_mov_b32 m0, s17
	v_readfirstlane_b32 s17, v1
	v_add_u32_e32 v1, 0xc000, v105
	global_load_lds_dwordx4 v[6:7], off
	v_lshl_add_u64 v[2:3], v[2:3], 0, s[22:23]
	s_mov_b32 m0, s17
	v_readfirstlane_b32 s17, v1
	v_add_u32_e32 v1, 0xd000, v105
	global_load_lds_dwordx4 v[2:3], off
	v_lshl_add_u64 v[2:3], v[20:21], 0, s[22:23]
	s_mov_b32 m0, s17
	v_readfirstlane_b32 s17, v1
	v_add_u32_e32 v1, 0xe000, v105
	global_load_lds_dwordx4 v[2:3], off
	v_lshl_add_u64 v[2:3], v[22:23], 0, s[22:23]
	s_mov_b32 m0, s17
	v_readfirstlane_b32 s17, v1
	v_add_u32_e32 v1, 0xf000, v105
	global_load_lds_dwordx4 v[2:3], off
	v_lshl_add_u64 v[2:3], v[24:25], 0, s[22:23]
	s_mov_b32 m0, s17
	v_readfirstlane_b32 s17, v1
	global_load_lds_dwordx4 v[2:3], off
	v_lshl_add_u64 v[2:3], v[18:19], 0, s[22:23]
	s_mov_b32 m0, s17
	v_lshlrev_b32_e32 v1, 6, v26
	global_load_lds_dwordx4 v[2:3], off
	v_lshlrev_b32_e32 v2, 2, v26
	v_and_b32_e32 v3, 48, v26
	v_bitop3_b32 v2, v2, v3, 32 bitop3:0x6c
	s_movk_i32 s17, 0x3c0
	v_and_or_b32 v2, v1, s17, v2
	s_movk_i32 s17, 0xe000
	v_and_or_b32 v104, v1, s17, v2
	v_lshlrev_b32_e32 v1, 7, v26
	s_movk_i32 s17, 0x2000
	s_add_i32 s21, s21, s26
	v_and_or_b32 v73, v1, s17, v2
	s_and_b32 s17, s21, 15
	v_readlane_b32 s22, v249, 19
	v_readlane_b32 s23, v249, 20
	s_lshl_b32 s22, s17, 18
	s_mov_b32 s17, s23
	v_lshl_add_u64 v[2:3], s[22:23], 0, v[16:17]
	v_or_b32_e32 v2, v2, v0
	v_lshl_add_u64 v[74:75], s[12:13], 0, v[2:3]
	v_lshl_add_u64 v[2:3], s[22:23], 0, v[12:13]
	v_or_b32_e32 v2, v2, v0
	v_lshl_add_u64 v[76:77], s[12:13], 0, v[2:3]
	v_lshl_add_u64 v[2:3], s[22:23], 0, v[8:9]
	v_or_b32_e32 v2, v2, v0
	v_lshl_add_u64 v[78:79], s[12:13], 0, v[2:3]
	v_lshl_add_u64 v[2:3], s[22:23], 0, v[4:5]
	v_or_b32_e32 v2, v2, v0
	v_lshl_add_u64 v[82:83], s[12:13], 0, v[2:3]
	v_lshl_add_u64 v[2:3], s[0:1], 0, v[16:17]
	v_or_b32_e32 v2, v2, v0
	v_lshl_add_u64 v[84:85], s[14:15], 0, v[2:3]
	v_lshl_add_u64 v[2:3], s[0:1], 0, v[12:13]
	v_or_b32_e32 v2, v2, v0
	v_lshl_add_u64 v[86:87], s[14:15], 0, v[2:3]
	v_lshl_add_u64 v[2:3], s[0:1], 0, v[8:9]
	v_or_b32_e32 v2, v2, v0
	v_lshl_add_u64 v[88:89], s[14:15], 0, v[2:3]
	v_lshl_add_u64 v[2:3], s[0:1], 0, v[4:5]
	v_writelane_b32 v249, s16, 19
	v_or_b32_e32 v2, v2, v0
	v_mov_b32_e32 v0, 0
	v_writelane_b32 v249, s17, 20
	v_lshl_add_u64 v[90:91], s[14:15], 0, v[2:3]
	s_mov_b64 s[0:1], 0
	s_mov_b32 s17, 0
	v_mov_b32_e32 v1, v0
	v_mov_b32_e32 v2, v0
	v_mov_b32_e32 v3, v0
	v_mov_b32_e32 v4, v0
	v_mov_b32_e32 v5, v0
	v_mov_b32_e32 v6, v0
	v_mov_b32_e32 v7, v0
	v_mov_b32_e32 v8, v0
	v_mov_b32_e32 v9, v0
	v_mov_b32_e32 v10, v0
	v_mov_b32_e32 v11, v0
	v_mov_b32_e32 v12, v0
	v_mov_b32_e32 v13, v0
	v_mov_b32_e32 v14, v0
	v_mov_b32_e32 v15, v0
	v_mov_b32_e32 v16, v0
	v_mov_b32_e32 v17, v0
	v_mov_b32_e32 v18, v0
	v_mov_b32_e32 v19, v0
	v_mov_b32_e32 v20, v0
	v_mov_b32_e32 v21, v0
	v_mov_b32_e32 v22, v0
	v_mov_b32_e32 v23, v0
	v_mov_b32_e32 v24, v0
	v_mov_b32_e32 v25, v0
	v_mov_b32_e32 v26, v0
	v_mov_b32_e32 v27, v0
	v_mov_b32_e32 v28, v0
	v_mov_b32_e32 v29, v0
	v_mov_b32_e32 v30, v0
	v_mov_b32_e32 v31, v0
	v_mov_b32_e32 v32, v0
	v_mov_b32_e32 v33, v0
	v_mov_b32_e32 v34, v0
	v_mov_b32_e32 v35, v0
	v_mov_b32_e32 v36, v0
	v_mov_b32_e32 v37, v0
	v_mov_b32_e32 v38, v0
	v_mov_b32_e32 v39, v0
	v_mov_b32_e32 v40, v0
	v_mov_b32_e32 v41, v0
	v_mov_b32_e32 v42, v0
	v_mov_b32_e32 v43, v0
	v_mov_b32_e32 v44, v0
	v_mov_b32_e32 v45, v0
	v_mov_b32_e32 v46, v0
	v_mov_b32_e32 v47, v0
	v_mov_b32_e32 v48, v0
	v_mov_b32_e32 v49, v0
	v_mov_b32_e32 v50, v0
	v_mov_b32_e32 v51, v0
	v_mov_b32_e32 v52, v0
	v_mov_b32_e32 v53, v0
	v_mov_b32_e32 v54, v0
	v_mov_b32_e32 v55, v0
	v_mov_b32_e32 v56, v0
	v_mov_b32_e32 v57, v0
	v_mov_b32_e32 v58, v0
	v_mov_b32_e32 v59, v0
	v_mov_b32_e32 v60, v0
	v_mov_b32_e32 v61, v0
	v_mov_b32_e32 v62, v0
	v_mov_b32_e32 v63, v0
	v_readfirstlane_b32 s60, v105
.LBB0_21:
	s_and_b32 s21, s17, 0x8000
	s_waitcnt vmcnt(8)
	s_barrier
	v_add_u32_e32 v140, s21, v104
	v_or_b32_e32 v141, s21, v73
	s_add_u32 s61, s60, s21
	ds_read_b128 v[106:109], v140
	ds_read_b128 v[124:127], v141 offset:16384
	ds_read_b128 v[128:131], v141 offset:18432
	ds_read_b128 v[132:135], v141 offset:20480
	ds_read_b128 v[136:139], v141 offset:22528
	ds_read_b128 v[110:113], v140 offset:2048
	ds_read_b128 v[116:119], v140 offset:4096
	ds_read_b128 v[120:123], v140 offset:6144
	s_waitcnt lgkmcnt(6)
	v_mfma_f32_16x16x32_bf16 v[60:63], v[106:109], v[124:127], v[60:63]
	ds_read_b128 v[196:199], v140 offset:1024
	s_waitcnt lgkmcnt(6)
	v_mfma_f32_16x16x32_bf16 v[56:59], v[106:109], v[128:131], v[56:59]
	ds_read_b128 v[212:215], v141 offset:17408
	s_waitcnt lgkmcnt(6)
	v_mfma_f32_16x16x32_bf16 v[52:55], v[106:109], v[132:135], v[52:55]
	ds_read_b128 v[216:219], v141 offset:19456
	s_waitcnt lgkmcnt(6)
	v_mfma_f32_16x16x32_bf16 v[48:51], v[106:109], v[136:139], v[48:51]
	ds_read_b128 v[240:243], v141 offset:21504
	ds_read_b128 v[244:247], v141 offset:23552
	s_waitcnt lgkmcnt(7)
	v_mfma_f32_16x16x32_bf16 v[44:47], v[110:113], v[124:127], v[44:47]
	v_mfma_f32_16x16x32_bf16 v[40:43], v[110:113], v[128:131], v[40:43]
	v_mfma_f32_16x16x32_bf16 v[36:39], v[110:113], v[132:135], v[36:39]
	v_mfma_f32_16x16x32_bf16 v[32:35], v[110:113], v[136:139], v[32:35]
	ds_read_b128 v[200:203], v140 offset:3072
	ds_read_b128 v[204:207], v140 offset:5120
	s_waitcnt lgkmcnt(8)
	v_mfma_f32_16x16x32_bf16 v[28:31], v[116:119], v[124:127], v[28:31]
	v_mfma_f32_16x16x32_bf16 v[24:27], v[116:119], v[128:131], v[24:27]
	v_mfma_f32_16x16x32_bf16 v[20:23], v[116:119], v[132:135], v[20:23]
	v_mfma_f32_16x16x32_bf16 v[16:19], v[116:119], v[136:139], v[16:19]
	ds_read_b128 v[208:211], v140 offset:7168
	s_waitcnt lgkmcnt(8)
	v_mfma_f32_16x16x32_bf16 v[12:15], v[120:123], v[124:127], v[12:15]
	v_mfma_f32_16x16x32_bf16 v[8:11], v[120:123], v[128:131], v[8:11]
	v_mfma_f32_16x16x32_bf16 v[4:7], v[120:123], v[132:135], v[4:7]
	v_mfma_f32_16x16x32_bf16 v[0:3], v[120:123], v[136:139], v[0:3]
	s_waitcnt lgkmcnt(0)
	s_barrier
	s_mov_b32 m0, s61
	v_lshl_add_u64 v[106:107], v[90:91], 0, s[0:1]
	v_mfma_f32_16x16x32_bf16 v[60:63], v[196:199], v[212:215], v[60:63]
	global_load_lds_dwordx4 v[106:107], off
	v_mfma_f32_16x16x32_bf16 v[56:59], v[196:199], v[216:219], v[56:59]
	s_add_u32 m0, s61, 0x1000
	v_lshl_add_u64 v[108:109], v[88:89], 0, s[0:1]
	v_mfma_f32_16x16x32_bf16 v[52:55], v[196:199], v[240:243], v[52:55]
	global_load_lds_dwordx4 v[108:109], off
	v_mfma_f32_16x16x32_bf16 v[48:51], v[196:199], v[244:247], v[48:51]
	s_add_u32 m0, s61, 0x2000
	v_lshl_add_u64 v[110:111], v[86:87], 0, s[0:1]
	v_mfma_f32_16x16x32_bf16 v[44:47], v[200:203], v[212:215], v[44:47]
	global_load_lds_dwordx4 v[110:111], off
	v_mfma_f32_16x16x32_bf16 v[40:43], v[200:203], v[216:219], v[40:43]
	s_add_u32 m0, s61, 0x3000
	v_lshl_add_u64 v[112:113], v[84:85], 0, s[0:1]
	v_mfma_f32_16x16x32_bf16 v[36:39], v[200:203], v[240:243], v[36:39]
	global_load_lds_dwordx4 v[112:113], off
	v_mfma_f32_16x16x32_bf16 v[32:35], v[200:203], v[244:247], v[32:35]
	s_add_u32 m0, s61, 0x4000
	v_lshl_add_u64 v[116:117], v[82:83], 0, s[0:1]
	v_mfma_f32_16x16x32_bf16 v[28:31], v[204:207], v[212:215], v[28:31]
	global_load_lds_dwordx4 v[116:117], off
	v_mfma_f32_16x16x32_bf16 v[24:27], v[204:207], v[216:219], v[24:27]
	s_add_u32 m0, s61, 0x5000
	v_lshl_add_u64 v[118:119], v[78:79], 0, s[0:1]
	v_mfma_f32_16x16x32_bf16 v[20:23], v[204:207], v[240:243], v[20:23]
	global_load_lds_dwordx4 v[118:119], off
	v_mfma_f32_16x16x32_bf16 v[16:19], v[204:207], v[244:247], v[16:19]
	s_add_u32 m0, s61, 0x6000
	v_lshl_add_u64 v[120:121], v[76:77], 0, s[0:1]
	v_mfma_f32_16x16x32_bf16 v[12:15], v[208:211], v[212:215], v[12:15]
	global_load_lds_dwordx4 v[120:121], off
	v_mfma_f32_16x16x32_bf16 v[8:11], v[208:211], v[216:219], v[8:11]
	s_add_u32 m0, s61, 0x7000
	v_lshl_add_u64 v[122:123], v[74:75], 0, s[0:1]
	v_mfma_f32_16x16x32_bf16 v[4:7], v[208:211], v[240:243], v[4:7]
	global_load_lds_dwordx4 v[122:123], off
	v_mfma_f32_16x16x32_bf16 v[0:3], v[208:211], v[244:247], v[0:3]
	s_add_u32 s0, s0, 0x80
	s_addc_u32 s1, s1, 0
	s_add_i32 s17, s17, 0x8000
	s_cmpk_lg_i32 s0, 0x700
	s_cbranch_scc1 .LBB0_21
	s_waitcnt vmcnt(8)
	s_barrier
	ds_read_b128 v[74:77], v104
	ds_read_b128 v[82:85], v104 offset:2048
	ds_read_b128 v[86:89], v104 offset:4096
	ds_read_b128 v[106:109], v104 offset:6144
	ds_read_b128 v[110:113], v73 offset:16384
	ds_read_b128 v[116:119], v73 offset:18432
	ds_read_b128 v[120:123], v73 offset:20480
	ds_read_b128 v[124:127], v73 offset:22528
	s_waitcnt lgkmcnt(0)
	v_mfma_f32_16x16x32_bf16 v[60:63], v[74:77], v[110:113], v[60:63]
	v_readlane_b32 s0, v249, 30
	v_readlane_b32 s1, v249, 31
	v_readlane_b32 s22, v249, 41
	v_mfma_f32_16x16x32_bf16 v[56:59], v[74:77], v[116:119], v[56:59]
	v_readlane_b32 s23, v249, 42
	s_movk_i32 s21, 0x6f
	v_mfma_f32_16x16x32_bf16 v[52:55], v[74:77], v[120:123], v[52:55]
	v_mfma_f32_16x16x32_bf16 v[48:51], v[74:77], v[124:127], v[48:51]
	v_mfma_f32_16x16x32_bf16 v[44:47], v[82:85], v[110:113], v[44:47]
	v_mfma_f32_16x16x32_bf16 v[40:43], v[82:85], v[116:119], v[40:43]
	v_mfma_f32_16x16x32_bf16 v[36:39], v[82:85], v[120:123], v[36:39]
	v_mfma_f32_16x16x32_bf16 v[32:35], v[82:85], v[124:127], v[32:35]
	v_mfma_f32_16x16x32_bf16 v[28:31], v[86:89], v[110:113], v[28:31]
	v_mfma_f32_16x16x32_bf16 v[24:27], v[86:89], v[116:119], v[24:27]
	v_mfma_f32_16x16x32_bf16 v[20:23], v[86:89], v[120:123], v[20:23]
	v_mfma_f32_16x16x32_bf16 v[16:19], v[86:89], v[124:127], v[16:19]
	v_mfma_f32_16x16x32_bf16 v[12:15], v[106:109], v[110:113], v[12:15]
	v_mfma_f32_16x16x32_bf16 v[8:11], v[106:109], v[116:119], v[8:11]
	v_mfma_f32_16x16x32_bf16 v[4:7], v[106:109], v[120:123], v[4:7]
	v_mfma_f32_16x16x32_bf16 v[0:3], v[106:109], v[124:127], v[0:3]
	ds_read_b128 v[74:77], v104 offset:1024
	ds_read_b128 v[82:85], v104 offset:3072
	ds_read_b128 v[86:89], v104 offset:5120
	ds_read_b128 v[106:109], v104 offset:7168
	ds_read_b128 v[110:113], v73 offset:17408
	ds_read_b128 v[116:119], v73 offset:19456
	ds_read_b128 v[120:123], v73 offset:21504
	ds_read_b128 v[124:127], v73 offset:23552
	s_waitcnt lgkmcnt(0)
	s_barrier
	s_waitcnt vmcnt(0)
	s_barrier
	s_waitcnt lgkmcnt(3)
	v_mfma_f32_16x16x32_bf16 v[60:63], v[74:77], v[110:113], v[60:63]
	s_waitcnt lgkmcnt(2)
	v_mfma_f32_16x16x32_bf16 v[56:59], v[74:77], v[116:119], v[56:59]
	s_waitcnt lgkmcnt(1)
	v_mfma_f32_16x16x32_bf16 v[52:55], v[74:77], v[120:123], v[52:55]
	s_waitcnt lgkmcnt(0)
	v_mfma_f32_16x16x32_bf16 v[48:51], v[74:77], v[124:127], v[48:51]
	v_mfma_f32_16x16x32_bf16 v[44:47], v[82:85], v[110:113], v[44:47]
	v_mfma_f32_16x16x32_bf16 v[40:43], v[82:85], v[116:119], v[40:43]
	v_mfma_f32_16x16x32_bf16 v[36:39], v[82:85], v[120:123], v[36:39]
	v_mfma_f32_16x16x32_bf16 v[32:35], v[82:85], v[124:127], v[32:35]
	v_mfma_f32_16x16x32_bf16 v[28:31], v[86:89], v[110:113], v[28:31]
	v_mfma_f32_16x16x32_bf16 v[24:27], v[86:89], v[116:119], v[24:27]
	v_mfma_f32_16x16x32_bf16 v[20:23], v[86:89], v[120:123], v[20:23]
	v_mfma_f32_16x16x32_bf16 v[16:19], v[86:89], v[124:127], v[16:19]
	v_mfma_f32_16x16x32_bf16 v[12:15], v[106:109], v[110:113], v[12:15]
	v_mfma_f32_16x16x32_bf16 v[8:11], v[106:109], v[116:119], v[8:11]
	v_mfma_f32_16x16x32_bf16 v[4:7], v[106:109], v[120:123], v[4:7]
	v_mfma_f32_16x16x32_bf16 v[0:3], v[106:109], v[124:127], v[0:3]
	ds_read_b128 v[74:77], v104 offset:32768
	ds_read_b128 v[82:85], v104 offset:34816
	ds_read_b128 v[86:89], v104 offset:36864
	ds_read_b128 v[106:109], v104 offset:38912
	ds_read_b128 v[110:113], v73 offset:49152
	ds_read_b128 v[116:119], v73 offset:51200
	ds_read_b128 v[120:123], v73 offset:53248
	ds_read_b128 v[124:127], v73 offset:55296
	s_waitcnt lgkmcnt(3)
	v_mfma_f32_16x16x32_bf16 v[60:63], v[74:77], v[110:113], v[60:63]
	s_waitcnt lgkmcnt(2)
	v_mfma_f32_16x16x32_bf16 v[56:59], v[74:77], v[116:119], v[56:59]
	s_waitcnt lgkmcnt(1)
	v_mfma_f32_16x16x32_bf16 v[52:55], v[74:77], v[120:123], v[52:55]
	s_waitcnt lgkmcnt(0)
	v_mfma_f32_16x16x32_bf16 v[48:51], v[74:77], v[124:127], v[48:51]
	v_mfma_f32_16x16x32_bf16 v[44:47], v[82:85], v[110:113], v[44:47]
	v_mfma_f32_16x16x32_bf16 v[40:43], v[82:85], v[116:119], v[40:43]
	v_mfma_f32_16x16x32_bf16 v[36:39], v[82:85], v[120:123], v[36:39]
	v_mfma_f32_16x16x32_bf16 v[32:35], v[82:85], v[124:127], v[32:35]
	v_mfma_f32_16x16x32_bf16 v[28:31], v[86:89], v[110:113], v[28:31]
	v_mfma_f32_16x16x32_bf16 v[24:27], v[86:89], v[116:119], v[24:27]
	v_mfma_f32_16x16x32_bf16 v[20:23], v[86:89], v[120:123], v[20:23]
	v_mfma_f32_16x16x32_bf16 v[16:19], v[86:89], v[124:127], v[16:19]
	v_mfma_f32_16x16x32_bf16 v[12:15], v[106:109], v[110:113], v[12:15]
	v_mfma_f32_16x16x32_bf16 v[8:11], v[106:109], v[116:119], v[8:11]
	v_mfma_f32_16x16x32_bf16 v[4:7], v[106:109], v[120:123], v[4:7]
	v_mfma_f32_16x16x32_bf16 v[0:3], v[106:109], v[124:127], v[0:3]
	ds_read_b128 v[74:77], v104 offset:33792
	ds_read_b128 v[82:85], v104 offset:35840
	ds_read_b128 v[86:89], v104 offset:37888
	ds_read_b128 v[104:107], v104 offset:39936
	ds_read_b128 v[108:111], v73 offset:50176
	ds_read_b128 v[116:119], v73 offset:52224
	ds_read_b128 v[120:123], v73 offset:54272
	ds_read_b128 v[124:127], v73 offset:56320
	s_waitcnt lgkmcnt(0)
	s_barrier
	s_waitcnt lgkmcnt(0)
	s_barrier
	s_load_dwordx2 s[0:1], s[0:1], 0x130
	v_mov_b32_e32 v73, v80
	v_mfma_f32_16x16x32_bf16 v[60:63], v[74:77], v[108:111], v[60:63]
	s_waitcnt lgkmcnt(0)
	s_add_u32 s0, s0, s22
	s_addc_u32 s1, s1, s23
	s_lshl_b32 s17, s20, 15
	s_add_u32 s0, s0, s17
	s_addc_u32 s1, s1, 0
	v_mfma_f32_16x16x32_bf16 v[56:59], v[74:77], v[116:119], v[56:59]
	s_mov_b64 s[22:23], 0x80
	s_movk_i32 s17, 0x7f
	v_mfma_f32_16x16x32_bf16 v[52:55], v[74:77], v[120:123], v[52:55]
	v_mfma_f32_16x16x32_bf16 v[48:51], v[74:77], v[124:127], v[48:51]
	v_lshl_add_u64 v[74:75], s[0:1], 0, v[72:73]
	v_add_u32_e32 v73, 0x9000, v92
	v_lshl_add_u64 v[76:77], v[64:65], 1, v[74:75]
	v_readfirstlane_b32 s0, v73
	v_add_u32_e32 v73, 0xa000, v92
	s_mov_b32 m0, s0
	v_readfirstlane_b32 s0, v73
	v_add_u32_e32 v73, 0xb000, v92
	global_load_lds_dwordx4 v[76:77], off
	v_lshl_add_u64 v[78:79], v[66:67], 1, v[74:75]
	s_mov_b32 m0, s0
	v_readfirstlane_b32 s0, v73
	v_add_u32_e32 v73, 0xc000, v92
	v_mfma_f32_16x16x32_bf16 v[44:47], v[82:85], v[108:111], v[44:47]
	global_load_lds_dwordx4 v[78:79], off
	s_mov_b32 m0, s0
	v_mfma_f32_16x16x32_bf16 v[40:43], v[82:85], v[116:119], v[40:43]
	v_readfirstlane_b32 s0, v73
	v_add_u32_e32 v73, 0xd000, v92
	v_lshl_add_u64 v[76:77], v[76:77], 0, s[22:23]
	v_mfma_f32_16x16x32_bf16 v[36:39], v[82:85], v[120:123], v[36:39]
	v_mfma_f32_16x16x32_bf16 v[32:35], v[82:85], v[124:127], v[32:35]
	v_lshl_add_u64 v[82:83], v[68:69], 1, v[74:75]
	global_load_lds_dwordx4 v[82:83], off
	v_lshl_add_u64 v[74:75], v[70:71], 1, v[74:75]
	s_mov_b32 m0, s0
	v_readfirstlane_b32 s0, v73
	v_add_u32_e32 v73, 0xe000, v92
	global_load_lds_dwordx4 v[74:75], off
	s_mov_b32 m0, s0
	v_readfirstlane_b32 s0, v73
	v_add_u32_e32 v73, 0xf000, v92
	global_load_lds_dwordx4 v[76:77], off
	v_lshl_add_u64 v[76:77], v[78:79], 0, s[22:23]
	s_mov_b32 m0, s0
	v_readfirstlane_b32 s0, v73
	v_add_u32_e32 v73, 0xd000, v93
	global_load_lds_dwordx4 v[76:77], off
	v_lshl_add_u64 v[76:77], v[82:83], 0, s[22:23]
	s_mov_b32 m0, s0
	v_readfirstlane_b32 s0, v73
	global_load_lds_dwordx4 v[76:77], off
	v_lshl_add_u64 v[74:75], v[74:75], 0, s[22:23]
	s_mov_b32 m0, s0
	v_mfma_f32_16x16x32_bf16 v[28:31], v[86:89], v[108:111], v[28:31]
	global_load_lds_dwordx4 v[74:75], off
	v_lshl_or_b32 v74, s20, 9, v98
	global_load_dword v73, v74, s[10:11]
	v_mfma_f32_16x16x32_bf16 v[24:27], v[86:89], v[116:119], v[24:27]
	s_movk_i32 s22, 0x5f
	s_movk_i32 s23, 0x4f
	s_waitcnt vmcnt(0)
	v_add_f32_e32 v60, v60, v73
	v_bfe_u32 v75, v60, 16, 1
	v_add3_u32 v75, v60, v75, s33
	v_add_u32_e32 v60, v96, v97
	v_add_f32_e32 v61, v61, v73
	ds_write_b16_d16_hi v60, v75
	v_bfe_u32 v75, v61, 16, 1
	v_add3_u32 v61, v61, v75, s33
	ds_write_b16_d16_hi v60, v61 offset:272
	v_add_f32_e32 v61, v62, v73
	v_bfe_u32 v62, v61, 16, 1
	v_add3_u32 v61, v61, v62, s33
	ds_write_b16_d16_hi v60, v61 offset:544
	v_add_f32_e32 v61, v63, v73
	v_bfe_u32 v62, v61, 16, 1
	v_add3_u32 v61, v61, v62, s33
	ds_write_b16_d16_hi v60, v61 offset:816
	global_load_dword v61, v74, s[10:11] offset:64
	v_add_f32_e32 v44, v44, v73
	v_add_f32_e32 v28, v28, v73
	v_mfma_f32_16x16x32_bf16 v[20:23], v[86:89], v[120:123], v[20:23]
	s_waitcnt vmcnt(0)
	v_add_f32_e32 v56, v56, v61
	v_bfe_u32 v62, v56, 16, 1
	v_add3_u32 v56, v56, v62, s33
	ds_write_b16_d16_hi v60, v56 offset:32
	v_add_f32_e32 v56, v57, v61
	v_bfe_u32 v57, v56, 16, 1
	v_add3_u32 v56, v56, v57, s33
	ds_write_b16_d16_hi v60, v56 offset:304
	v_add_f32_e32 v56, v58, v61
	v_bfe_u32 v57, v56, 16, 1
	v_add3_u32 v56, v56, v57, s33
	ds_write_b16_d16_hi v60, v56 offset:576
	v_add_f32_e32 v56, v59, v61
	v_bfe_u32 v57, v56, 16, 1
	v_add3_u32 v56, v56, v57, s33
	ds_write_b16_d16_hi v60, v56 offset:848
	global_load_dword v56, v74, s[10:11] offset:128
	v_add_f32_e32 v40, v40, v61
	v_add_f32_e32 v24, v24, v61
	v_mfma_f32_16x16x32_bf16 v[16:19], v[86:89], v[124:127], v[16:19]
	s_waitcnt vmcnt(0)
	v_add_f32_e32 v52, v52, v56
	v_bfe_u32 v57, v52, 16, 1
	v_add3_u32 v52, v52, v57, s33
	ds_write_b16_d16_hi v60, v52 offset:64
	v_add_f32_e32 v52, v53, v56
	v_bfe_u32 v53, v52, 16, 1
	v_add3_u32 v52, v52, v53, s33
	ds_write_b16_d16_hi v60, v52 offset:336
	v_add_f32_e32 v52, v54, v56
	v_bfe_u32 v53, v52, 16, 1
	v_add3_u32 v52, v52, v53, s33
	ds_write_b16_d16_hi v60, v52 offset:608
	v_add_f32_e32 v52, v55, v56
	v_bfe_u32 v53, v52, 16, 1
	v_add3_u32 v52, v52, v53, s33
	ds_write_b16_d16_hi v60, v52 offset:880
	global_load_dword v52, v74, s[10:11] offset:192
	v_add_f32_e32 v36, v36, v56
	v_add_f32_e32 v20, v20, v56
	v_mfma_f32_16x16x32_bf16 v[12:15], v[104:107], v[108:111], v[12:15]
	s_waitcnt vmcnt(0)
	v_add_f32_e32 v48, v48, v52
	v_bfe_u32 v53, v48, 16, 1
	v_add3_u32 v48, v48, v53, s33
	ds_write_b16_d16_hi v60, v48 offset:96
	v_add_f32_e32 v48, v49, v52
	v_bfe_u32 v49, v48, 16, 1
	v_add3_u32 v48, v48, v49, s33
	ds_write_b16_d16_hi v60, v48 offset:368
	v_add_f32_e32 v48, v50, v52
	v_bfe_u32 v49, v48, 16, 1
	v_add3_u32 v48, v48, v49, s33
	ds_write_b16_d16_hi v60, v48 offset:640
	v_add_f32_e32 v48, v51, v52
	v_bfe_u32 v49, v48, 16, 1
	v_add3_u32 v48, v48, v49, s33
	ds_write_b16_d16_hi v60, v48 offset:912
	v_bfe_u32 v48, v44, 16, 1
	v_add3_u32 v44, v44, v48, s33
	ds_write_b16_d16_hi v60, v44 offset:4352
	v_add_f32_e32 v44, v45, v73
	v_bfe_u32 v45, v44, 16, 1
	v_add3_u32 v44, v44, v45, s33
	ds_write_b16_d16_hi v60, v44 offset:4624
	v_add_f32_e32 v44, v46, v73
	v_bfe_u32 v45, v44, 16, 1
	v_add3_u32 v44, v44, v45, s33
	ds_write_b16_d16_hi v100, v44 offset:272
	v_add_f32_e32 v44, v47, v73
	v_bfe_u32 v45, v44, 16, 1
	v_add3_u32 v44, v44, v45, s33
	ds_write_b16_d16_hi v100, v44 offset:544
	v_bfe_u32 v44, v40, 16, 1
	v_add3_u32 v40, v40, v44, s33
	ds_write_b16_d16_hi v60, v40 offset:4384
	v_add_f32_e32 v40, v41, v61
	v_bfe_u32 v41, v40, 16, 1
	v_add3_u32 v40, v40, v41, s33
	ds_write_b16_d16_hi v100, v40 offset:32
	v_add_f32_e32 v40, v42, v61
	v_bfe_u32 v41, v40, 16, 1
	v_add3_u32 v40, v40, v41, s33
	ds_write_b16_d16_hi v100, v40 offset:304
	v_add_f32_e32 v40, v43, v61
	v_bfe_u32 v41, v40, 16, 1
	v_add3_u32 v40, v40, v41, s33
	ds_write_b16_d16_hi v100, v40 offset:576
	v_bfe_u32 v40, v36, 16, 1
	v_add3_u32 v36, v36, v40, s33
	ds_write_b16_d16_hi v60, v36 offset:4416
	v_add_f32_e32 v36, v37, v56
	v_bfe_u32 v37, v36, 16, 1
	v_add3_u32 v36, v36, v37, s33
	ds_write_b16_d16_hi v100, v36 offset:64
	v_add_f32_e32 v36, v38, v56
	v_bfe_u32 v37, v36, 16, 1
	v_add3_u32 v36, v36, v37, s33
	ds_write_b16_d16_hi v100, v36 offset:336
	v_add_f32_e32 v36, v39, v56
	v_bfe_u32 v37, v36, 16, 1
	v_add3_u32 v36, v36, v37, s33
	v_add_f32_e32 v32, v32, v52
	ds_write_b16_d16_hi v100, v36 offset:608
	v_bfe_u32 v36, v32, 16, 1
	v_add3_u32 v32, v32, v36, s33
	ds_write_b16_d16_hi v60, v32 offset:4448
	v_add_f32_e32 v32, v33, v52
	v_bfe_u32 v33, v32, 16, 1
	v_add3_u32 v32, v32, v33, s33
	ds_write_b16_d16_hi v100, v32 offset:96
	v_add_f32_e32 v32, v34, v52
	v_bfe_u32 v33, v32, 16, 1
	v_add3_u32 v32, v32, v33, s33
	ds_write_b16_d16_hi v100, v32 offset:368
	v_add_f32_e32 v32, v35, v52
	v_bfe_u32 v33, v32, 16, 1
	v_add3_u32 v32, v32, v33, s33
	ds_write_b16_d16_hi v100, v32 offset:640
	v_bfe_u32 v32, v28, 16, 1
	v_add3_u32 v28, v28, v32, s33
	ds_write_b16_d16_hi v100, v28 offset:4080
	v_add_f32_e32 v28, v29, v73
	v_bfe_u32 v29, v28, 16, 1
	v_add3_u32 v28, v28, v29, s33
	ds_write_b16_d16_hi v100, v28 offset:4352
	v_add_f32_e32 v28, v30, v73
	v_bfe_u32 v29, v28, 16, 1
	v_add3_u32 v28, v28, v29, s33
	ds_write_b16_d16_hi v100, v28 offset:4624
	v_add_f32_e32 v28, v31, v73
	v_bfe_u32 v29, v28, 16, 1
	v_add3_u32 v28, v28, v29, s33
	ds_write_b16_d16_hi v100, v28 offset:4896
	v_bfe_u32 v28, v24, 16, 1
	v_add3_u32 v24, v24, v28, s33
	ds_write_b16_d16_hi v100, v24 offset:4112
	v_add_f32_e32 v24, v25, v61
	v_bfe_u32 v25, v24, 16, 1
	v_add3_u32 v24, v24, v25, s33
	ds_write_b16_d16_hi v100, v24 offset:4384
	v_add_f32_e32 v24, v26, v61
	v_bfe_u32 v25, v24, 16, 1
	v_add3_u32 v24, v24, v25, s33
	ds_write_b16_d16_hi v100, v24 offset:4656
	v_add_f32_e32 v24, v27, v61
	v_bfe_u32 v25, v24, 16, 1
	v_add3_u32 v24, v24, v25, s33
	ds_write_b16_d16_hi v100, v24 offset:4928
	v_bfe_u32 v24, v20, 16, 1
	v_add3_u32 v20, v20, v24, s33
	ds_write_b16_d16_hi v100, v20 offset:4144
	v_add_f32_e32 v20, v21, v56
	v_bfe_u32 v21, v20, 16, 1
	v_add3_u32 v20, v20, v21, s33
	ds_write_b16_d16_hi v100, v20 offset:4416
	v_add_f32_e32 v20, v22, v56
	v_bfe_u32 v21, v20, 16, 1
	v_add3_u32 v20, v20, v21, s33
	ds_write_b16_d16_hi v100, v20 offset:4688
	v_add_f32_e32 v20, v23, v56
	v_bfe_u32 v21, v20, 16, 1
	v_add3_u32 v20, v20, v21, s33
	v_add_f32_e32 v16, v16, v52
	ds_write_b16_d16_hi v100, v20 offset:4960
	v_bfe_u32 v20, v16, 16, 1
	v_add3_u32 v16, v16, v20, s33
	ds_write_b16_d16_hi v100, v16 offset:4176
	v_add_f32_e32 v16, v17, v52
	v_bfe_u32 v17, v16, 16, 1
	v_add3_u32 v16, v16, v17, s33
	ds_write_b16_d16_hi v100, v16 offset:4448
	v_add_f32_e32 v16, v18, v52
	v_bfe_u32 v17, v16, 16, 1
	v_add3_u32 v16, v16, v17, s33
	ds_write_b16_d16_hi v100, v16 offset:4720
	v_add_f32_e32 v16, v19, v52
	v_bfe_u32 v17, v16, 16, 1
	v_add3_u32 v16, v16, v17, s33
	v_add_f32_e32 v12, v12, v73
	ds_write_b16_d16_hi v100, v16 offset:4992
	v_bfe_u32 v16, v12, 16, 1
	v_add3_u32 v12, v12, v16, s33
	ds_write_b16_d16_hi v100, v12 offset:8432
	v_add_f32_e32 v12, v13, v73
	v_bfe_u32 v13, v12, 16, 1
	v_add3_u32 v12, v12, v13, s33
	ds_write_b16_d16_hi v100, v12 offset:8704
	v_add_f32_e32 v12, v14, v73
	v_mfma_f32_16x16x32_bf16 v[8:11], v[104:107], v[116:119], v[8:11]
	v_bfe_u32 v13, v12, 16, 1
	v_add3_u32 v12, v12, v13, s33
	ds_write_b16_d16_hi v100, v12 offset:8976
	v_add_f32_e32 v12, v15, v73
	v_bfe_u32 v13, v12, 16, 1
	v_add3_u32 v12, v12, v13, s33
	s_nop 1
	v_add_f32_e32 v8, v8, v61
	ds_write_b16_d16_hi v100, v12 offset:9248
	v_bfe_u32 v12, v8, 16, 1
	v_add3_u32 v8, v8, v12, s33
	ds_write_b16_d16_hi v100, v8 offset:8464
	v_add_f32_e32 v8, v9, v61
	v_bfe_u32 v9, v8, 16, 1
	v_add3_u32 v8, v8, v9, s33
	ds_write_b16_d16_hi v100, v8 offset:8736
	v_add_f32_e32 v8, v10, v61
	v_mfma_f32_16x16x32_bf16 v[4:7], v[104:107], v[120:123], v[4:7]
	v_bfe_u32 v9, v8, 16, 1
	v_add3_u32 v8, v8, v9, s33
	ds_write_b16_d16_hi v100, v8 offset:9008
	v_add_f32_e32 v8, v11, v61
	v_bfe_u32 v9, v8, 16, 1
	v_add3_u32 v8, v8, v9, s33
	s_nop 1
	v_add_f32_e32 v4, v4, v56
	ds_write_b16_d16_hi v100, v8 offset:9280
	v_bfe_u32 v8, v4, 16, 1
	v_add3_u32 v4, v4, v8, s33
	ds_write_b16_d16_hi v100, v4 offset:8496
	v_add_f32_e32 v4, v5, v56
	v_bfe_u32 v5, v4, 16, 1
	v_add3_u32 v4, v4, v5, s33
	ds_write_b16_d16_hi v100, v4 offset:8768
	v_add_f32_e32 v4, v6, v56
	v_mfma_f32_16x16x32_bf16 v[0:3], v[104:107], v[124:127], v[0:3]
	v_bfe_u32 v5, v4, 16, 1
	v_add3_u32 v4, v4, v5, s33
	ds_write_b16_d16_hi v100, v4 offset:9040
	v_add_f32_e32 v4, v7, v56
	v_bfe_u32 v5, v4, 16, 1
	v_add3_u32 v4, v4, v5, s33
	s_nop 1
	v_add_f32_e32 v0, v0, v52
	ds_write_b16_d16_hi v100, v4 offset:9312
	v_bfe_u32 v4, v0, 16, 1
	v_add3_u32 v0, v0, v4, s33
	ds_write_b16_d16_hi v100, v0 offset:8528
	v_add_f32_e32 v0, v1, v52
	v_bfe_u32 v1, v0, 16, 1
	v_add3_u32 v0, v0, v1, s33
	ds_write_b16_d16_hi v100, v0 offset:8800
	v_add_f32_e32 v0, v2, v52
	v_bfe_u32 v1, v0, 16, 1
	v_add3_u32 v0, v0, v1, s33
	ds_write_b16_d16_hi v100, v0 offset:9072
	v_add_f32_e32 v0, v3, v52
	v_bfe_u32 v1, v0, 16, 1
	v_add3_u32 v0, v0, v1, s33
	ds_write_b16_d16_hi v100, v0 offset:9344
	s_waitcnt vmcnt(0)
	s_waitcnt lgkmcnt(0)
	s_barrier
	ds_read_b128 v[0:3], v101
	ds_read_b128 v[4:7], v101 offset:4352
	ds_read_b128 v[8:11], v101 offset:8704
	ds_read_b128 v[12:15], v101 offset:13056
	ds_read_b128 v[16:19], v102 offset:36864
	ds_read_b128 v[20:23], v102 offset:38912
	ds_read_b128 v[24:27], v102 offset:40960
	ds_read_b128 v[28:31], v102 offset:43008
	s_waitcnt lgkmcnt(3)
	v_mfma_f32_16x16x32_bf16 v[32:35], v[0:3], v[16:19], 0
	s_waitcnt lgkmcnt(2)
	v_mfma_f32_16x16x32_bf16 v[36:39], v[0:3], v[20:23], 0
	s_waitcnt lgkmcnt(1)
	v_mfma_f32_16x16x32_bf16 v[40:43], v[0:3], v[24:27], 0
	s_waitcnt lgkmcnt(0)
	v_mfma_f32_16x16x32_bf16 v[0:3], v[0:3], v[28:31], 0
	v_mfma_f32_16x16x32_bf16 v[44:47], v[4:7], v[16:19], 0
	v_mfma_f32_16x16x32_bf16 v[48:51], v[4:7], v[20:23], 0
	v_mfma_f32_16x16x32_bf16 v[52:55], v[4:7], v[24:27], 0
	v_mfma_f32_16x16x32_bf16 v[4:7], v[4:7], v[28:31], 0
	v_mfma_f32_16x16x32_bf16 v[56:59], v[8:11], v[16:19], 0
	v_mfma_f32_16x16x32_bf16 v[60:63], v[8:11], v[20:23], 0
	v_mfma_f32_16x16x32_bf16 v[74:77], v[8:11], v[24:27], 0
	v_mfma_f32_16x16x32_bf16 v[8:11], v[8:11], v[28:31], 0
	v_mfma_f32_16x16x32_bf16 v[16:19], v[12:15], v[16:19], 0
	v_mfma_f32_16x16x32_bf16 v[20:23], v[12:15], v[20:23], 0
	v_mfma_f32_16x16x32_bf16 v[24:27], v[12:15], v[24:27], 0
	v_mfma_f32_16x16x32_bf16 v[12:15], v[12:15], v[28:31], 0
	ds_read_b128 v[28:31], v101 offset:64
	ds_read_b128 v[82:85], v101 offset:4416
	ds_read_b128 v[86:89], v101 offset:8768
	ds_read_b128 v[104:107], v101 offset:13120
	ds_read_b128 v[108:111], v102 offset:37888
	ds_read_b128 v[116:119], v102 offset:39936
	ds_read_b128 v[120:123], v102 offset:41984
	ds_read_b128 v[124:127], v102 offset:44032
	s_waitcnt lgkmcnt(3)
	v_mfma_f32_16x16x32_bf16 v[32:35], v[28:31], v[108:111], v[32:35]
	s_waitcnt lgkmcnt(2)
	v_mfma_f32_16x16x32_bf16 v[36:39], v[28:31], v[116:119], v[36:39]
	s_waitcnt lgkmcnt(1)
	v_mfma_f32_16x16x32_bf16 v[40:43], v[28:31], v[120:123], v[40:43]
	s_waitcnt lgkmcnt(0)
	v_mfma_f32_16x16x32_bf16 v[0:3], v[28:31], v[124:127], v[0:3]
	v_mfma_f32_16x16x32_bf16 v[28:31], v[82:85], v[108:111], v[44:47]
	v_mfma_f32_16x16x32_bf16 v[44:47], v[82:85], v[116:119], v[48:51]
	v_mfma_f32_16x16x32_bf16 v[48:51], v[82:85], v[120:123], v[52:55]
	v_mfma_f32_16x16x32_bf16 v[4:7], v[82:85], v[124:127], v[4:7]
	v_mfma_f32_16x16x32_bf16 v[52:55], v[86:89], v[108:111], v[56:59]
	v_mfma_f32_16x16x32_bf16 v[56:59], v[86:89], v[116:119], v[60:63]
	v_mfma_f32_16x16x32_bf16 v[60:63], v[86:89], v[120:123], v[74:77]
	v_mfma_f32_16x16x32_bf16 v[8:11], v[86:89], v[124:127], v[8:11]
	v_mfma_f32_16x16x32_bf16 v[16:19], v[104:107], v[108:111], v[16:19]
	v_mfma_f32_16x16x32_bf16 v[20:23], v[104:107], v[116:119], v[20:23]
	v_mfma_f32_16x16x32_bf16 v[24:27], v[104:107], v[120:123], v[24:27]
	v_mfma_f32_16x16x32_bf16 v[12:15], v[104:107], v[124:127], v[12:15]
	ds_read_b128 v[74:77], v101 offset:128
	ds_read_b128 v[82:85], v101 offset:4480
	ds_read_b128 v[86:89], v101 offset:8832
	ds_read_b128 v[104:107], v101 offset:13184
	ds_read_b128 v[108:111], v102 offset:53248
	ds_read_b128 v[116:119], v102 offset:55296
	ds_read_b128 v[120:123], v102 offset:57344
	ds_read_b128 v[124:127], v102 offset:59392
	s_waitcnt lgkmcnt(3)
	v_mfma_f32_16x16x32_bf16 v[32:35], v[74:77], v[108:111], v[32:35]
	s_waitcnt lgkmcnt(2)
	v_mfma_f32_16x16x32_bf16 v[36:39], v[74:77], v[116:119], v[36:39]
	s_waitcnt lgkmcnt(1)
	v_mfma_f32_16x16x32_bf16 v[40:43], v[74:77], v[120:123], v[40:43]
	s_waitcnt lgkmcnt(0)
	v_mfma_f32_16x16x32_bf16 v[0:3], v[74:77], v[124:127], v[0:3]
	v_mfma_f32_16x16x32_bf16 v[28:31], v[82:85], v[108:111], v[28:31]
	v_mfma_f32_16x16x32_bf16 v[44:47], v[82:85], v[116:119], v[44:47]
	v_mfma_f32_16x16x32_bf16 v[48:51], v[82:85], v[120:123], v[48:51]
	v_mfma_f32_16x16x32_bf16 v[4:7], v[82:85], v[124:127], v[4:7]
	v_mfma_f32_16x16x32_bf16 v[52:55], v[86:89], v[108:111], v[52:55]
	v_mfma_f32_16x16x32_bf16 v[56:59], v[86:89], v[116:119], v[56:59]
	v_mfma_f32_16x16x32_bf16 v[60:63], v[86:89], v[120:123], v[60:63]
	v_mfma_f32_16x16x32_bf16 v[8:11], v[86:89], v[124:127], v[8:11]
	v_mfma_f32_16x16x32_bf16 v[74:77], v[104:107], v[108:111], v[16:19]
	v_mfma_f32_16x16x32_bf16 v[82:85], v[104:107], v[116:119], v[20:23]
	v_mfma_f32_16x16x32_bf16 v[24:27], v[104:107], v[120:123], v[24:27]
	v_mfma_f32_16x16x32_bf16 v[86:89], v[104:107], v[124:127], v[12:15]
	s_nop 2
	ds_read_b128 v[12:15], v101 offset:192
	ds_read_b128 v[16:19], v101 offset:4544
	ds_read_b128 v[104:107], v101 offset:8896
	ds_read_b128 v[108:111], v101 offset:13248
	ds_read_b128 v[116:119], v102 offset:54272
	ds_read_b128 v[120:123], v102 offset:56320
	ds_read_b128 v[124:127], v102 offset:58368
	ds_read_b128 v[128:131], v102 offset:60416
	s_waitcnt lgkmcnt(0)
	s_barrier
	v_mfma_f32_16x16x32_bf16 v[32:35], v[12:15], v[116:119], v[32:35]
	v_mfma_f32_16x16x32_bf16 v[36:39], v[12:15], v[120:123], v[36:39]
	v_mfma_f32_16x16x32_bf16 v[136:139], v[16:19], v[128:131], v[4:7]
	s_nop 5
	v_cmp_gt_i32_e64 s[0:1], 0, v32
	v_mfma_f32_16x16x32_bf16 v[4:7], v[108:111], v[124:127], v[24:27]
	s_nop 2
	v_not_b32_e32 v24, v32
	v_cndmask_b32_e64 v24, -|v32|, v24, s[0:1]
	v_not_b32_e32 v26, v33
	v_cmp_gt_i32_e64 s[0:1], 0, v33
	v_not_b32_e32 v27, v34
	v_not_b32_e32 v32, v35
	v_cndmask_b32_e64 v26, -|v33|, v26, s[0:1]
	v_cmp_gt_i32_e64 s[0:1], 0, v34
	v_not_b32_e32 v33, v36
	v_and_b32_e32 v24, 0xffffff80, v24
	v_cndmask_b32_e64 v27, -|v34|, v27, s[0:1]
	v_cmp_gt_i32_e64 s[0:1], 0, v35
	v_bitop3_b32 v24, v94, s17, v24 bitop3:0x36
	v_add_u32_e32 v25, v98, v99
	v_cndmask_b32_e64 v32, -|v35|, v32, s[0:1]
	v_cmp_gt_i32_e64 s[0:1], 0, v36
	v_and_b32_e32 v26, 0xffffff80, v26
	v_bitop3_b32 v26, v94, s17, v26 bitop3:0x36
	v_cndmask_b32_e64 v33, -|v36|, v33, s[0:1]
	v_and_b32_e32 v33, 0xffffff80, v33
	v_bitop3_b32 v33, v94, s21, v33 bitop3:0x36
	ds_write2_b32 v25, v24, v33 offset1:16
	v_not_b32_e32 v24, v37
	v_cmp_gt_i32_e64 s[0:1], 0, v37
	v_and_b32_e32 v27, 0xffffff80, v27
	v_bitop3_b32 v27, v94, s17, v27 bitop3:0x36
	v_cndmask_b32_e64 v24, -|v37|, v24, s[0:1]
	v_and_b32_e32 v24, 0xffffff80, v24
	v_bitop3_b32 v24, v94, s21, v24 bitop3:0x36
	ds_write2_b32 v25, v26, v24 offset0:129 offset1:145
	v_not_b32_e32 v24, v38
	v_cmp_gt_i32_e64 s[0:1], 0, v38
	v_add_u32_e32 v26, 0x400, v25
	v_mfma_f32_16x16x32_bf16 v[40:43], v[12:15], v[124:127], v[40:43]
	v_cndmask_b32_e64 v24, -|v38|, v24, s[0:1]
	v_and_b32_e32 v24, 0xffffff80, v24
	v_bitop3_b32 v24, v94, s21, v24 bitop3:0x36
	ds_write2_b32 v26, v27, v24 offset0:2 offset1:18
	v_not_b32_e32 v24, v39
	v_cmp_gt_i32_e64 s[0:1], 0, v39
	v_and_b32_e32 v32, 0xffffff80, v32
	v_bitop3_b32 v32, v94, s17, v32 bitop3:0x36
	v_cndmask_b32_e64 v24, -|v39|, v24, s[0:1]
	v_and_b32_e32 v24, 0xffffff80, v24
	v_bitop3_b32 v24, v94, s21, v24 bitop3:0x36
	v_mfma_f32_16x16x32_bf16 v[132:135], v[12:15], v[128:131], v[0:3]
	ds_write2_b32 v26, v32, v24 offset0:131 offset1:147
	v_not_b32_e32 v24, v40
	v_cmp_gt_i32_e64 s[0:1], 0, v40
	v_not_b32_e32 v27, v41
	v_not_b32_e32 v32, v42
	v_cndmask_b32_e64 v24, -|v40|, v24, s[0:1]
	v_cmp_gt_i32_e64 s[0:1], 0, v41
	v_not_b32_e32 v33, v43
	v_not_b32_e32 v34, v132
	v_cndmask_b32_e64 v27, -|v41|, v27, s[0:1]
	v_cmp_gt_i32_e64 s[0:1], 0, v42
	v_and_b32_e32 v24, 0xffffff80, v24
	v_bitop3_b32 v24, v94, s22, v24 bitop3:0x36
	v_cndmask_b32_e64 v32, -|v42|, v32, s[0:1]
	v_cmp_gt_i32_e64 s[0:1], 0, v43
	v_and_b32_e32 v27, 0xffffff80, v27
	v_bitop3_b32 v27, v94, s22, v27 bitop3:0x36
	v_cndmask_b32_e64 v33, -|v43|, v33, s[0:1]
	v_cmp_gt_i32_e64 s[0:1], 0, v132
	v_and_b32_e32 v32, 0xffffff80, v32
	v_bitop3_b32 v32, v94, s22, v32 bitop3:0x36
	v_cndmask_b32_e64 v34, -|v132|, v34, s[0:1]
	v_and_b32_e32 v34, 0xffffff80, v34
	v_bitop3_b32 v34, v94, s23, v34 bitop3:0x36
	ds_write2_b32 v25, v24, v34 offset0:32 offset1:48
	v_not_b32_e32 v24, v133
	v_cmp_gt_i32_e64 s[0:1], 0, v133
	v_mfma_f32_16x16x32_bf16 v[28:31], v[16:19], v[116:119], v[28:31]
	v_and_b32_e32 v33, 0xffffff80, v33
	v_cndmask_b32_e64 v24, -|v133|, v24, s[0:1]
	v_and_b32_e32 v24, 0xffffff80, v24
	v_bitop3_b32 v24, v94, s23, v24 bitop3:0x36
	ds_write2_b32 v25, v27, v24 offset0:161 offset1:177
	v_not_b32_e32 v24, v134
	v_cmp_gt_i32_e64 s[0:1], 0, v134
	v_bitop3_b32 v33, v94, s22, v33 bitop3:0x36
	v_mfma_f32_16x16x32_bf16 v[44:47], v[16:19], v[120:123], v[44:47]
	v_cndmask_b32_e64 v24, -|v134|, v24, s[0:1]
	v_and_b32_e32 v24, 0xffffff80, v24
	v_bitop3_b32 v24, v94, s23, v24 bitop3:0x36
	ds_write2_b32 v26, v32, v24 offset0:34 offset1:50
	v_not_b32_e32 v24, v135
	v_cmp_gt_i32_e64 s[0:1], 0, v135
	v_not_b32_e32 v27, v31
	v_mfma_f32_16x16x32_bf16 v[48:51], v[16:19], v[124:127], v[48:51]
	v_cndmask_b32_e64 v24, -|v135|, v24, s[0:1]
	v_and_b32_e32 v24, 0xffffff80, v24
	v_bitop3_b32 v24, v94, s23, v24 bitop3:0x36
	ds_write2_b32 v26, v33, v24 offset0:163 offset1:179
	v_not_b32_e32 v24, v28
	v_cmp_gt_i32_e64 s[0:1], 0, v28
	v_not_b32_e32 v26, v29
	v_mfma_f32_16x16x32_bf16 v[52:55], v[104:107], v[116:119], v[52:55]
	v_cndmask_b32_e64 v24, -|v28|, v24, s[0:1]
	v_cmp_gt_i32_e64 s[0:1], 0, v29
	v_not_b32_e32 v28, v44
	v_and_b32_e32 v24, 0xffffff80, v24
	v_cndmask_b32_e64 v26, -|v29|, v26, s[0:1]
	v_and_b32_e32 v26, 0xffffff80, v26
	v_bitop3_b32 v26, v94, s17, v26 bitop3:0x36
	ds_write_b32 v25, v26 offset:8772
	v_not_b32_e32 v26, v30
	v_cmp_gt_i32_e64 s[0:1], 0, v30
	v_bitop3_b32 v24, v94, s17, v24 bitop3:0x36
	v_add_u32_e32 v25, 0x2000, v25
	v_cndmask_b32_e64 v26, -|v30|, v26, s[0:1]
	v_cmp_gt_i32_e64 s[0:1], 0, v31
	v_not_b32_e32 v29, v47
	v_not_b32_e32 v30, v48
	v_cndmask_b32_e64 v27, -|v31|, v27, s[0:1]
	v_cmp_gt_i32_e64 s[0:1], 0, v44
	v_not_b32_e32 v31, v49
	v_and_b32_e32 v26, 0xffffff80, v26
	v_cndmask_b32_e64 v28, -|v44|, v28, s[0:1]
	v_and_b32_e32 v28, 0xffffff80, v28
	v_bitop3_b32 v28, v94, s21, v28 bitop3:0x36
	ds_write2_b32 v25, v24, v28 offset0:16 offset1:32
	v_not_b32_e32 v24, v45
	v_cmp_gt_i32_e64 s[0:1], 0, v45
	v_not_b32_e32 v28, v46
	v_bitop3_b32 v26, v94, s17, v26 bitop3:0x36
	v_cndmask_b32_e64 v24, -|v45|, v24, s[0:1]
	v_cmp_gt_i32_e64 s[0:1], 0, v46
	v_and_b32_e32 v24, 0xffffff80, v24
	v_bitop3_b32 v24, v94, s21, v24 bitop3:0x36
	v_cndmask_b32_e64 v28, -|v46|, v28, s[0:1]
	v_cmp_gt_i32_e64 s[0:1], 0, v47
	v_and_b32_e32 v28, 0xffffff80, v28
	v_bitop3_b32 v28, v94, s21, v28 bitop3:0x36
	v_cndmask_b32_e64 v29, -|v47|, v29, s[0:1]
	v_cmp_gt_i32_e64 s[0:1], 0, v48
	v_and_b32_e32 v29, 0xffffff80, v29
	v_bitop3_b32 v29, v94, s21, v29 bitop3:0x36
	v_cndmask_b32_e64 v30, -|v48|, v30, s[0:1]
	v_cmp_gt_i32_e64 s[0:1], 0, v49
	v_and_b32_e32 v30, 0xffffff80, v30
	v_bitop3_b32 v30, v94, s22, v30 bitop3:0x36
	v_cndmask_b32_e64 v31, -|v49|, v31, s[0:1]
	v_and_b32_e32 v31, 0xffffff80, v31
	v_bitop3_b32 v31, v94, s22, v31 bitop3:0x36
	ds_write2_b32 v103, v24, v31 offset0:16 offset1:32
	v_not_b32_e32 v24, v50
	v_cmp_gt_i32_e64 s[0:1], 0, v50
	v_and_b32_e32 v27, 0xffffff80, v27
	v_bitop3_b32 v27, v94, s17, v27 bitop3:0x36
	v_cndmask_b32_e64 v24, -|v50|, v24, s[0:1]
	v_and_b32_e32 v24, 0xffffff80, v24
	v_bitop3_b32 v24, v94, s22, v24 bitop3:0x36
	ds_write2_b32 v103, v28, v24 offset0:145 offset1:161
	v_not_b32_e32 v24, v51
	v_cmp_gt_i32_e64 s[0:1], 0, v51
	v_add_u32_e32 v28, 0x400, v103
	v_mfma_f32_16x16x32_bf16 v[56:59], v[104:107], v[120:123], v[56:59]
	v_cndmask_b32_e64 v24, -|v51|, v24, s[0:1]
	v_and_b32_e32 v24, 0xffffff80, v24
	v_bitop3_b32 v24, v94, s22, v24 bitop3:0x36
	ds_write2_b32 v28, v29, v24 offset0:18 offset1:34
	v_not_b32_e32 v24, v136
	v_cmp_gt_i32_e64 s[0:1], 0, v136
	s_nop 1
	v_not_b32_e32 v28, v56
	v_add_u32_e32 v29, 0x1c00, v103
	v_cndmask_b32_e64 v24, -|v136|, v24, s[0:1]
	v_and_b32_e32 v24, 0xffffff80, v24
	v_bitop3_b32 v24, v94, s23, v24 bitop3:0x36
	ds_write2_b32 v25, v30, v24 offset0:48 offset1:64
	v_not_b32_e32 v24, v137
	v_cmp_gt_i32_e64 s[0:1], 0, v137
	v_add_u32_e32 v25, 0x200, v103
	v_mfma_f32_16x16x32_bf16 v[20:23], v[104:107], v[124:127], v[60:63]
	v_cndmask_b32_e64 v24, -|v137|, v24, s[0:1]
	v_and_b32_e32 v24, 0xffffff80, v24
	v_bitop3_b32 v24, v94, s23, v24 bitop3:0x36
	ds_write2_b32 v103, v24, v26 offset0:48 offset1:129
	v_not_b32_e32 v24, v138
	v_cmp_gt_i32_e64 s[0:1], 0, v138
	v_not_b32_e32 v26, v54
	v_mfma_f32_16x16x32_bf16 v[16:19], v[104:107], v[128:131], v[8:11]
	v_cndmask_b32_e64 v24, -|v138|, v24, s[0:1]
	v_and_b32_e32 v24, 0xffffff80, v24
	v_bitop3_b32 v24, v94, s23, v24 bitop3:0x36
	ds_write2_b32 v25, v24, v27 offset0:49 offset1:130
	v_not_b32_e32 v24, v139
	v_cmp_gt_i32_e64 s[0:1], 0, v139
	v_not_b32_e32 v25, v53
	v_not_b32_e32 v27, v55
	v_cndmask_b32_e64 v24, -|v139|, v24, s[0:1]
	v_and_b32_e32 v24, 0xffffff80, v24
	v_bitop3_b32 v24, v94, s23, v24 bitop3:0x36
	ds_write_b32 v103, v24 offset:1224
	v_not_b32_e32 v24, v52
	v_cmp_gt_i32_e64 s[0:1], 0, v52
	v_mfma_f32_16x16x32_bf16 v[12:15], v[108:111], v[116:119], v[74:77]
	s_nop 0
	v_cndmask_b32_e64 v24, -|v52|, v24, s[0:1]
	v_cmp_gt_i32_e64 s[0:1], 0, v53
	v_and_b32_e32 v24, 0xffffff80, v24
	v_bitop3_b32 v24, v94, s17, v24 bitop3:0x36
	v_cndmask_b32_e64 v25, -|v53|, v25, s[0:1]
	v_cmp_gt_i32_e64 s[0:1], 0, v54
	v_and_b32_e32 v25, 0xffffff80, v25
	v_bitop3_b32 v25, v94, s17, v25 bitop3:0x36
	v_cndmask_b32_e64 v26, -|v54|, v26, s[0:1]
	v_cmp_gt_i32_e64 s[0:1], 0, v55
	v_and_b32_e32 v26, 0xffffff80, v26
	v_bitop3_b32 v26, v94, s17, v26 bitop3:0x36
	v_cndmask_b32_e64 v27, -|v55|, v27, s[0:1]
	v_cmp_gt_i32_e64 s[0:1], 0, v56
	v_and_b32_e32 v27, 0xffffff80, v27
	v_bitop3_b32 v27, v94, s17, v27 bitop3:0x36
	v_cndmask_b32_e64 v28, -|v56|, v28, s[0:1]
	v_and_b32_e32 v28, 0xffffff80, v28
	v_bitop3_b32 v28, v94, s21, v28 bitop3:0x36
	ds_write2_b32 v29, v24, v28 offset0:143 offset1:159
	v_not_b32_e32 v24, v57
	v_cmp_gt_i32_e64 s[0:1], 0, v57
	v_add_u32_e32 v28, 0x2000, v103
	v_mfma_f32_16x16x32_bf16 v[8:11], v[108:111], v[120:123], v[82:85]
	v_cndmask_b32_e64 v24, -|v57|, v24, s[0:1]
	v_and_b32_e32 v24, 0xffffff80, v24
	v_bitop3_b32 v24, v94, s21, v24 bitop3:0x36
	ds_write2_b32 v28, v25, v24 offset0:16 offset1:32
	v_not_b32_e32 v24, v58
	v_cmp_gt_i32_e64 s[0:1], 0, v58
	v_add_u32_e32 v25, 0x2400, v103
	v_mfma_f32_16x16x32_bf16 v[0:3], v[108:111], v[128:131], v[86:89]
	v_cndmask_b32_e64 v24, -|v58|, v24, s[0:1]
	v_and_b32_e32 v24, 0xffffff80, v24
	v_bitop3_b32 v24, v94, s21, v24 bitop3:0x36
	ds_write2_b32 v28, v26, v24 offset0:145 offset1:161
	v_not_b32_e32 v24, v59
	v_cmp_gt_i32_e64 s[0:1], 0, v59
	s_nop 1
	v_cndmask_b32_e64 v24, -|v59|, v24, s[0:1]
	v_and_b32_e32 v24, 0xffffff80, v24
	v_bitop3_b32 v24, v94, s21, v24 bitop3:0x36
	ds_write2_b32 v25, v27, v24 offset0:18 offset1:34
	v_not_b32_e32 v24, v20
	v_cmp_gt_i32_e64 s[0:1], 0, v20
	s_nop 1
	v_cndmask_b32_e64 v20, -|v20|, v24, s[0:1]
	v_not_b32_e32 v24, v21
	v_cmp_gt_i32_e64 s[0:1], 0, v21
	v_and_b32_e32 v20, 0xffffff80, v20
	v_bitop3_b32 v20, v94, s22, v20 bitop3:0x36
	v_cndmask_b32_e64 v21, -|v21|, v24, s[0:1]
	v_not_b32_e32 v24, v22
	v_cmp_gt_i32_e64 s[0:1], 0, v22
	v_and_b32_e32 v21, 0xffffff80, v21
	v_bitop3_b32 v21, v94, s22, v21 bitop3:0x36
	v_cndmask_b32_e64 v22, -|v22|, v24, s[0:1]
	v_not_b32_e32 v24, v23
	v_cmp_gt_i32_e64 s[0:1], 0, v23
	v_and_b32_e32 v22, 0xffffff80, v22
	v_bitop3_b32 v22, v94, s22, v22 bitop3:0x36
	v_cndmask_b32_e64 v23, -|v23|, v24, s[0:1]
	v_not_b32_e32 v24, v16
	v_cmp_gt_i32_e64 s[0:1], 0, v16
	v_and_b32_e32 v23, 0xffffff80, v23
	v_bitop3_b32 v23, v94, s22, v23 bitop3:0x36
	v_cndmask_b32_e64 v16, -|v16|, v24, s[0:1]
	v_and_b32_e32 v16, 0xffffff80, v16
	v_bitop3_b32 v16, v94, s23, v16 bitop3:0x36
	ds_write2_b32 v29, v20, v16 offset0:175 offset1:191
	v_not_b32_e32 v16, v17
	v_cmp_gt_i32_e64 s[0:1], 0, v17
	s_nop 1
	v_cndmask_b32_e64 v16, -|v17|, v16, s[0:1]
	v_and_b32_e32 v16, 0xffffff80, v16
	v_bitop3_b32 v16, v94, s23, v16 bitop3:0x36
	ds_write2_b32 v28, v21, v16 offset0:48 offset1:64
	v_not_b32_e32 v16, v18
	v_cmp_gt_i32_e64 s[0:1], 0, v18
	s_nop 1
	v_cndmask_b32_e64 v16, -|v18|, v16, s[0:1]
	v_and_b32_e32 v16, 0xffffff80, v16
	v_bitop3_b32 v16, v94, s23, v16 bitop3:0x36
	ds_write2_b32 v28, v22, v16 offset0:177 offset1:193
	v_not_b32_e32 v16, v19
	v_cmp_gt_i32_e64 s[0:1], 0, v19
	s_nop 1
	v_cndmask_b32_e64 v16, -|v19|, v16, s[0:1]
	v_and_b32_e32 v16, 0xffffff80, v16
	v_bitop3_b32 v16, v94, s23, v16 bitop3:0x36
	ds_write2_b32 v25, v23, v16 offset0:50 offset1:66
	v_not_b32_e32 v16, v12
	v_cmp_gt_i32_e64 s[0:1], 0, v12
	s_nop 1
	v_cndmask_b32_e64 v12, -|v12|, v16, s[0:1]
	v_not_b32_e32 v16, v13
	v_cmp_gt_i32_e64 s[0:1], 0, v13
	v_and_b32_e32 v12, 0xffffff80, v12
	v_bitop3_b32 v12, v94, s17, v12 bitop3:0x36
	v_cndmask_b32_e64 v13, -|v13|, v16, s[0:1]
	v_not_b32_e32 v16, v14
	v_cmp_gt_i32_e64 s[0:1], 0, v14
	v_and_b32_e32 v13, 0xffffff80, v13
	v_bitop3_b32 v13, v94, s17, v13 bitop3:0x36
	v_cndmask_b32_e64 v14, -|v14|, v16, s[0:1]
	v_not_b32_e32 v16, v15
	v_cmp_gt_i32_e64 s[0:1], 0, v15
	v_and_b32_e32 v14, 0xffffff80, v14
	v_bitop3_b32 v14, v94, s17, v14 bitop3:0x36
	v_cndmask_b32_e64 v15, -|v15|, v16, s[0:1]
	v_not_b32_e32 v16, v8
	v_cmp_gt_i32_e64 s[0:1], 0, v8
	v_and_b32_e32 v15, 0xffffff80, v15
	v_bitop3_b32 v15, v94, s17, v15 bitop3:0x36
	v_cndmask_b32_e64 v8, -|v8|, v16, s[0:1]
	v_and_b32_e32 v8, 0xffffff80, v8
	v_bitop3_b32 v8, v94, s21, v8 bitop3:0x36
	v_add_u32_e32 v16, 0x3c00, v103
	ds_write2_b32 v16, v12, v8 offset0:159 offset1:175
	v_not_b32_e32 v8, v9
	v_cmp_gt_i32_e64 s[0:1], 0, v9
	s_nop 1
	v_cndmask_b32_e64 v8, -|v9|, v8, s[0:1]
	v_and_b32_e32 v8, 0xffffff80, v8
	v_bitop3_b32 v8, v94, s21, v8 bitop3:0x36
	v_add_u32_e32 v9, 0x4000, v103
	ds_write2_b32 v9, v13, v8 offset0:32 offset1:48
	v_not_b32_e32 v8, v10
	v_cmp_gt_i32_e64 s[0:1], 0, v10
	s_nop 1
	v_cndmask_b32_e64 v8, -|v10|, v8, s[0:1]
	v_and_b32_e32 v8, 0xffffff80, v8
	v_bitop3_b32 v8, v94, s21, v8 bitop3:0x36
	ds_write2_b32 v9, v14, v8 offset0:161 offset1:177
	v_not_b32_e32 v8, v11
	v_cmp_gt_i32_e64 s[0:1], 0, v11
	v_add_u32_e32 v10, 0x4400, v103
	s_nop 0
	v_cndmask_b32_e64 v8, -|v11|, v8, s[0:1]
	v_and_b32_e32 v8, 0xffffff80, v8
	v_bitop3_b32 v8, v94, s21, v8 bitop3:0x36
	ds_write2_b32 v10, v15, v8 offset0:34 offset1:50
	v_not_b32_e32 v8, v4
	v_cmp_gt_i32_e64 s[0:1], 0, v4
	s_nop 1
	v_cndmask_b32_e64 v4, -|v4|, v8, s[0:1]
	v_not_b32_e32 v8, v5
	v_cmp_gt_i32_e64 s[0:1], 0, v5
	v_and_b32_e32 v4, 0xffffff80, v4
	v_bitop3_b32 v4, v94, s22, v4 bitop3:0x36
	v_cndmask_b32_e64 v5, -|v5|, v8, s[0:1]
	v_not_b32_e32 v8, v6
	v_cmp_gt_i32_e64 s[0:1], 0, v6
	v_and_b32_e32 v5, 0xffffff80, v5
	v_bitop3_b32 v5, v94, s22, v5 bitop3:0x36
	v_cndmask_b32_e64 v6, -|v6|, v8, s[0:1]
	v_not_b32_e32 v8, v7
	v_cmp_gt_i32_e64 s[0:1], 0, v7
	v_and_b32_e32 v6, 0xffffff80, v6
	v_bitop3_b32 v6, v94, s22, v6 bitop3:0x36
	v_cndmask_b32_e64 v7, -|v7|, v8, s[0:1]
	v_not_b32_e32 v8, v0
	v_cmp_gt_i32_e64 s[0:1], 0, v0
	v_and_b32_e32 v7, 0xffffff80, v7
	v_bitop3_b32 v7, v94, s22, v7 bitop3:0x36
	v_cndmask_b32_e64 v0, -|v0|, v8, s[0:1]
	v_and_b32_e32 v0, 0xffffff80, v0
	v_bitop3_b32 v0, v94, s23, v0 bitop3:0x36
	ds_write2_b32 v16, v4, v0 offset0:191 offset1:207
	v_not_b32_e32 v0, v1
	v_cmp_gt_i32_e64 s[0:1], 0, v1
	s_nop 1
	v_cndmask_b32_e64 v0, -|v1|, v0, s[0:1]
	v_and_b32_e32 v0, 0xffffff80, v0
	v_bitop3_b32 v0, v94, s23, v0 bitop3:0x36
	ds_write2_b32 v9, v5, v0 offset0:64 offset1:80
	v_not_b32_e32 v0, v2
	v_cmp_gt_i32_e64 s[0:1], 0, v2
	s_nop 1
	v_cndmask_b32_e64 v0, -|v2|, v0, s[0:1]
	v_and_b32_e32 v0, 0xffffff80, v0
	v_bitop3_b32 v0, v94, s23, v0 bitop3:0x36
	ds_write2_b32 v9, v6, v0 offset0:193 offset1:209
	v_not_b32_e32 v0, v3
	v_cmp_gt_i32_e64 s[0:1], 0, v3
	s_nop 1
	v_cndmask_b32_e64 v0, -|v3|, v0, s[0:1]
	v_and_b32_e32 v0, 0xffffff80, v0
	v_bitop3_b32 v0, v94, s23, v0 bitop3:0x36
	ds_write2_b32 v10, v7, v0 offset0:66 offset1:82
	s_waitcnt lgkmcnt(0)
	s_barrier
	s_and_saveexec_b64 s[0:1], vcc
	s_cbranch_execz .LBB0_19
	ds_read2_b32 v[0:1], v95 offset1:1
	ds_read2_b32 v[2:3], v95 offset0:2 offset1:3
	ds_read2_b32 v[4:5], v95 offset0:4 offset1:5
	ds_read2_b32 v[6:7], v95 offset0:6 offset1:7
	ds_read2_b32 v[8:9], v95 offset0:8 offset1:9
	ds_read2_b32 v[10:11], v95 offset0:10 offset1:11
	ds_read2_b32 v[12:13], v95 offset0:12 offset1:13
	ds_read2_b32 v[14:15], v95 offset0:14 offset1:15
	ds_read2_b32 v[16:17], v95 offset0:16 offset1:17
	ds_read2_b32 v[18:19], v95 offset0:18 offset1:19
	ds_read2_b32 v[20:21], v95 offset0:20 offset1:21
	ds_read2_b32 v[22:23], v95 offset0:22 offset1:23
	ds_read2_b32 v[24:25], v95 offset0:24 offset1:25
	ds_read2_b32 v[26:27], v95 offset0:26 offset1:27
	ds_read2_b32 v[28:29], v95 offset0:28 offset1:29
	ds_read2_b32 v[30:31], v95 offset0:30 offset1:31
	ds_read2_b32 v[32:33], v95 offset0:32 offset1:33
	ds_read2_b32 v[34:35], v95 offset0:34 offset1:35
	ds_read2_b32 v[36:37], v95 offset0:36 offset1:37
	ds_read2_b32 v[38:39], v95 offset0:38 offset1:39
	ds_read2_b32 v[40:41], v95 offset0:40 offset1:41
	ds_read2_b32 v[42:43], v95 offset0:42 offset1:43
	ds_read2_b32 v[44:45], v95 offset0:44 offset1:45
	ds_read2_b32 v[46:47], v95 offset0:46 offset1:47
	ds_read2_b32 v[48:49], v95 offset0:48 offset1:49
	ds_read2_b32 v[50:51], v95 offset0:50 offset1:51
	ds_read2_b32 v[52:53], v95 offset0:52 offset1:53
	ds_read2_b32 v[54:55], v95 offset0:54 offset1:55
	ds_read2_b32 v[56:57], v95 offset0:56 offset1:57
	ds_read2_b32 v[58:59], v95 offset0:58 offset1:59
	ds_read2_b32 v[60:61], v95 offset0:60 offset1:61
	ds_read2_b32 v[62:63], v95 offset0:62 offset1:63
	ds_read2_b32 v[74:75], v95 offset0:64 offset1:65
	ds_read2_b32 v[76:77], v95 offset0:66 offset1:67
	ds_read2_b32 v[78:79], v95 offset0:68 offset1:69
	ds_read2_b32 v[82:83], v95 offset0:70 offset1:71
	ds_read2_b32 v[84:85], v95 offset0:72 offset1:73
	ds_read2_b32 v[86:87], v95 offset0:74 offset1:75
	ds_read2_b32 v[88:89], v95 offset0:76 offset1:77
	ds_read2_b32 v[90:91], v95 offset0:78 offset1:79
	ds_read2_b32 v[104:105], v95 offset0:80 offset1:81
	ds_read2_b32 v[106:107], v95 offset0:82 offset1:83
	ds_read2_b32 v[108:109], v95 offset0:84 offset1:85
	ds_read2_b32 v[110:111], v95 offset0:86 offset1:87
	ds_read2_b32 v[112:113], v95 offset0:88 offset1:89
	ds_read2_b32 v[116:117], v95 offset0:90 offset1:91
	ds_read2_b32 v[118:119], v95 offset0:92 offset1:93
	ds_read2_b32 v[120:121], v95 offset0:94 offset1:95
	ds_read2_b32 v[122:123], v95 offset0:96 offset1:97
	ds_read2_b32 v[124:125], v95 offset0:98 offset1:99
	ds_read2_b32 v[126:127], v95 offset0:100 offset1:101
	ds_read2_b32 v[128:129], v95 offset0:102 offset1:103
	ds_read2_b32 v[130:131], v95 offset0:104 offset1:105
	ds_read2_b32 v[132:133], v95 offset0:106 offset1:107
	ds_read2_b32 v[134:135], v95 offset0:108 offset1:109
	ds_read2_b32 v[136:137], v95 offset0:110 offset1:111
	ds_read2_b32 v[138:139], v95 offset0:112 offset1:113
	ds_read2_b32 v[140:141], v95 offset0:114 offset1:115
	ds_read2_b32 v[142:143], v95 offset0:116 offset1:117
	ds_read2_b32 v[144:145], v95 offset0:118 offset1:119
	ds_read2_b32 v[146:147], v95 offset0:120 offset1:121
	ds_read2_b32 v[148:149], v95 offset0:122 offset1:123
	ds_read2_b32 v[150:151], v95 offset0:124 offset1:125
	ds_read2_b32 v[152:153], v95 offset0:126 offset1:127
	s_waitcnt lgkmcnt(14)
	v_max_u32_e32 v73, v0, v1
	v_min_u32_e32 v0, v0, v1
	v_max_u32_e32 v1, v2, v3
	v_min_u32_e32 v2, v2, v3
	v_max_u32_e32 v3, v4, v5
	v_min_u32_e32 v4, v4, v5
	v_max_u32_e32 v5, v6, v7
	v_min_u32_e32 v6, v6, v7
	v_max_u32_e32 v7, v8, v9
	v_min_u32_e32 v8, v8, v9
	v_max_u32_e32 v9, v10, v11
	v_min_u32_e32 v10, v10, v11
	v_max_u32_e32 v11, v12, v13
	v_min_u32_e32 v12, v12, v13
	v_max_u32_e32 v13, v14, v15
	v_min_u32_e32 v14, v14, v15
	v_max_u32_e32 v15, v16, v17
	v_min_u32_e32 v16, v16, v17
	v_max_u32_e32 v17, v18, v19
	v_min_u32_e32 v18, v18, v19
	v_max_u32_e32 v19, v20, v21
	v_min_u32_e32 v20, v20, v21
	v_max_u32_e32 v21, v22, v23
	v_min_u32_e32 v22, v22, v23
	v_max_u32_e32 v23, v24, v25
	v_min_u32_e32 v24, v24, v25
	v_max_u32_e32 v25, v26, v27
	v_min_u32_e32 v26, v26, v27
	v_max_u32_e32 v27, v28, v29
	v_min_u32_e32 v28, v28, v29
	v_max_u32_e32 v29, v30, v31
	v_min_u32_e32 v30, v30, v31
	v_max_u32_e32 v31, v32, v33
	v_min_u32_e32 v32, v32, v33
	v_max_u32_e32 v33, v34, v35
	v_min_u32_e32 v34, v34, v35
	v_max_u32_e32 v35, v36, v37
	v_min_u32_e32 v36, v36, v37
	v_max_u32_e32 v37, v38, v39
	v_min_u32_e32 v38, v38, v39
	v_max_u32_e32 v39, v40, v41
	v_min_u32_e32 v40, v40, v41
	v_max_u32_e32 v41, v42, v43
	v_min_u32_e32 v42, v42, v43
	v_max_u32_e32 v43, v44, v45
	v_min_u32_e32 v44, v44, v45
	v_max_u32_e32 v45, v46, v47
	v_min_u32_e32 v46, v46, v47
	v_max_u32_e32 v47, v48, v49
	v_min_u32_e32 v48, v48, v49
	v_max_u32_e32 v49, v50, v51
	v_min_u32_e32 v50, v50, v51
	v_max_u32_e32 v51, v52, v53
	v_min_u32_e32 v52, v52, v53
	v_max_u32_e32 v53, v54, v55
	v_min_u32_e32 v54, v54, v55
	v_max_u32_e32 v55, v56, v57
	v_min_u32_e32 v56, v56, v57
	v_max_u32_e32 v57, v58, v59
	v_min_u32_e32 v58, v58, v59
	v_max_u32_e32 v59, v60, v61
	v_min_u32_e32 v60, v60, v61
	v_max_u32_e32 v61, v62, v63
	v_min_u32_e32 v62, v62, v63
	v_max_u32_e32 v63, v74, v75
	v_min_u32_e32 v74, v74, v75
	v_max_u32_e32 v75, v76, v77
	v_min_u32_e32 v76, v76, v77
	v_max_u32_e32 v77, v78, v79
	v_min_u32_e32 v78, v78, v79
	v_max_u32_e32 v79, v82, v83
	v_min_u32_e32 v82, v82, v83
	v_max_u32_e32 v83, v84, v85
	v_min_u32_e32 v84, v84, v85
	v_max_u32_e32 v85, v86, v87
	v_min_u32_e32 v86, v86, v87
	v_max_u32_e32 v87, v88, v89
	v_min_u32_e32 v88, v88, v89
	v_max_u32_e32 v89, v90, v91
	v_min_u32_e32 v90, v90, v91
	v_max_u32_e32 v91, v104, v105
	v_min_u32_e32 v104, v104, v105
	v_max_u32_e32 v105, v106, v107
	v_min_u32_e32 v106, v106, v107
	v_max_u32_e32 v107, v108, v109
	v_min_u32_e32 v108, v108, v109
	v_max_u32_e32 v109, v110, v111
	v_min_u32_e32 v110, v110, v111
	v_max_u32_e32 v111, v112, v113
	v_min_u32_e32 v112, v112, v113
	v_max_u32_e32 v113, v116, v117
	v_min_u32_e32 v116, v116, v117
	v_max_u32_e32 v117, v118, v119
	v_min_u32_e32 v118, v118, v119
	v_max_u32_e32 v119, v120, v121
	v_min_u32_e32 v120, v120, v121
	v_max_u32_e32 v121, v122, v123
	v_min_u32_e32 v122, v122, v123
	v_max_u32_e32 v123, v124, v125
	v_min_u32_e32 v124, v124, v125
	s_waitcnt lgkmcnt(13)
	v_max_u32_e32 v125, v126, v127
	v_min_u32_e32 v126, v126, v127
	s_waitcnt lgkmcnt(12)
	v_max_u32_e32 v127, v128, v129
	v_min_u32_e32 v128, v128, v129
	s_waitcnt lgkmcnt(11)
	v_max_u32_e32 v129, v130, v131
	v_min_u32_e32 v130, v130, v131
	s_waitcnt lgkmcnt(10)
	v_max_u32_e32 v131, v132, v133
	v_min_u32_e32 v132, v132, v133
	s_waitcnt lgkmcnt(9)
	v_max_u32_e32 v133, v134, v135
	v_min_u32_e32 v134, v134, v135
	s_waitcnt lgkmcnt(8)
	v_max_u32_e32 v135, v136, v137
	v_min_u32_e32 v136, v136, v137
	s_waitcnt lgkmcnt(7)
	v_max_u32_e32 v137, v138, v139
	v_min_u32_e32 v138, v138, v139
	s_waitcnt lgkmcnt(6)
	v_max_u32_e32 v139, v140, v141
	v_min_u32_e32 v140, v140, v141
	s_waitcnt lgkmcnt(5)
	v_max_u32_e32 v141, v142, v143
	v_min_u32_e32 v142, v142, v143
	s_waitcnt lgkmcnt(4)
	v_max_u32_e32 v143, v144, v145
	v_min_u32_e32 v144, v144, v145
	s_waitcnt lgkmcnt(3)
	v_max_u32_e32 v145, v146, v147
	v_min_u32_e32 v146, v146, v147
	s_waitcnt lgkmcnt(2)
	v_max_u32_e32 v147, v148, v149
	v_min_u32_e32 v148, v148, v149
	s_waitcnt lgkmcnt(1)
	v_max_u32_e32 v149, v150, v151
	v_min_u32_e32 v150, v150, v151
	s_waitcnt lgkmcnt(0)
	v_max_u32_e32 v151, v152, v153
	v_min_u32_e32 v152, v152, v153
	v_max_u32_e32 v153, v73, v2
	v_min_u32_e32 v2, v73, v2
	v_max_u32_e32 v73, v0, v1
	v_min_u32_e32 v0, v0, v1
	v_max_u32_e32 v1, v3, v6
	v_min_u32_e32 v3, v3, v6
	v_max_u32_e32 v6, v4, v5
	v_min_u32_e32 v4, v4, v5
	v_max_u32_e32 v5, v7, v10
	v_min_u32_e32 v7, v7, v10
	v_max_u32_e32 v10, v8, v9
	v_min_u32_e32 v8, v8, v9
	v_max_u32_e32 v9, v11, v14
	v_min_u32_e32 v11, v11, v14
	v_max_u32_e32 v14, v12, v13
	v_min_u32_e32 v12, v12, v13
	v_max_u32_e32 v13, v15, v18
	v_min_u32_e32 v15, v15, v18
	v_max_u32_e32 v18, v16, v17
	v_min_u32_e32 v16, v16, v17
	v_max_u32_e32 v17, v19, v22
	v_min_u32_e32 v19, v19, v22
	v_max_u32_e32 v22, v20, v21
	v_min_u32_e32 v20, v20, v21
	v_max_u32_e32 v21, v23, v26
	v_min_u32_e32 v23, v23, v26
	v_max_u32_e32 v26, v24, v25
	v_min_u32_e32 v24, v24, v25
	v_max_u32_e32 v25, v27, v30
	v_min_u32_e32 v27, v27, v30
	v_max_u32_e32 v30, v28, v29
	v_min_u32_e32 v28, v28, v29
	v_max_u32_e32 v29, v31, v34
	v_min_u32_e32 v31, v31, v34
	v_max_u32_e32 v34, v32, v33
	v_min_u32_e32 v32, v32, v33
	v_max_u32_e32 v33, v35, v38
	v_min_u32_e32 v35, v35, v38
	v_max_u32_e32 v38, v36, v37
	v_min_u32_e32 v36, v36, v37
	v_max_u32_e32 v37, v39, v42
	v_min_u32_e32 v39, v39, v42
	v_max_u32_e32 v42, v40, v41
	v_min_u32_e32 v40, v40, v41
	v_max_u32_e32 v41, v43, v46
	v_min_u32_e32 v43, v43, v46
	v_max_u32_e32 v46, v44, v45
	v_min_u32_e32 v44, v44, v45
	v_max_u32_e32 v45, v47, v50
	v_min_u32_e32 v47, v47, v50
	v_max_u32_e32 v50, v48, v49
	v_min_u32_e32 v48, v48, v49
	v_max_u32_e32 v49, v51, v54
	v_min_u32_e32 v51, v51, v54
	v_max_u32_e32 v54, v52, v53
	v_min_u32_e32 v52, v52, v53
	v_max_u32_e32 v53, v55, v58
	v_min_u32_e32 v55, v55, v58
	v_max_u32_e32 v58, v56, v57
	v_min_u32_e32 v56, v56, v57
	v_max_u32_e32 v57, v59, v62
	v_min_u32_e32 v59, v59, v62
	v_max_u32_e32 v62, v60, v61
	v_min_u32_e32 v60, v60, v61
	v_max_u32_e32 v61, v63, v76
	v_min_u32_e32 v63, v63, v76
	v_max_u32_e32 v76, v74, v75
	v_min_u32_e32 v74, v74, v75
	v_max_u32_e32 v75, v77, v82
	v_min_u32_e32 v77, v77, v82
	v_max_u32_e32 v82, v78, v79
	v_min_u32_e32 v78, v78, v79
	v_max_u32_e32 v79, v83, v86
	v_min_u32_e32 v83, v83, v86
	v_max_u32_e32 v86, v84, v85
	v_min_u32_e32 v84, v84, v85
	v_max_u32_e32 v85, v87, v90
	v_min_u32_e32 v87, v87, v90
	v_max_u32_e32 v90, v88, v89
	v_min_u32_e32 v88, v88, v89
	v_max_u32_e32 v89, v91, v106
	v_min_u32_e32 v91, v91, v106
	v_max_u32_e32 v106, v104, v105
	v_min_u32_e32 v104, v104, v105
	v_max_u32_e32 v105, v107, v110
	v_min_u32_e32 v107, v107, v110
	v_max_u32_e32 v110, v108, v109
	v_min_u32_e32 v108, v108, v109
	v_max_u32_e32 v109, v111, v116
	v_min_u32_e32 v111, v111, v116
	v_max_u32_e32 v116, v112, v113
	v_min_u32_e32 v112, v112, v113
	v_max_u32_e32 v113, v117, v120
	v_min_u32_e32 v117, v117, v120
	v_max_u32_e32 v120, v118, v119
	v_min_u32_e32 v118, v118, v119
	v_max_u32_e32 v119, v121, v124
	v_min_u32_e32 v121, v121, v124
	v_max_u32_e32 v124, v122, v123
	v_min_u32_e32 v122, v122, v123
	v_max_u32_e32 v123, v125, v128
	v_min_u32_e32 v125, v125, v128
	v_max_u32_e32 v128, v126, v127
	v_min_u32_e32 v126, v126, v127
	v_max_u32_e32 v127, v129, v132
	v_min_u32_e32 v129, v129, v132
	v_max_u32_e32 v132, v130, v131
	v_min_u32_e32 v130, v130, v131
	v_max_u32_e32 v131, v133, v136
	v_min_u32_e32 v133, v133, v136
	v_max_u32_e32 v136, v134, v135
	v_min_u32_e32 v134, v134, v135
	v_max_u32_e32 v135, v137, v140
	v_min_u32_e32 v137, v137, v140
	v_max_u32_e32 v140, v138, v139
	v_min_u32_e32 v138, v138, v139
	v_max_u32_e32 v139, v141, v144
	v_min_u32_e32 v141, v141, v144
	v_max_u32_e32 v144, v142, v143
	v_min_u32_e32 v142, v142, v143
	v_max_u32_e32 v143, v145, v148
	v_min_u32_e32 v145, v145, v148
	v_max_u32_e32 v148, v146, v147
	v_min_u32_e32 v146, v146, v147
	v_max_u32_e32 v147, v149, v152
	v_min_u32_e32 v149, v149, v152
	v_max_u32_e32 v152, v150, v151
	v_min_u32_e32 v150, v150, v151
	v_max_u32_e32 v151, v153, v73
	v_min_u32_e32 v73, v153, v73
	v_max_u32_e32 v153, v2, v0
	v_min_u32_e32 v0, v2, v0
	v_max_u32_e32 v2, v3, v4
	v_min_u32_e32 v3, v3, v4
	v_max_u32_e32 v4, v1, v6
	v_min_u32_e32 v1, v1, v6
	v_max_u32_e32 v6, v5, v10
	v_min_u32_e32 v5, v5, v10
	v_max_u32_e32 v10, v7, v8
	v_min_u32_e32 v7, v7, v8
	v_max_u32_e32 v8, v11, v12
	v_min_u32_e32 v11, v11, v12
	v_max_u32_e32 v12, v9, v14
	v_min_u32_e32 v9, v9, v14
	v_max_u32_e32 v14, v13, v18
	v_min_u32_e32 v13, v13, v18
	v_max_u32_e32 v18, v15, v16
	v_min_u32_e32 v15, v15, v16
	v_max_u32_e32 v16, v19, v20
	v_min_u32_e32 v19, v19, v20
	v_max_u32_e32 v20, v17, v22
	v_min_u32_e32 v17, v17, v22
	v_max_u32_e32 v22, v21, v26
	v_min_u32_e32 v21, v21, v26
	v_max_u32_e32 v26, v23, v24
	v_min_u32_e32 v23, v23, v24
	v_max_u32_e32 v24, v27, v28
	v_min_u32_e32 v27, v27, v28
	v_max_u32_e32 v28, v25, v30
	v_min_u32_e32 v25, v25, v30
	v_max_u32_e32 v30, v29, v34
	v_min_u32_e32 v29, v29, v34
	v_max_u32_e32 v34, v31, v32
	v_min_u32_e32 v31, v31, v32
	v_max_u32_e32 v32, v35, v36
	v_min_u32_e32 v35, v35, v36
	v_max_u32_e32 v36, v33, v38
	v_min_u32_e32 v33, v33, v38
	v_max_u32_e32 v38, v37, v42
	v_min_u32_e32 v37, v37, v42
	v_max_u32_e32 v42, v39, v40
	v_min_u32_e32 v39, v39, v40
	v_max_u32_e32 v40, v43, v44
	v_min_u32_e32 v43, v43, v44
	v_max_u32_e32 v44, v41, v46
	v_min_u32_e32 v41, v41, v46
	v_max_u32_e32 v46, v45, v50
	v_min_u32_e32 v45, v45, v50
	v_max_u32_e32 v50, v47, v48
	v_min_u32_e32 v47, v47, v48
	v_max_u32_e32 v48, v51, v52
	v_min_u32_e32 v51, v51, v52
	v_max_u32_e32 v52, v49, v54
	v_min_u32_e32 v49, v49, v54
	v_max_u32_e32 v54, v53, v58
	v_min_u32_e32 v53, v53, v58
	v_max_u32_e32 v58, v55, v56
	v_min_u32_e32 v55, v55, v56
	v_max_u32_e32 v56, v59, v60
	v_min_u32_e32 v59, v59, v60
	v_max_u32_e32 v60, v57, v62
	v_min_u32_e32 v57, v57, v62
	v_max_u32_e32 v62, v61, v76
	v_min_u32_e32 v61, v61, v76
	v_max_u32_e32 v76, v63, v74
	v_min_u32_e32 v63, v63, v74
	v_max_u32_e32 v74, v77, v78
	v_min_u32_e32 v77, v77, v78
	v_max_u32_e32 v78, v75, v82
	v_min_u32_e32 v75, v75, v82
	v_max_u32_e32 v82, v79, v86
	v_min_u32_e32 v79, v79, v86
	v_max_u32_e32 v86, v83, v84
	v_min_u32_e32 v83, v83, v84
	v_max_u32_e32 v84, v87, v88
	v_min_u32_e32 v87, v87, v88
	v_max_u32_e32 v88, v85, v90
	v_min_u32_e32 v85, v85, v90
	v_max_u32_e32 v90, v89, v106
	v_min_u32_e32 v89, v89, v106
	v_max_u32_e32 v106, v91, v104
	v_min_u32_e32 v91, v91, v104
	v_max_u32_e32 v104, v107, v108
	v_min_u32_e32 v107, v107, v108
	v_max_u32_e32 v108, v105, v110
	v_min_u32_e32 v105, v105, v110
	v_max_u32_e32 v110, v109, v116
	v_min_u32_e32 v109, v109, v116
	v_max_u32_e32 v116, v111, v112
	v_min_u32_e32 v111, v111, v112
	v_max_u32_e32 v112, v117, v118
	v_min_u32_e32 v117, v117, v118
	v_max_u32_e32 v118, v113, v120
	v_min_u32_e32 v113, v113, v120
	v_max_u32_e32 v120, v119, v124
	v_min_u32_e32 v119, v119, v124
	v_max_u32_e32 v124, v121, v122
	v_min_u32_e32 v121, v121, v122
	v_max_u32_e32 v122, v125, v126
	v_min_u32_e32 v125, v125, v126
	v_max_u32_e32 v126, v123, v128
	v_min_u32_e32 v123, v123, v128
	v_max_u32_e32 v128, v127, v132
	v_min_u32_e32 v127, v127, v132
	v_max_u32_e32 v132, v129, v130
	v_min_u32_e32 v129, v129, v130
	v_max_u32_e32 v130, v133, v134
	v_min_u32_e32 v133, v133, v134
	v_max_u32_e32 v134, v131, v136
	v_min_u32_e32 v131, v131, v136
	v_max_u32_e32 v136, v135, v140
	v_min_u32_e32 v135, v135, v140
	v_max_u32_e32 v140, v137, v138
	v_min_u32_e32 v137, v137, v138
	v_max_u32_e32 v138, v141, v142
	v_min_u32_e32 v141, v141, v142
	v_max_u32_e32 v142, v139, v144
	v_min_u32_e32 v139, v139, v144
	v_max_u32_e32 v144, v143, v148
	v_min_u32_e32 v143, v143, v148
	v_max_u32_e32 v148, v145, v146
	v_min_u32_e32 v145, v145, v146
	v_max_u32_e32 v146, v149, v150
	v_min_u32_e32 v149, v149, v150
	v_max_u32_e32 v150, v147, v152
	v_min_u32_e32 v147, v147, v152
	v_max_u32_e32 v152, v151, v3
	v_min_u32_e32 v3, v151, v3
	v_max_u32_e32 v151, v73, v2
	v_min_u32_e32 v2, v73, v2
	v_max_u32_e32 v73, v153, v1
	v_min_u32_e32 v1, v153, v1
	v_max_u32_e32 v153, v0, v4
	v_min_u32_e32 v0, v0, v4
	v_max_u32_e32 v4, v6, v11
	v_min_u32_e32 v6, v6, v11
	v_max_u32_e32 v11, v5, v8
	v_min_u32_e32 v5, v5, v8
	v_max_u32_e32 v8, v10, v9
	v_min_u32_e32 v9, v10, v9
	v_max_u32_e32 v10, v7, v12
	v_min_u32_e32 v7, v7, v12
	v_max_u32_e32 v12, v14, v19
	v_min_u32_e32 v14, v14, v19
	v_max_u32_e32 v19, v13, v16
	v_min_u32_e32 v13, v13, v16
	v_max_u32_e32 v16, v18, v17
	v_min_u32_e32 v17, v18, v17
	v_max_u32_e32 v18, v15, v20
	v_min_u32_e32 v15, v15, v20
	v_max_u32_e32 v20, v22, v27
	v_min_u32_e32 v22, v22, v27
	v_max_u32_e32 v27, v21, v24
	v_min_u32_e32 v21, v21, v24
	v_max_u32_e32 v24, v26, v25
	v_min_u32_e32 v25, v26, v25
	v_max_u32_e32 v26, v23, v28
	v_min_u32_e32 v23, v23, v28
	v_max_u32_e32 v28, v30, v35
	v_min_u32_e32 v30, v30, v35
	v_max_u32_e32 v35, v29, v32
	v_min_u32_e32 v29, v29, v32
	v_max_u32_e32 v32, v34, v33
	v_min_u32_e32 v33, v34, v33
	v_max_u32_e32 v34, v31, v36
	v_min_u32_e32 v31, v31, v36
	v_max_u32_e32 v36, v38, v43
	v_min_u32_e32 v38, v38, v43
	v_max_u32_e32 v43, v37, v40
	v_min_u32_e32 v37, v37, v40
	v_max_u32_e32 v40, v42, v41
	v_min_u32_e32 v41, v42, v41
	v_max_u32_e32 v42, v39, v44
	v_min_u32_e32 v39, v39, v44
	v_max_u32_e32 v44, v46, v51
	v_min_u32_e32 v46, v46, v51
	v_max_u32_e32 v51, v45, v48
	v_min_u32_e32 v45, v45, v48
	v_max_u32_e32 v48, v50, v49
	v_min_u32_e32 v49, v50, v49
	v_max_u32_e32 v50, v47, v52
	v_min_u32_e32 v47, v47, v52
	v_max_u32_e32 v52, v54, v59
	v_min_u32_e32 v54, v54, v59
	v_max_u32_e32 v59, v53, v56
	v_min_u32_e32 v53, v53, v56
	v_max_u32_e32 v56, v58, v57
	v_min_u32_e32 v57, v58, v57
	v_max_u32_e32 v58, v55, v60
	v_min_u32_e32 v55, v55, v60
	v_max_u32_e32 v60, v62, v77
	v_min_u32_e32 v62, v62, v77
	v_max_u32_e32 v77, v61, v74
	v_min_u32_e32 v61, v61, v74
	v_max_u32_e32 v74, v76, v75
	v_min_u32_e32 v75, v76, v75
	v_max_u32_e32 v76, v63, v78
	v_min_u32_e32 v63, v63, v78
	v_max_u32_e32 v78, v82, v87
	v_min_u32_e32 v82, v82, v87
	v_max_u32_e32 v87, v79, v84
	v_min_u32_e32 v79, v79, v84
	v_max_u32_e32 v84, v86, v85
	v_min_u32_e32 v85, v86, v85
	v_max_u32_e32 v86, v83, v88
	v_min_u32_e32 v83, v83, v88
	v_max_u32_e32 v88, v90, v107
	v_min_u32_e32 v90, v90, v107
	v_max_u32_e32 v107, v89, v104
	v_min_u32_e32 v89, v89, v104
	v_max_u32_e32 v104, v106, v105
	v_min_u32_e32 v105, v106, v105
	v_max_u32_e32 v106, v91, v108
	v_min_u32_e32 v91, v91, v108
	v_max_u32_e32 v108, v110, v117
	v_min_u32_e32 v110, v110, v117
	v_max_u32_e32 v117, v109, v112
	v_min_u32_e32 v109, v109, v112
	v_max_u32_e32 v112, v116, v113
	v_min_u32_e32 v113, v116, v113
	v_max_u32_e32 v116, v111, v118
	v_min_u32_e32 v111, v111, v118
	v_max_u32_e32 v118, v120, v125
	v_min_u32_e32 v120, v120, v125
	v_max_u32_e32 v125, v119, v122
	v_min_u32_e32 v119, v119, v122
	v_max_u32_e32 v122, v124, v123
	v_min_u32_e32 v123, v124, v123
	v_max_u32_e32 v124, v121, v126
	v_min_u32_e32 v121, v121, v126
	v_max_u32_e32 v126, v128, v133
	v_min_u32_e32 v128, v128, v133
	v_max_u32_e32 v133, v127, v130
	v_min_u32_e32 v127, v127, v130
	v_max_u32_e32 v130, v132, v131
	v_min_u32_e32 v131, v132, v131
	v_max_u32_e32 v132, v129, v134
	v_min_u32_e32 v129, v129, v134
	v_max_u32_e32 v134, v136, v141
	v_min_u32_e32 v136, v136, v141
	v_max_u32_e32 v141, v135, v138
	v_min_u32_e32 v135, v135, v138
	v_max_u32_e32 v138, v140, v139
	v_min_u32_e32 v139, v140, v139
	v_max_u32_e32 v140, v137, v142
	v_min_u32_e32 v137, v137, v142
	v_max_u32_e32 v142, v144, v149
	v_min_u32_e32 v144, v144, v149
	v_max_u32_e32 v149, v143, v146
	v_min_u32_e32 v143, v143, v146
	v_max_u32_e32 v146, v148, v147
	v_min_u32_e32 v147, v148, v147
	v_max_u32_e32 v148, v145, v150
	v_min_u32_e32 v145, v145, v150
	v_max_u32_e32 v150, v152, v73
	v_min_u32_e32 v73, v152, v73
	v_max_u32_e32 v152, v151, v153
	v_min_u32_e32 v151, v151, v153
	v_max_u32_e32 v153, v3, v1
	v_min_u32_e32 v1, v3, v1
	v_max_u32_e32 v3, v2, v0
	v_min_u32_e32 v0, v2, v0
	v_max_u32_e32 v2, v6, v9
	v_min_u32_e32 v6, v6, v9
	v_max_u32_e32 v9, v5, v7
	v_min_u32_e32 v5, v5, v7
	v_max_u32_e32 v7, v4, v8
	v_min_u32_e32 v4, v4, v8
	v_max_u32_e32 v8, v11, v10
	v_min_u32_e32 v10, v11, v10
	v_max_u32_e32 v11, v12, v16
	v_min_u32_e32 v12, v12, v16
	v_max_u32_e32 v16, v19, v18
	v_min_u32_e32 v18, v19, v18
	v_max_u32_e32 v19, v14, v17
	v_min_u32_e32 v14, v14, v17
	v_max_u32_e32 v17, v13, v15
	v_min_u32_e32 v13, v13, v15
	v_max_u32_e32 v15, v22, v25
	v_min_u32_e32 v22, v22, v25
	v_max_u32_e32 v25, v21, v23
	v_min_u32_e32 v21, v21, v23
	v_max_u32_e32 v23, v20, v24
	v_min_u32_e32 v20, v20, v24
	v_max_u32_e32 v24, v27, v26
	v_min_u32_e32 v26, v27, v26
	v_max_u32_e32 v27, v28, v32
	v_min_u32_e32 v28, v28, v32
	v_max_u32_e32 v32, v35, v34
	v_min_u32_e32 v34, v35, v34
	v_max_u32_e32 v35, v30, v33
	v_min_u32_e32 v30, v30, v33
	v_max_u32_e32 v33, v29, v31
	v_min_u32_e32 v29, v29, v31
	v_max_u32_e32 v31, v38, v41
	v_min_u32_e32 v38, v38, v41
	v_max_u32_e32 v41, v37, v39
	v_min_u32_e32 v37, v37, v39
	v_max_u32_e32 v39, v36, v40
	v_min_u32_e32 v36, v36, v40
	v_max_u32_e32 v40, v43, v42
	v_min_u32_e32 v42, v43, v42
	v_max_u32_e32 v43, v44, v48
	v_min_u32_e32 v44, v44, v48
	v_max_u32_e32 v48, v51, v50
	v_min_u32_e32 v50, v51, v50
	v_max_u32_e32 v51, v46, v49
	v_min_u32_e32 v46, v46, v49
	v_max_u32_e32 v49, v45, v47
	v_min_u32_e32 v45, v45, v47
	v_max_u32_e32 v47, v54, v57
	v_min_u32_e32 v54, v54, v57
	v_max_u32_e32 v57, v53, v55
	v_min_u32_e32 v53, v53, v55
	v_max_u32_e32 v55, v52, v56
	v_min_u32_e32 v52, v52, v56
	v_max_u32_e32 v56, v59, v58
	v_min_u32_e32 v58, v59, v58
	v_max_u32_e32 v59, v60, v74
	v_min_u32_e32 v60, v60, v74
	v_max_u32_e32 v74, v77, v76
	v_min_u32_e32 v76, v77, v76
	v_max_u32_e32 v77, v62, v75
	v_min_u32_e32 v62, v62, v75
	v_max_u32_e32 v75, v61, v63
	v_min_u32_e32 v61, v61, v63
	v_max_u32_e32 v63, v82, v85
	v_min_u32_e32 v82, v82, v85
	v_max_u32_e32 v85, v79, v83
	v_min_u32_e32 v79, v79, v83
	v_max_u32_e32 v83, v78, v84
	v_min_u32_e32 v78, v78, v84
	v_max_u32_e32 v84, v87, v86
	v_min_u32_e32 v86, v87, v86
	v_max_u32_e32 v87, v88, v104
	v_min_u32_e32 v88, v88, v104
	v_max_u32_e32 v104, v107, v106
	v_min_u32_e32 v106, v107, v106
	v_max_u32_e32 v107, v90, v105
	v_min_u32_e32 v90, v90, v105
	v_max_u32_e32 v105, v89, v91
	v_min_u32_e32 v89, v89, v91
	v_max_u32_e32 v91, v110, v113
	v_min_u32_e32 v110, v110, v113
	v_max_u32_e32 v113, v109, v111
	v_min_u32_e32 v109, v109, v111
	v_max_u32_e32 v111, v108, v112
	v_min_u32_e32 v108, v108, v112
	v_max_u32_e32 v112, v117, v116
	v_min_u32_e32 v116, v117, v116
	v_max_u32_e32 v117, v118, v122
	v_min_u32_e32 v118, v118, v122
	v_max_u32_e32 v122, v125, v124
	v_min_u32_e32 v124, v125, v124
	v_max_u32_e32 v125, v120, v123
	v_min_u32_e32 v120, v120, v123
	v_max_u32_e32 v123, v119, v121
	v_min_u32_e32 v119, v119, v121
	v_max_u32_e32 v121, v128, v131
	v_min_u32_e32 v128, v128, v131
	v_max_u32_e32 v131, v127, v129
	v_min_u32_e32 v127, v127, v129
	v_max_u32_e32 v129, v126, v130
	v_min_u32_e32 v126, v126, v130
	v_max_u32_e32 v130, v133, v132
	v_min_u32_e32 v132, v133, v132
	v_max_u32_e32 v133, v134, v138
	v_min_u32_e32 v134, v134, v138
	v_max_u32_e32 v138, v141, v140
	v_min_u32_e32 v140, v141, v140
	v_max_u32_e32 v141, v136, v139
	v_min_u32_e32 v136, v136, v139
	v_max_u32_e32 v139, v135, v137
	v_min_u32_e32 v135, v135, v137
	v_max_u32_e32 v137, v144, v147
	v_min_u32_e32 v144, v144, v147
	v_max_u32_e32 v147, v143, v145
	v_min_u32_e32 v143, v143, v145
	v_max_u32_e32 v145, v142, v146
	v_min_u32_e32 v142, v142, v146
	v_max_u32_e32 v146, v149, v148
	v_min_u32_e32 v148, v149, v148
	v_max_u32_e32 v149, v150, v152
	v_min_u32_e32 v150, v150, v152
	v_max_u32_e32 v152, v73, v151
	v_min_u32_e32 v73, v73, v151
	v_max_u32_e32 v151, v153, v3
	v_min_u32_e32 v3, v153, v3
	v_max_u32_e32 v153, v1, v0
	v_min_u32_e32 v0, v1, v0
	v_max_u32_e32 v1, v6, v5
	v_min_u32_e32 v5, v6, v5
	v_max_u32_e32 v6, v2, v9
	v_min_u32_e32 v2, v2, v9
	v_max_u32_e32 v9, v4, v10
	v_min_u32_e32 v4, v4, v10
	v_max_u32_e32 v10, v7, v8
	v_min_u32_e32 v7, v7, v8
	v_max_u32_e32 v8, v11, v16
	v_min_u32_e32 v11, v11, v16
	v_max_u32_e32 v16, v12, v18
	v_min_u32_e32 v12, v12, v18
	v_max_u32_e32 v18, v19, v17
	v_min_u32_e32 v17, v19, v17
	v_max_u32_e32 v19, v14, v13
	v_min_u32_e32 v13, v14, v13
	v_max_u32_e32 v14, v22, v21
	v_min_u32_e32 v21, v22, v21
	v_max_u32_e32 v22, v15, v25
	v_min_u32_e32 v15, v15, v25
	v_max_u32_e32 v25, v20, v26
	v_min_u32_e32 v20, v20, v26
	v_max_u32_e32 v26, v23, v24
	v_min_u32_e32 v23, v23, v24
	v_max_u32_e32 v24, v27, v32
	v_min_u32_e32 v27, v27, v32
	v_max_u32_e32 v32, v28, v34
	v_min_u32_e32 v28, v28, v34
	v_max_u32_e32 v34, v35, v33
	v_min_u32_e32 v33, v35, v33
	v_max_u32_e32 v35, v30, v29
	v_min_u32_e32 v29, v30, v29
	v_max_u32_e32 v30, v38, v37
	v_min_u32_e32 v37, v38, v37
	v_max_u32_e32 v38, v31, v41
	v_min_u32_e32 v31, v31, v41
	v_max_u32_e32 v41, v36, v42
	v_min_u32_e32 v36, v36, v42
	v_max_u32_e32 v42, v39, v40
	v_min_u32_e32 v39, v39, v40
	v_max_u32_e32 v40, v43, v48
	v_min_u32_e32 v43, v43, v48
	v_max_u32_e32 v48, v44, v50
	v_min_u32_e32 v44, v44, v50
	v_max_u32_e32 v50, v51, v49
	v_min_u32_e32 v49, v51, v49
	v_max_u32_e32 v51, v46, v45
	v_min_u32_e32 v45, v46, v45
	v_max_u32_e32 v46, v54, v53
	v_min_u32_e32 v53, v54, v53
	v_max_u32_e32 v54, v47, v57
	v_min_u32_e32 v47, v47, v57
	v_max_u32_e32 v57, v52, v58
	v_min_u32_e32 v52, v52, v58
	v_max_u32_e32 v58, v55, v56
	v_min_u32_e32 v55, v55, v56
	v_max_u32_e32 v56, v59, v74
	v_min_u32_e32 v59, v59, v74
	v_max_u32_e32 v74, v60, v76
	v_min_u32_e32 v60, v60, v76
	v_max_u32_e32 v76, v77, v75
	v_min_u32_e32 v75, v77, v75
	v_max_u32_e32 v77, v62, v61
	v_min_u32_e32 v61, v62, v61
	v_max_u32_e32 v62, v82, v79
	v_min_u32_e32 v79, v82, v79
	v_max_u32_e32 v82, v63, v85
	v_min_u32_e32 v63, v63, v85
	v_max_u32_e32 v85, v78, v86
	v_min_u32_e32 v78, v78, v86
	v_max_u32_e32 v86, v83, v84
	v_min_u32_e32 v83, v83, v84
	v_max_u32_e32 v84, v87, v104
	v_min_u32_e32 v87, v87, v104
	v_max_u32_e32 v104, v88, v106
	v_min_u32_e32 v88, v88, v106
	v_max_u32_e32 v106, v107, v105
	v_min_u32_e32 v105, v107, v105
	v_max_u32_e32 v107, v90, v89
	v_min_u32_e32 v89, v90, v89
	v_max_u32_e32 v90, v110, v109
	v_min_u32_e32 v109, v110, v109
	v_max_u32_e32 v110, v91, v113
	v_min_u32_e32 v91, v91, v113
	v_max_u32_e32 v113, v108, v116
	v_min_u32_e32 v108, v108, v116
	v_max_u32_e32 v116, v111, v112
	v_min_u32_e32 v111, v111, v112
	v_max_u32_e32 v112, v117, v122
	v_min_u32_e32 v117, v117, v122
	v_max_u32_e32 v122, v118, v124
	v_min_u32_e32 v118, v118, v124
	v_max_u32_e32 v124, v125, v123
	v_min_u32_e32 v123, v125, v123
	v_max_u32_e32 v125, v120, v119
	v_min_u32_e32 v119, v120, v119
	v_max_u32_e32 v120, v128, v127
	v_min_u32_e32 v127, v128, v127
	v_max_u32_e32 v128, v121, v131
	v_min_u32_e32 v121, v121, v131
	v_max_u32_e32 v131, v126, v132
	v_min_u32_e32 v126, v126, v132
	v_max_u32_e32 v132, v129, v130
	v_min_u32_e32 v129, v129, v130
	v_max_u32_e32 v130, v133, v138
	v_min_u32_e32 v133, v133, v138
	v_max_u32_e32 v138, v134, v140
	v_min_u32_e32 v134, v134, v140
	v_max_u32_e32 v140, v141, v139
	v_min_u32_e32 v139, v141, v139
	v_max_u32_e32 v141, v136, v135
	v_min_u32_e32 v135, v136, v135
	v_max_u32_e32 v136, v144, v143
	v_min_u32_e32 v143, v144, v143
	v_max_u32_e32 v144, v137, v147
	v_min_u32_e32 v137, v137, v147
	v_max_u32_e32 v147, v142, v148
	v_min_u32_e32 v142, v142, v148
	v_max_u32_e32 v148, v145, v146
	v_min_u32_e32 v145, v145, v146
	v_max_u32_e32 v146, v149, v5
	v_min_u32_e32 v5, v149, v5
	v_max_u32_e32 v149, v150, v1
	v_min_u32_e32 v1, v150, v1
	v_max_u32_e32 v150, v152, v2
	v_min_u32_e32 v2, v152, v2
	v_max_u32_e32 v152, v73, v6
	v_min_u32_e32 v6, v73, v6
	v_max_u32_e32 v73, v151, v4
	v_min_u32_e32 v4, v151, v4
	v_max_u32_e32 v151, v3, v9
	v_min_u32_e32 v3, v3, v9
	v_max_u32_e32 v9, v153, v7
	v_min_u32_e32 v7, v153, v7
	v_max_u32_e32 v153, v0, v10
	v_min_u32_e32 v0, v0, v10
	v_max_u32_e32 v10, v8, v21
	v_min_u32_e32 v8, v8, v21
	v_max_u32_e32 v21, v11, v14
	v_min_u32_e32 v11, v11, v14
	v_max_u32_e32 v14, v16, v15
	v_min_u32_e32 v15, v16, v15
	v_max_u32_e32 v16, v12, v22
	v_min_u32_e32 v12, v12, v22
	v_max_u32_e32 v22, v18, v20
	v_min_u32_e32 v18, v18, v20
	v_max_u32_e32 v20, v17, v25
	v_min_u32_e32 v17, v17, v25
	v_max_u32_e32 v25, v19, v23
	v_min_u32_e32 v19, v19, v23
	v_max_u32_e32 v23, v13, v26
	v_min_u32_e32 v13, v13, v26
	v_max_u32_e32 v26, v24, v37
	v_min_u32_e32 v24, v24, v37
	v_max_u32_e32 v37, v27, v30
	v_min_u32_e32 v27, v27, v30
	v_max_u32_e32 v30, v32, v31
	v_min_u32_e32 v31, v32, v31
	v_max_u32_e32 v32, v28, v38
	v_min_u32_e32 v28, v28, v38
	v_max_u32_e32 v38, v34, v36
	v_min_u32_e32 v34, v34, v36
	v_max_u32_e32 v36, v33, v41
	v_min_u32_e32 v33, v33, v41
	v_max_u32_e32 v41, v35, v39
	v_min_u32_e32 v35, v35, v39
	v_max_u32_e32 v39, v29, v42
	v_min_u32_e32 v29, v29, v42
	v_max_u32_e32 v42, v40, v53
	v_min_u32_e32 v40, v40, v53
	v_max_u32_e32 v53, v43, v46
	v_min_u32_e32 v43, v43, v46
	v_max_u32_e32 v46, v48, v47
	v_min_u32_e32 v47, v48, v47
	v_max_u32_e32 v48, v44, v54
	v_min_u32_e32 v44, v44, v54
	v_max_u32_e32 v54, v50, v52
	v_min_u32_e32 v50, v50, v52
	v_max_u32_e32 v52, v49, v57
	v_min_u32_e32 v49, v49, v57
	v_max_u32_e32 v57, v51, v55
	v_min_u32_e32 v51, v51, v55
	v_max_u32_e32 v55, v45, v58
	v_min_u32_e32 v45, v45, v58
	v_max_u32_e32 v58, v56, v79
	v_min_u32_e32 v56, v56, v79
	v_max_u32_e32 v79, v59, v62
	v_min_u32_e32 v59, v59, v62
	v_max_u32_e32 v62, v74, v63
	v_min_u32_e32 v63, v74, v63
	v_max_u32_e32 v74, v60, v82
	v_min_u32_e32 v60, v60, v82
	v_max_u32_e32 v82, v76, v78
	v_min_u32_e32 v76, v76, v78
	v_max_u32_e32 v78, v75, v85
	v_min_u32_e32 v75, v75, v85
	v_max_u32_e32 v85, v77, v83
	v_min_u32_e32 v77, v77, v83
	v_max_u32_e32 v83, v61, v86
	v_min_u32_e32 v61, v61, v86
	v_max_u32_e32 v86, v84, v109
	v_min_u32_e32 v84, v84, v109
	v_max_u32_e32 v109, v87, v90
	v_min_u32_e32 v87, v87, v90
	v_max_u32_e32 v90, v104, v91
	v_min_u32_e32 v91, v104, v91
	v_max_u32_e32 v104, v88, v110
	v_min_u32_e32 v88, v88, v110
	v_max_u32_e32 v110, v106, v108
	v_min_u32_e32 v106, v106, v108
	v_max_u32_e32 v108, v105, v113
	v_min_u32_e32 v105, v105, v113
	v_max_u32_e32 v113, v107, v111
	v_min_u32_e32 v107, v107, v111
	v_max_u32_e32 v111, v89, v116
	v_min_u32_e32 v89, v89, v116
	v_max_u32_e32 v116, v112, v127
	v_min_u32_e32 v112, v112, v127
	v_max_u32_e32 v127, v117, v120
	v_min_u32_e32 v117, v117, v120
	v_max_u32_e32 v120, v122, v121
	v_min_u32_e32 v121, v122, v121
	v_max_u32_e32 v122, v118, v128
	v_min_u32_e32 v118, v118, v128
	v_max_u32_e32 v128, v124, v126
	v_min_u32_e32 v124, v124, v126
	v_max_u32_e32 v126, v123, v131
	v_min_u32_e32 v123, v123, v131
	v_max_u32_e32 v131, v125, v129
	v_min_u32_e32 v125, v125, v129
	v_max_u32_e32 v129, v119, v132
	v_min_u32_e32 v119, v119, v132
	v_max_u32_e32 v132, v130, v143
	v_min_u32_e32 v130, v130, v143
	v_max_u32_e32 v143, v133, v136
	v_min_u32_e32 v133, v133, v136
	v_max_u32_e32 v136, v138, v137
	v_min_u32_e32 v137, v138, v137
	v_max_u32_e32 v138, v134, v144
	v_min_u32_e32 v134, v134, v144
	v_max_u32_e32 v144, v140, v142
	v_min_u32_e32 v140, v140, v142
	v_max_u32_e32 v142, v139, v147
	v_min_u32_e32 v139, v139, v147
	v_max_u32_e32 v147, v141, v145
	v_min_u32_e32 v141, v141, v145
	v_max_u32_e32 v145, v135, v148
	v_min_u32_e32 v135, v135, v148
	v_max_u32_e32 v148, v146, v73
	v_min_u32_e32 v73, v146, v73
	v_max_u32_e32 v146, v149, v151
	v_min_u32_e32 v149, v149, v151
	v_max_u32_e32 v151, v150, v9
	v_min_u32_e32 v9, v150, v9
	v_max_u32_e32 v150, v152, v153
	v_min_u32_e32 v152, v152, v153
	v_max_u32_e32 v153, v5, v4
	v_min_u32_e32 v4, v5, v4
	v_max_u32_e32 v5, v1, v3
	v_min_u32_e32 v1, v1, v3
	v_max_u32_e32 v3, v2, v7
	v_min_u32_e32 v2, v2, v7
	v_max_u32_e32 v7, v6, v0
	v_min_u32_e32 v0, v6, v0
	v_max_u32_e32 v6, v8, v18
	v_min_u32_e32 v8, v8, v18
	v_max_u32_e32 v18, v11, v17
	v_min_u32_e32 v11, v11, v17
	v_max_u32_e32 v17, v15, v19
	v_min_u32_e32 v15, v15, v19
	v_max_u32_e32 v19, v12, v13
	v_min_u32_e32 v12, v12, v13
	v_max_u32_e32 v13, v10, v22
	v_min_u32_e32 v10, v10, v22
	v_max_u32_e32 v22, v21, v20
	v_min_u32_e32 v20, v21, v20
	v_max_u32_e32 v21, v14, v25
	v_min_u32_e32 v14, v14, v25
	v_max_u32_e32 v25, v16, v23
	v_min_u32_e32 v16, v16, v23
	v_max_u32_e32 v23, v26, v38
	v_min_u32_e32 v26, v26, v38
	v_max_u32_e32 v38, v37, v36
	v_min_u32_e32 v36, v37, v36
	v_max_u32_e32 v37, v30, v41
	v_min_u32_e32 v30, v30, v41
	v_max_u32_e32 v41, v32, v39
	v_min_u32_e32 v32, v32, v39
	v_max_u32_e32 v39, v24, v34
	v_min_u32_e32 v24, v24, v34
	v_max_u32_e32 v34, v27, v33
	v_min_u32_e32 v27, v27, v33
	v_max_u32_e32 v33, v31, v35
	v_min_u32_e32 v31, v31, v35
	v_max_u32_e32 v35, v28, v29
	v_min_u32_e32 v28, v28, v29
	v_max_u32_e32 v29, v40, v50
	v_min_u32_e32 v40, v40, v50
	v_max_u32_e32 v50, v43, v49
	v_min_u32_e32 v43, v43, v49
	v_max_u32_e32 v49, v47, v51
	v_min_u32_e32 v47, v47, v51
	v_max_u32_e32 v51, v44, v45
	v_min_u32_e32 v44, v44, v45
	v_max_u32_e32 v45, v42, v54
	v_min_u32_e32 v42, v42, v54
	v_max_u32_e32 v54, v53, v52
	v_min_u32_e32 v52, v53, v52
	v_max_u32_e32 v53, v46, v57
	v_min_u32_e32 v46, v46, v57
	v_max_u32_e32 v57, v48, v55
	v_min_u32_e32 v48, v48, v55
	v_max_u32_e32 v55, v58, v82
	v_min_u32_e32 v58, v58, v82
	v_max_u32_e32 v82, v79, v78
	v_min_u32_e32 v78, v79, v78
	v_max_u32_e32 v79, v62, v85
	v_min_u32_e32 v62, v62, v85
	v_max_u32_e32 v85, v74, v83
	v_min_u32_e32 v74, v74, v83
	v_max_u32_e32 v83, v56, v76
	v_min_u32_e32 v56, v56, v76
	v_max_u32_e32 v76, v59, v75
	v_min_u32_e32 v59, v59, v75
	v_max_u32_e32 v75, v63, v77
	v_min_u32_e32 v63, v63, v77
	v_max_u32_e32 v77, v60, v61
	v_min_u32_e32 v60, v60, v61
	v_max_u32_e32 v61, v84, v106
	v_min_u32_e32 v84, v84, v106
	v_max_u32_e32 v106, v87, v105
	v_min_u32_e32 v87, v87, v105
	v_max_u32_e32 v105, v91, v107
	v_min_u32_e32 v91, v91, v107
	v_max_u32_e32 v107, v88, v89
	v_min_u32_e32 v88, v88, v89
	v_max_u32_e32 v89, v86, v110
	v_min_u32_e32 v86, v86, v110
	v_max_u32_e32 v110, v109, v108
	v_min_u32_e32 v108, v109, v108
	v_max_u32_e32 v109, v90, v113
	v_min_u32_e32 v90, v90, v113
	v_max_u32_e32 v113, v104, v111
	v_min_u32_e32 v104, v104, v111
	v_max_u32_e32 v111, v116, v128
	v_min_u32_e32 v116, v116, v128
	v_max_u32_e32 v128, v127, v126
	v_min_u32_e32 v126, v127, v126
	v_max_u32_e32 v127, v120, v131
	v_min_u32_e32 v120, v120, v131
	v_max_u32_e32 v131, v122, v129
	v_min_u32_e32 v122, v122, v129
	v_max_u32_e32 v129, v112, v124
	v_min_u32_e32 v112, v112, v124
	v_max_u32_e32 v124, v117, v123
	v_min_u32_e32 v117, v117, v123
	v_max_u32_e32 v123, v121, v125
	v_min_u32_e32 v121, v121, v125
	v_max_u32_e32 v125, v118, v119
	v_min_u32_e32 v118, v118, v119
	v_max_u32_e32 v119, v130, v140
	v_min_u32_e32 v130, v130, v140
	v_max_u32_e32 v140, v133, v139
	v_min_u32_e32 v133, v133, v139
	v_max_u32_e32 v139, v137, v141
	v_min_u32_e32 v137, v137, v141
	v_max_u32_e32 v141, v134, v135
	v_min_u32_e32 v134, v134, v135
	v_max_u32_e32 v135, v132, v144
	v_min_u32_e32 v132, v132, v144
	v_max_u32_e32 v144, v143, v142
	v_min_u32_e32 v142, v143, v142
	v_max_u32_e32 v143, v136, v147
	v_min_u32_e32 v136, v136, v147
	v_max_u32_e32 v147, v138, v145
	v_min_u32_e32 v138, v138, v145
	v_max_u32_e32 v145, v148, v151
	v_min_u32_e32 v148, v148, v151
	v_max_u32_e32 v151, v146, v150
	v_min_u32_e32 v146, v146, v150
	v_max_u32_e32 v150, v73, v9
	v_min_u32_e32 v9, v73, v9
	v_max_u32_e32 v73, v149, v152
	v_min_u32_e32 v149, v149, v152
	v_max_u32_e32 v152, v153, v3
	v_min_u32_e32 v3, v153, v3
	v_max_u32_e32 v153, v5, v7
	v_min_u32_e32 v5, v5, v7
	v_max_u32_e32 v7, v4, v2
	v_min_u32_e32 v2, v4, v2
	v_max_u32_e32 v4, v1, v0
	v_min_u32_e32 v0, v1, v0
	v_max_u32_e32 v1, v8, v15
	v_min_u32_e32 v8, v8, v15
	v_max_u32_e32 v15, v11, v12
	v_min_u32_e32 v11, v11, v12
	v_max_u32_e32 v12, v6, v17
	v_min_u32_e32 v6, v6, v17
	v_max_u32_e32 v17, v18, v19
	v_min_u32_e32 v18, v18, v19
	v_max_u32_e32 v19, v10, v14
	v_min_u32_e32 v10, v10, v14
	v_max_u32_e32 v14, v20, v16
	v_min_u32_e32 v16, v20, v16
	v_max_u32_e32 v20, v13, v21
	v_min_u32_e32 v13, v13, v21
	v_max_u32_e32 v21, v22, v25
	v_min_u32_e32 v22, v22, v25
	v_max_u32_e32 v25, v23, v37
	v_min_u32_e32 v23, v23, v37
	v_max_u32_e32 v37, v38, v41
	v_min_u32_e32 v38, v38, v41
	v_max_u32_e32 v41, v26, v30
	v_min_u32_e32 v26, v26, v30
	v_max_u32_e32 v30, v36, v32
	v_min_u32_e32 v32, v36, v32
	v_max_u32_e32 v36, v39, v33
	v_min_u32_e32 v33, v39, v33
	v_max_u32_e32 v39, v34, v35
	v_min_u32_e32 v34, v34, v35
	v_max_u32_e32 v35, v24, v31
	v_min_u32_e32 v24, v24, v31
	v_max_u32_e32 v31, v27, v28
	v_min_u32_e32 v27, v27, v28
	v_max_u32_e32 v28, v40, v47
	v_min_u32_e32 v40, v40, v47
	v_max_u32_e32 v47, v43, v44
	v_min_u32_e32 v43, v43, v44
	v_max_u32_e32 v44, v29, v49
	v_min_u32_e32 v29, v29, v49
	v_max_u32_e32 v49, v50, v51
	v_min_u32_e32 v50, v50, v51
	v_max_u32_e32 v51, v42, v46
	v_min_u32_e32 v42, v42, v46
	v_max_u32_e32 v46, v52, v48
	v_min_u32_e32 v48, v52, v48
	v_max_u32_e32 v52, v45, v53
	v_min_u32_e32 v45, v45, v53
	v_max_u32_e32 v53, v54, v57
	v_min_u32_e32 v54, v54, v57
	v_max_u32_e32 v57, v55, v79
	v_min_u32_e32 v55, v55, v79
	v_max_u32_e32 v79, v82, v85
	v_min_u32_e32 v82, v82, v85
	v_max_u32_e32 v85, v58, v62
	v_min_u32_e32 v58, v58, v62
	v_max_u32_e32 v62, v78, v74
	v_min_u32_e32 v74, v78, v74
	v_max_u32_e32 v78, v83, v75
	v_min_u32_e32 v75, v83, v75
	v_max_u32_e32 v83, v76, v77
	v_min_u32_e32 v76, v76, v77
	v_max_u32_e32 v77, v56, v63
	v_min_u32_e32 v56, v56, v63
	v_max_u32_e32 v63, v59, v60
	v_min_u32_e32 v59, v59, v60
	v_max_u32_e32 v60, v84, v91
	v_min_u32_e32 v84, v84, v91
	v_max_u32_e32 v91, v87, v88
	v_min_u32_e32 v87, v87, v88
	v_max_u32_e32 v88, v61, v105
	v_min_u32_e32 v61, v61, v105
	v_max_u32_e32 v105, v106, v107
	v_min_u32_e32 v106, v106, v107
	v_max_u32_e32 v107, v86, v90
	v_min_u32_e32 v86, v86, v90
	v_max_u32_e32 v90, v108, v104
	v_min_u32_e32 v104, v108, v104
	v_max_u32_e32 v108, v89, v109
	v_min_u32_e32 v89, v89, v109
	v_max_u32_e32 v109, v110, v113
	v_min_u32_e32 v110, v110, v113
	v_max_u32_e32 v113, v111, v127
	v_min_u32_e32 v111, v111, v127
	v_max_u32_e32 v127, v128, v131
	v_min_u32_e32 v128, v128, v131
	v_max_u32_e32 v131, v116, v120
	v_min_u32_e32 v116, v116, v120
	v_max_u32_e32 v120, v126, v122
	v_min_u32_e32 v122, v126, v122
	v_max_u32_e32 v126, v129, v123
	v_min_u32_e32 v123, v129, v123
	v_max_u32_e32 v129, v124, v125
	v_min_u32_e32 v124, v124, v125
	v_max_u32_e32 v125, v112, v121
	v_min_u32_e32 v112, v112, v121
	v_max_u32_e32 v121, v117, v118
	v_min_u32_e32 v117, v117, v118
	v_max_u32_e32 v118, v130, v137
	v_min_u32_e32 v130, v130, v137
	v_max_u32_e32 v137, v133, v134
	v_min_u32_e32 v133, v133, v134
	v_max_u32_e32 v134, v119, v139
	v_min_u32_e32 v119, v119, v139
	v_max_u32_e32 v139, v140, v141
	v_min_u32_e32 v140, v140, v141
	v_max_u32_e32 v141, v132, v136
	v_min_u32_e32 v132, v132, v136
	v_max_u32_e32 v136, v142, v138
	v_min_u32_e32 v138, v142, v138
	v_max_u32_e32 v142, v135, v143
	v_min_u32_e32 v135, v135, v143
	v_max_u32_e32 v143, v144, v147
	v_min_u32_e32 v144, v144, v147
	v_min_u32_e32 v147, v145, v151
	v_min_u32_e32 v154, v148, v146
	v_min_u32_e32 v155, v150, v73
	v_min_u32_e32 v156, v9, v149
	v_min_u32_e32 v157, v152, v153
	v_min_u32_e32 v158, v3, v5
	v_min_u32_e32 v159, v7, v4
	v_min_u32_e32 v160, v2, v0
	v_min_u32_e32 v161, v8, v11
	v_min_u32_e32 v162, v1, v15
	v_min_u32_e32 v163, v6, v18
	v_min_u32_e32 v164, v12, v17
	v_min_u32_e32 v165, v10, v16
	v_min_u32_e32 v166, v19, v14
	v_min_u32_e32 v167, v13, v22
	v_min_u32_e32 v168, v20, v21
	v_min_u32_e32 v169, v25, v37
	v_min_u32_e32 v170, v23, v38
	v_min_u32_e32 v171, v41, v30
	v_min_u32_e32 v172, v26, v32
	v_min_u32_e32 v173, v36, v39
	v_min_u32_e32 v174, v33, v34
	v_min_u32_e32 v175, v35, v31
	v_min_u32_e32 v176, v24, v27
	v_min_u32_e32 v177, v40, v43
	v_min_u32_e32 v178, v28, v47
	v_min_u32_e32 v179, v29, v50
	v_min_u32_e32 v180, v44, v49
	v_min_u32_e32 v181, v42, v48
	v_min_u32_e32 v182, v51, v46
	v_min_u32_e32 v183, v45, v54
	v_min_u32_e32 v184, v52, v53
	v_min_u32_e32 v185, v57, v79
	v_min_u32_e32 v186, v55, v82
	v_min_u32_e32 v187, v85, v62
	v_min_u32_e32 v188, v58, v74
	v_min_u32_e32 v189, v78, v83
	v_min_u32_e32 v190, v75, v76
	v_min_u32_e32 v191, v77, v63
	v_min_u32_e32 v192, v56, v59
	v_min_u32_e32 v193, v84, v87
	v_min_u32_e32 v194, v60, v91
	v_min_u32_e32 v195, v61, v106
	v_min_u32_e32 v196, v88, v105
	v_min_u32_e32 v197, v86, v104
	v_min_u32_e32 v198, v107, v90
	v_min_u32_e32 v199, v89, v110
	v_min_u32_e32 v200, v108, v109
	v_min_u32_e32 v201, v113, v127
	v_min_u32_e32 v202, v111, v128
	v_min_u32_e32 v203, v131, v120
	v_min_u32_e32 v204, v116, v122
	v_min_u32_e32 v205, v126, v129
	v_min_u32_e32 v206, v123, v124
	v_min_u32_e32 v207, v125, v121
	v_min_u32_e32 v208, v112, v117
	v_min_u32_e32 v209, v130, v133
	v_min_u32_e32 v210, v118, v137
	v_min_u32_e32 v211, v119, v140
	v_min_u32_e32 v212, v134, v139
	v_min_u32_e32 v213, v132, v138
	v_min_u32_e32 v214, v141, v136
	v_min_u32_e32 v215, v135, v144
	v_min_u32_e32 v216, v142, v143
	v_max3_u32 v145, v145, v151, v161
	v_max3_u32 v8, v147, v8, v11
	v_max3_u32 v11, v148, v146, v162
	v_max3_u32 v1, v154, v1, v15
	v_max3_u32 v15, v150, v73, v163
	v_max3_u32 v6, v155, v6, v18
	v_max3_u32 v9, v9, v149, v164
	v_max3_u32 v12, v156, v12, v17
	v_max3_u32 v17, v152, v153, v165
	v_max3_u32 v10, v157, v10, v16
	v_max3_u32 v3, v3, v5, v166
	v_max3_u32 v5, v158, v19, v14
	v_max3_u32 v4, v7, v4, v167
	v_max3_u32 v7, v159, v13, v22
	v_max3_u32 v0, v2, v0, v168
	v_max3_u32 v2, v160, v20, v21
	v_max3_u32 v13, v25, v37, v177
	v_max3_u32 v14, v169, v40, v43
	v_max3_u32 v16, v23, v38, v178
	v_max3_u32 v18, v170, v28, v47
	v_max3_u32 v19, v41, v30, v179
	v_max3_u32 v20, v171, v29, v50
	v_max3_u32 v21, v26, v32, v180
	v_max3_u32 v22, v172, v44, v49
	v_max3_u32 v23, v36, v39, v181
	v_max3_u32 v25, v173, v42, v48
	v_max3_u32 v26, v33, v34, v182
	v_max3_u32 v28, v174, v51, v46
	v_max3_u32 v29, v35, v31, v183
	v_max3_u32 v30, v175, v45, v54
	v_max3_u32 v24, v24, v27, v184
	v_max3_u32 v27, v176, v52, v53
	v_max3_u32 v31, v57, v79, v193
	v_max3_u32 v32, v185, v84, v87
	v_max3_u32 v33, v55, v82, v194
	v_max3_u32 v34, v186, v60, v91
	v_max3_u32 v35, v85, v62, v195
	v_max3_u32 v36, v187, v61, v106
	v_max3_u32 v37, v58, v74, v196
	v_max3_u32 v38, v188, v88, v105
	v_max3_u32 v39, v78, v83, v197
	v_max3_u32 v40, v189, v86, v104
	v_max3_u32 v41, v75, v76, v198
	v_max3_u32 v42, v190, v107, v90
	v_max3_u32 v43, v77, v63, v199
	v_max3_u32 v44, v191, v89, v110
	v_max3_u32 v45, v56, v59, v200
	v_max3_u32 v46, v192, v108, v109
	v_max3_u32 v47, v113, v127, v209
	v_max3_u32 v48, v201, v130, v133
	v_max3_u32 v49, v111, v128, v210
	v_max3_u32 v50, v202, v118, v137
	v_max3_u32 v51, v131, v120, v211
	v_max3_u32 v52, v203, v119, v140
	v_max3_u32 v53, v116, v122, v212
	v_max3_u32 v54, v204, v134, v139
	v_max3_u32 v55, v126, v129, v213
	v_max3_u32 v56, v205, v132, v138
	v_max3_u32 v57, v123, v124, v214
	v_max3_u32 v58, v206, v141, v136
	v_max3_u32 v59, v125, v121, v215
	v_max3_u32 v60, v207, v135, v144
	v_max3_u32 v61, v112, v117, v216
	v_max3_u32 v62, v208, v142, v143
	v_max_u32_e32 v63, v145, v17
	v_min_u32_e32 v17, v145, v17
	v_max_u32_e32 v73, v8, v10
	v_min_u32_e32 v8, v8, v10
	v_max_u32_e32 v10, v11, v3
	v_min_u32_e32 v3, v11, v3
	v_max_u32_e32 v11, v1, v5
	v_min_u32_e32 v1, v1, v5
	v_max_u32_e32 v5, v15, v4
	v_min_u32_e32 v4, v15, v4
	v_max_u32_e32 v15, v6, v7
	v_min_u32_e32 v6, v6, v7
	v_max_u32_e32 v7, v9, v0
	v_min_u32_e32 v0, v9, v0
	v_max_u32_e32 v9, v12, v2
	v_min_u32_e32 v2, v12, v2
	v_max_u32_e32 v12, v13, v23
	v_min_u32_e32 v13, v13, v23
	v_max_u32_e32 v23, v14, v25
	v_min_u32_e32 v14, v14, v25
	v_max_u32_e32 v25, v16, v26
	v_min_u32_e32 v16, v16, v26
	v_max_u32_e32 v26, v18, v28
	v_min_u32_e32 v18, v18, v28
	v_max_u32_e32 v28, v19, v29
	v_min_u32_e32 v19, v19, v29
	v_max_u32_e32 v29, v20, v30
	v_min_u32_e32 v20, v20, v30
	v_max_u32_e32 v30, v21, v24
	v_min_u32_e32 v21, v21, v24
	v_max_u32_e32 v24, v22, v27
	v_min_u32_e32 v22, v22, v27
	v_max_u32_e32 v27, v31, v39
	v_min_u32_e32 v31, v31, v39
	v_max_u32_e32 v39, v32, v40
	v_min_u32_e32 v32, v32, v40
	v_max_u32_e32 v40, v33, v41
	v_min_u32_e32 v33, v33, v41
	v_max_u32_e32 v41, v34, v42
	v_min_u32_e32 v34, v34, v42
	v_max_u32_e32 v42, v35, v43
	v_min_u32_e32 v35, v35, v43
	v_max_u32_e32 v43, v36, v44
	v_min_u32_e32 v36, v36, v44
	v_max_u32_e32 v44, v37, v45
	v_min_u32_e32 v37, v37, v45
	v_max_u32_e32 v45, v38, v46
	v_min_u32_e32 v38, v38, v46
	v_max_u32_e32 v46, v47, v55
	v_min_u32_e32 v47, v47, v55
	v_max_u32_e32 v55, v48, v56
	v_min_u32_e32 v48, v48, v56
	v_max_u32_e32 v56, v49, v57
	v_min_u32_e32 v49, v49, v57
	v_max_u32_e32 v57, v50, v58
	v_min_u32_e32 v50, v50, v58
	v_max_u32_e32 v58, v51, v59
	v_min_u32_e32 v51, v51, v59
	v_max_u32_e32 v59, v52, v60
	v_min_u32_e32 v52, v52, v60
	v_max_u32_e32 v60, v53, v61
	v_min_u32_e32 v53, v53, v61
	v_max_u32_e32 v61, v54, v62
	v_min_u32_e32 v54, v54, v62
	v_max_u32_e32 v62, v63, v5
	v_min_u32_e32 v5, v63, v5
	v_max_u32_e32 v63, v73, v15
	v_min_u32_e32 v15, v73, v15
	v_max_u32_e32 v73, v10, v7
	v_min_u32_e32 v7, v10, v7
	v_max_u32_e32 v10, v11, v9
	v_min_u32_e32 v9, v11, v9
	v_max_u32_e32 v11, v17, v4
	v_min_u32_e32 v4, v17, v4
	v_max_u32_e32 v17, v8, v6
	v_min_u32_e32 v6, v8, v6
	v_max_u32_e32 v8, v3, v0
	v_min_u32_e32 v0, v3, v0
	v_max_u32_e32 v3, v1, v2
	v_min_u32_e32 v1, v1, v2
	v_max_u32_e32 v2, v13, v19
	v_min_u32_e32 v13, v13, v19
	v_max_u32_e32 v19, v14, v20
	v_min_u32_e32 v14, v14, v20
	v_max_u32_e32 v20, v16, v21
	v_min_u32_e32 v16, v16, v21
	v_max_u32_e32 v21, v18, v22
	v_min_u32_e32 v18, v18, v22
	v_max_u32_e32 v22, v12, v28
	v_min_u32_e32 v12, v12, v28
	v_max_u32_e32 v28, v23, v29
	v_min_u32_e32 v23, v23, v29
	v_max_u32_e32 v29, v25, v30
	v_min_u32_e32 v25, v25, v30
	v_max_u32_e32 v30, v26, v24
	v_min_u32_e32 v24, v26, v24
	v_max_u32_e32 v26, v27, v42
	v_min_u32_e32 v27, v27, v42
	v_max_u32_e32 v42, v39, v43
	v_min_u32_e32 v39, v39, v43
	v_max_u32_e32 v43, v40, v44
	v_min_u32_e32 v40, v40, v44
	v_max_u32_e32 v44, v41, v45
	v_min_u32_e32 v41, v41, v45
	v_max_u32_e32 v45, v31, v35
	v_min_u32_e32 v31, v31, v35
	v_max_u32_e32 v35, v32, v36
	v_min_u32_e32 v32, v32, v36
	v_max_u32_e32 v36, v33, v37
	v_min_u32_e32 v33, v33, v37
	v_max_u32_e32 v37, v34, v38
	v_min_u32_e32 v34, v34, v38
	v_max_u32_e32 v38, v47, v51
	v_min_u32_e32 v47, v47, v51
	v_max_u32_e32 v51, v48, v52
	v_min_u32_e32 v48, v48, v52
	v_max_u32_e32 v52, v49, v53
	v_min_u32_e32 v49, v49, v53
	v_max_u32_e32 v53, v50, v54
	v_min_u32_e32 v50, v50, v54
	v_max_u32_e32 v54, v46, v58
	v_min_u32_e32 v46, v46, v58
	v_max_u32_e32 v58, v55, v59
	v_min_u32_e32 v55, v55, v59
	v_max_u32_e32 v59, v56, v60
	v_min_u32_e32 v56, v56, v60
	v_max_u32_e32 v60, v57, v61
	v_min_u32_e32 v57, v57, v61
	v_max_u32_e32 v61, v62, v73
	v_min_u32_e32 v62, v62, v73
	v_max_u32_e32 v73, v63, v10
	v_min_u32_e32 v10, v63, v10
	v_max_u32_e32 v63, v5, v7
	v_min_u32_e32 v5, v5, v7
	v_max_u32_e32 v7, v15, v9
	v_min_u32_e32 v9, v15, v9
	v_max_u32_e32 v15, v11, v8
	v_min_u32_e32 v8, v11, v8
	v_max_u32_e32 v11, v17, v3
	v_min_u32_e32 v3, v17, v3
	v_max_u32_e32 v17, v4, v0
	v_min_u32_e32 v0, v4, v0
	v_max_u32_e32 v4, v6, v1
	v_min_u32_e32 v1, v6, v1
	v_max_u32_e32 v6, v13, v16
	v_min_u32_e32 v13, v13, v16
	v_max_u32_e32 v16, v14, v18
	v_min_u32_e32 v14, v14, v18
	v_max_u32_e32 v18, v2, v20
	v_min_u32_e32 v2, v2, v20
	v_max_u32_e32 v20, v19, v21
	v_min_u32_e32 v19, v19, v21
	v_max_u32_e32 v21, v12, v25
	v_min_u32_e32 v12, v12, v25
	v_max_u32_e32 v25, v23, v24
	v_min_u32_e32 v23, v23, v24
	v_max_u32_e32 v24, v22, v29
	v_min_u32_e32 v22, v22, v29
	v_max_u32_e32 v29, v28, v30
	v_min_u32_e32 v28, v28, v30
	v_max_u32_e32 v30, v26, v43
	v_min_u32_e32 v26, v26, v43
	v_max_u32_e32 v43, v42, v44
	v_min_u32_e32 v42, v42, v44
	v_max_u32_e32 v44, v27, v40
	v_min_u32_e32 v27, v27, v40
	v_max_u32_e32 v40, v39, v41
	v_min_u32_e32 v39, v39, v41
	v_max_u32_e32 v41, v45, v36
	v_min_u32_e32 v36, v45, v36
	v_max_u32_e32 v45, v35, v37
	v_min_u32_e32 v35, v35, v37
	v_max_u32_e32 v37, v31, v33
	v_min_u32_e32 v31, v31, v33
	v_max_u32_e32 v33, v32, v34
	v_min_u32_e32 v32, v32, v34
	v_max_u32_e32 v34, v47, v49
	v_min_u32_e32 v47, v47, v49
	v_max_u32_e32 v49, v48, v50
	v_min_u32_e32 v48, v48, v50
	v_max_u32_e32 v50, v38, v52
	v_min_u32_e32 v38, v38, v52
	v_max_u32_e32 v52, v51, v53
	v_min_u32_e32 v51, v51, v53
	v_max_u32_e32 v53, v46, v56
	v_min_u32_e32 v46, v46, v56
	v_max_u32_e32 v56, v55, v57
	v_min_u32_e32 v55, v55, v57
	v_max_u32_e32 v57, v54, v59
	v_min_u32_e32 v54, v54, v59
	v_max_u32_e32 v59, v58, v60
	v_min_u32_e32 v58, v58, v60
	v_min_u32_e32 v60, v61, v73
	v_min_u32_e32 v74, v62, v10
	v_min_u32_e32 v75, v63, v7
	v_min_u32_e32 v76, v5, v9
	v_min_u32_e32 v77, v15, v11
	v_min_u32_e32 v78, v8, v3
	v_min_u32_e32 v79, v17, v4
	v_min_u32_e32 v82, v0, v1
	v_min_u32_e32 v83, v13, v14
	v_min_u32_e32 v84, v6, v16
	v_min_u32_e32 v85, v2, v19
	v_min_u32_e32 v86, v18, v20
	v_min_u32_e32 v87, v12, v23
	v_min_u32_e32 v88, v21, v25
	v_min_u32_e32 v89, v22, v28
	v_min_u32_e32 v90, v24, v29
	v_min_u32_e32 v91, v30, v43
	v_min_u32_e32 v104, v26, v42
	v_min_u32_e32 v105, v44, v40
	v_min_u32_e32 v106, v27, v39
	v_min_u32_e32 v107, v41, v45
	v_min_u32_e32 v108, v36, v35
	v_min_u32_e32 v109, v37, v33
	v_min_u32_e32 v110, v31, v32
	v_min_u32_e32 v111, v47, v48
	v_min_u32_e32 v112, v34, v49
	v_min_u32_e32 v113, v38, v51
	v_min_u32_e32 v116, v50, v52
	v_min_u32_e32 v117, v46, v55
	v_min_u32_e32 v118, v53, v56
	v_min_u32_e32 v119, v54, v58
	v_min_u32_e32 v120, v57, v59
	v_max3_u32 v61, v61, v73, v83
	v_max3_u32 v13, v60, v13, v14
	v_max3_u32 v10, v62, v10, v84
	v_max3_u32 v6, v74, v6, v16
	v_max3_u32 v7, v63, v7, v85
	v_max3_u32 v2, v75, v2, v19
	v_max3_u32 v5, v5, v9, v86
	v_max3_u32 v9, v76, v18, v20
	v_max3_u32 v11, v15, v11, v87
	v_max3_u32 v12, v77, v12, v23
	v_max3_u32 v3, v8, v3, v88
	v_max3_u32 v8, v78, v21, v25
	v_max3_u32 v4, v17, v4, v89
	v_max3_u32 v14, v79, v22, v28
	v_max3_u32 v0, v0, v1, v90
	v_max3_u32 v1, v82, v24, v29
	v_max3_u32 v15, v30, v43, v111
	v_max3_u32 v16, v91, v47, v48
	v_max3_u32 v17, v26, v42, v112
	v_max3_u32 v18, v104, v34, v49
	v_max3_u32 v19, v44, v40, v113
	v_max3_u32 v20, v105, v38, v51
	v_max3_u32 v21, v27, v39, v116
	v_max3_u32 v22, v106, v50, v52
	v_max3_u32 v23, v41, v45, v117
	v_max3_u32 v24, v107, v46, v55
	v_max3_u32 v25, v36, v35, v118
	v_max3_u32 v26, v108, v53, v56
	v_max3_u32 v27, v37, v33, v119
	v_max3_u32 v28, v109, v54, v58
	v_max3_u32 v29, v31, v32, v120
	v_max3_u32 v30, v110, v57, v59
	v_max_u32_e32 v31, v61, v11
	v_min_u32_e32 v11, v61, v11
	v_max_u32_e32 v32, v13, v12
	v_min_u32_e32 v12, v13, v12
	v_max_u32_e32 v13, v10, v3
	v_min_u32_e32 v3, v10, v3
	v_max_u32_e32 v10, v6, v8
	v_min_u32_e32 v6, v6, v8
	v_max_u32_e32 v8, v7, v4
	v_min_u32_e32 v4, v7, v4
	v_max_u32_e32 v7, v2, v14
	v_min_u32_e32 v2, v2, v14
	v_max_u32_e32 v14, v5, v0
	v_min_u32_e32 v0, v5, v0
	v_max_u32_e32 v5, v9, v1
	v_min_u32_e32 v1, v9, v1
	v_max_u32_e32 v9, v15, v23
	v_min_u32_e32 v15, v15, v23
	v_max_u32_e32 v23, v16, v24
	v_min_u32_e32 v16, v16, v24
	v_max_u32_e32 v24, v17, v25
	v_min_u32_e32 v17, v17, v25
	v_max_u32_e32 v25, v18, v26
	v_min_u32_e32 v18, v18, v26
	v_max_u32_e32 v26, v19, v27
	v_min_u32_e32 v19, v19, v27
	v_max_u32_e32 v27, v20, v28
	v_min_u32_e32 v20, v20, v28
	v_max_u32_e32 v28, v21, v29
	v_min_u32_e32 v21, v21, v29
	v_max_u32_e32 v29, v22, v30
	v_min_u32_e32 v22, v22, v30
	v_max_u32_e32 v30, v31, v8
	v_min_u32_e32 v8, v31, v8
	v_max_u32_e32 v31, v32, v7
	v_min_u32_e32 v7, v32, v7
	v_max_u32_e32 v32, v13, v14
	v_min_u32_e32 v13, v13, v14
	v_max_u32_e32 v14, v10, v5
	v_min_u32_e32 v5, v10, v5
	v_max_u32_e32 v10, v11, v4
	v_min_u32_e32 v4, v11, v4
	v_max_u32_e32 v11, v12, v2
	v_min_u32_e32 v2, v12, v2
	v_max_u32_e32 v12, v3, v0
	v_min_u32_e32 v0, v3, v0
	v_max_u32_e32 v3, v6, v1
	v_min_u32_e32 v1, v6, v1
	v_max_u32_e32 v6, v15, v19
	v_min_u32_e32 v15, v15, v19
	v_max_u32_e32 v19, v16, v20
	v_min_u32_e32 v16, v16, v20
	v_max_u32_e32 v20, v17, v21
	v_min_u32_e32 v17, v17, v21
	v_max_u32_e32 v21, v18, v22
	v_min_u32_e32 v18, v18, v22
	v_max_u32_e32 v22, v9, v26
	v_min_u32_e32 v9, v9, v26
	v_max_u32_e32 v26, v23, v27
	v_min_u32_e32 v23, v23, v27
	v_max_u32_e32 v27, v24, v28
	v_min_u32_e32 v24, v24, v28
	v_max_u32_e32 v28, v25, v29
	v_min_u32_e32 v25, v25, v29
	v_max_u32_e32 v29, v30, v32
	v_min_u32_e32 v30, v30, v32
	v_max_u32_e32 v32, v31, v14
	v_min_u32_e32 v14, v31, v14
	v_max_u32_e32 v31, v8, v13
	v_min_u32_e32 v8, v8, v13
	v_max_u32_e32 v13, v7, v5
	v_min_u32_e32 v5, v7, v5
	v_max_u32_e32 v7, v10, v12
	v_min_u32_e32 v10, v10, v12
	v_max_u32_e32 v12, v11, v3
	v_min_u32_e32 v3, v11, v3
	v_max_u32_e32 v11, v4, v0
	v_min_u32_e32 v0, v4, v0
	v_max_u32_e32 v4, v2, v1
	v_min_u32_e32 v1, v2, v1
	v_max_u32_e32 v2, v15, v17
	v_min_u32_e32 v15, v15, v17
	v_max_u32_e32 v17, v16, v18
	v_min_u32_e32 v16, v16, v18
	v_max_u32_e32 v18, v6, v20
	v_min_u32_e32 v6, v6, v20
	v_max_u32_e32 v20, v19, v21
	v_min_u32_e32 v19, v19, v21
	v_max_u32_e32 v21, v9, v24
	v_min_u32_e32 v9, v9, v24
	v_max_u32_e32 v24, v23, v25
	v_min_u32_e32 v23, v23, v25
	v_max_u32_e32 v25, v22, v27
	v_min_u32_e32 v22, v22, v27
	v_max_u32_e32 v27, v26, v28
	v_min_u32_e32 v26, v26, v28
	v_min_u32_e32 v28, v29, v32
	v_min_u32_e32 v33, v30, v14
	v_min_u32_e32 v34, v31, v13
	v_min_u32_e32 v35, v8, v5
	v_min_u32_e32 v36, v7, v12
	v_min_u32_e32 v37, v10, v3
	v_min_u32_e32 v38, v11, v4
	v_min_u32_e32 v39, v0, v1
	v_min_u32_e32 v40, v15, v16
	v_min_u32_e32 v41, v2, v17
	v_min_u32_e32 v42, v6, v19
	v_min_u32_e32 v43, v18, v20
	v_min_u32_e32 v44, v9, v23
	v_min_u32_e32 v45, v21, v24
	v_min_u32_e32 v46, v22, v26
	v_min_u32_e32 v47, v25, v27
	v_max3_u32 v29, v29, v32, v40
	v_max3_u32 v15, v28, v15, v16
	v_max3_u32 v14, v30, v14, v41
	v_max3_u32 v2, v33, v2, v17
	v_max3_u32 v13, v31, v13, v42
	v_max3_u32 v6, v34, v6, v19
	v_max3_u32 v5, v8, v5, v43
	v_max3_u32 v8, v35, v18, v20
	v_max3_u32 v7, v7, v12, v44
	v_max3_u32 v9, v36, v9, v23
	v_max3_u32 v3, v10, v3, v45
	v_max3_u32 v10, v37, v21, v24
	v_max3_u32 v4, v11, v4, v46
	v_max3_u32 v11, v38, v22, v26
	v_max3_u32 v0, v0, v1, v47
	v_max3_u32 v1, v39, v25, v27
	v_readlane_b32 s22, v249, 30
	v_max_u32_e32 v12, v29, v7
	v_min_u32_e32 v7, v29, v7
	v_max_u32_e32 v16, v15, v9
	v_min_u32_e32 v9, v15, v9
	v_max_u32_e32 v15, v14, v3
	v_min_u32_e32 v3, v14, v3
	v_max_u32_e32 v14, v2, v10
	v_min_u32_e32 v2, v2, v10
	v_max_u32_e32 v10, v13, v4
	v_min_u32_e32 v4, v13, v4
	v_max_u32_e32 v13, v6, v11
	v_min_u32_e32 v6, v6, v11
	v_max_u32_e32 v11, v5, v0
	v_min_u32_e32 v0, v5, v0
	v_max_u32_e32 v5, v8, v1
	v_min_u32_e32 v1, v8, v1
	v_readlane_b32 s23, v249, 31
	v_max_u32_e32 v8, v12, v10
	v_min_u32_e32 v10, v12, v10
	v_max_u32_e32 v12, v16, v13
	v_min_u32_e32 v13, v16, v13
	v_max_u32_e32 v16, v15, v11
	v_min_u32_e32 v11, v15, v11
	v_max_u32_e32 v15, v14, v5
	v_min_u32_e32 v5, v14, v5
	v_max_u32_e32 v14, v7, v4
	v_min_u32_e32 v4, v7, v4
	v_max_u32_e32 v7, v9, v6
	v_min_u32_e32 v6, v9, v6
	v_max_u32_e32 v9, v3, v0
	v_min_u32_e32 v0, v3, v0
	v_max_u32_e32 v3, v2, v1
	v_min_u32_e32 v1, v2, v1
	s_load_dwordx2 s[22:23], s[22:23], 0x180
	v_max_u32_e32 v2, v8, v16
	v_min_u32_e32 v8, v8, v16
	v_max_u32_e32 v16, v12, v15
	v_min_u32_e32 v12, v12, v15
	v_max_u32_e32 v15, v10, v11
	v_min_u32_e32 v10, v10, v11
	v_max_u32_e32 v11, v13, v5
	v_min_u32_e32 v5, v13, v5
	v_max_u32_e32 v13, v14, v9
	v_min_u32_e32 v9, v14, v9
	v_max_u32_e32 v14, v7, v3
	v_min_u32_e32 v3, v7, v3
	v_max_u32_e32 v7, v4, v0
	v_min_u32_e32 v0, v4, v0
	v_max_u32_e32 v4, v6, v1
	v_min_u32_e32 v1, v6, v1
	v_max_u32_e32 v19, v0, v1
	v_min_u32_e32 v20, v0, v1
	v_lshl_add_u32 v0, s16, 7, v81
	v_ashrrev_i32_e32 v1, 31, v0
	v_readlane_b32 s16, v249, 19
	v_lshlrev_b64 v[0:1], 10, v[0:1]
	v_readlane_b32 s17, v249, 20
	v_max_u32_e32 v6, v2, v16
	v_min_u32_e32 v2, v2, v16
	v_max_u32_e32 v16, v8, v12
	v_min_u32_e32 v8, v8, v12
	s_waitcnt lgkmcnt(0)
	v_lshl_add_u64 v[0:1], s[22:23], 0, v[0:1]
	s_mov_b32 s21, s17
	s_lshl_b32 s20, s20, 6
	v_max_u32_e32 v12, v15, v11
	v_min_u32_e32 v11, v15, v11
	v_max_u32_e32 v15, v10, v5
	v_min_u32_e32 v10, v10, v5
	v_max_u32_e32 v17, v13, v14
	v_min_u32_e32 v13, v13, v14
	v_max_u32_e32 v14, v9, v3
	v_min_u32_e32 v9, v9, v3
	v_max_u32_e32 v18, v7, v4
	v_min_u32_e32 v7, v7, v4
	v_lshl_add_u64 v[4:5], v[0:1], 0, s[20:21]
	v_xor_b32_e32 v0, 0x7f, v6
	v_xor_b32_e32 v1, 0x7f, v2
	v_xor_b32_e32 v2, 0x7f, v16
	v_xor_b32_e32 v3, 0x7f, v8
	global_store_dwordx4 v[4:5], v[0:3], off
	v_writelane_b32 v249, s16, 19
	s_nop 0
	v_xor_b32_e32 v0, 0x7f, v12
	v_xor_b32_e32 v1, 0x7f, v11
	v_xor_b32_e32 v2, 0x7f, v15
	v_xor_b32_e32 v3, 0x7f, v10
	global_store_dwordx4 v[4:5], v[0:3], off offset:16
	v_writelane_b32 v249, s17, 20
	s_nop 0
	v_xor_b32_e32 v0, 0x7f, v17
	v_xor_b32_e32 v1, 0x7f, v13
	v_xor_b32_e32 v2, 0x7f, v14
	v_xor_b32_e32 v3, 0x7f, v9
	global_store_dwordx4 v[4:5], v[0:3], off offset:32
	s_nop 1
	v_xor_b32_e32 v0, 0x7f, v18
	v_xor_b32_e32 v1, 0x7f, v7
	v_xor_b32_e32 v2, 0x7f, v19
	v_xor_b32_e32 v3, 0x7f, v20
	global_store_dwordx4 v[4:5], v[0:3], off offset:48
	s_branch .LBB0_19

.LBB0_351:
	s_cmp_ge_i32 s21, s19
	s_mov_b64 s[2:3], -1
	s_cbranch_scc0 .LBB0_355
	v_readlane_b32 s40, v249, 19
	s_lshl_b32 s10, s27, 11
	v_readlane_b32 s41, v249, 20
	s_lshr_b32 s40, s26, 4
	s_and_b32 s38, s10, 0xc0000
	s_lshl_b32 s10, s26, 16
	s_lshl_b64 s[2:3], s[40:41], 20
	s_and_b32 s40, s10, 0xc0000
	v_readlane_b32 s10, v249, 30
	v_readlane_b32 s11, v249, 31
	s_load_dwordx2 s[16:17], s[10:11], 0x118
	s_load_dwordx2 s[14:15], s[10:11], 0x138
	v_mov_b32_e32 v26, v220
	s_sub_i32 s10, s21, s19
	s_bfe_u32 s30, s10, 0x20002
	v_lshlrev_b32_e32 v92, 4, v26
	v_and_b32_e32 v0, 32, v26
	v_bitop3_b32 v0, v92, v0, 48 bitop3:0x6c
	s_lshr_b32 s12, s10, 4
	s_lshl_b32 s10, s30, 18
	v_lshrrev_b32_e32 v16, 2, v26
	v_lshrrev_b32_e32 v1, 1, v26
	v_lshrrev_b32_e32 v0, 1, v0
	v_ashrrev_i32_e32 v4, 3, v26
	s_waitcnt lgkmcnt(0)
	s_add_u32 s34, s14, s10
	v_and_or_b32 v0, v1, 32, v0
	v_bfi_b32 v4, 15, v16, v4
	s_addc_u32 s35, s15, 0
	s_mov_b32 s13, s41
	s_lshl_b32 s31, s21, 7
	v_lshlrev_b32_e32 v0, 1, v0
	v_mov_b32_e32 v1, v80
	v_ashrrev_i32_e32 v5, 31, v4
	v_add_u32_e32 v12, 0x1000, v92
	s_lshl_b64 s[10:11], s[12:13], 9
	s_and_b32 s13, s31, 0x180
	v_lshl_add_u64 v[2:3], s[34:35], 0, v[0:1]
	v_lshlrev_b64 v[4:5], 11, v[4:5]
	v_readfirstlane_b32 s34, v92
	v_ashrrev_i32_e32 v8, 7, v12
	v_add_u32_e32 v17, 0x2000, v92
	s_or_b32 s36, s10, s13
	s_mov_b32 s37, s11
	v_lshl_add_u64 v[6:7], v[2:3], 0, v[4:5]
	s_mov_b32 m0, s34
	v_bfi_b32 v8, -16, v8, v16
	v_readfirstlane_b32 s34, v12
	v_ashrrev_i32_e32 v12, 7, v17
	v_add_u32_e32 v18, 0x3000, v92
	s_lshl_b64 s[36:37], s[36:37], 11
	global_load_lds_dwordx4 v[6:7], off
	v_ashrrev_i32_e32 v9, 31, v8
	s_mov_b32 m0, s34
	v_bfi_b32 v12, -16, v12, v16
	v_readfirstlane_b32 s34, v17
	v_ashrrev_i32_e32 v17, 7, v18
	s_add_u32 s36, s16, s36
	v_lshlrev_b64 v[8:9], 11, v[8:9]
	v_ashrrev_i32_e32 v13, 31, v12
	v_bfi_b32 v16, -16, v17, v16
	s_addc_u32 s37, s17, s37
	v_lshl_add_u64 v[10:11], v[2:3], 0, v[8:9]
	v_lshlrev_b64 v[12:13], 11, v[12:13]
	v_ashrrev_i32_e32 v17, 31, v16
	global_load_lds_dwordx4 v[10:11], off
	v_lshl_add_u64 v[14:15], v[2:3], 0, v[12:13]
	s_mov_b32 m0, s34
	v_lshlrev_b64 v[16:17], 11, v[16:17]
	v_readfirstlane_b32 s34, v18
	v_lshl_add_u64 v[18:19], s[36:37], 0, v[0:1]
	v_add_u32_e32 v1, 0x4000, v92
	global_load_lds_dwordx4 v[14:15], off
	v_lshl_add_u64 v[2:3], v[2:3], 0, v[16:17]
	s_mov_b32 m0, s34
	v_readfirstlane_b32 s34, v1
	v_add_u32_e32 v1, 0x5000, v92
	global_load_lds_dwordx4 v[2:3], off
	v_lshl_add_u64 v[20:21], v[18:19], 0, v[4:5]
	s_mov_b32 m0, s34
	v_readfirstlane_b32 s34, v1
	v_add_u32_e32 v1, 0x6000, v92
	global_load_lds_dwordx4 v[20:21], off
	v_lshl_add_u64 v[22:23], v[18:19], 0, v[8:9]
	s_mov_b32 m0, s34
	v_readfirstlane_b32 s34, v1
	v_add_u32_e32 v1, 0x7000, v92
	global_load_lds_dwordx4 v[22:23], off
	v_lshl_add_u64 v[24:25], v[18:19], 0, v[12:13]
	s_mov_b32 m0, s34
	v_readfirstlane_b32 s34, v1
	v_add_u32_e32 v1, 0x8000, v92
	global_load_lds_dwordx4 v[24:25], off
	v_lshl_add_u64 v[18:19], v[18:19], 0, v[16:17]
	s_mov_b32 m0, s34
	s_mov_b64 s[36:37], 0x80
	v_readfirstlane_b32 s34, v1
	v_add_u32_e32 v1, 0x9000, v92
	global_load_lds_dwordx4 v[18:19], off
	v_lshl_add_u64 v[6:7], v[6:7], 0, s[36:37]
	s_mov_b32 m0, s34
	v_readfirstlane_b32 s34, v1
	v_add_u32_e32 v1, 0xa000, v92
	global_load_lds_dwordx4 v[6:7], off
	v_lshl_add_u64 v[6:7], v[10:11], 0, s[36:37]
	s_mov_b32 m0, s34
	v_readfirstlane_b32 s34, v1
	v_add_u32_e32 v1, 0xb000, v92
	global_load_lds_dwordx4 v[6:7], off
	v_lshl_add_u64 v[6:7], v[14:15], 0, s[36:37]
	s_mov_b32 m0, s34
	v_readfirstlane_b32 s34, v1
	v_add_u32_e32 v1, 0xc000, v92
	global_load_lds_dwordx4 v[6:7], off
	v_lshl_add_u64 v[2:3], v[2:3], 0, s[36:37]
	s_mov_b32 m0, s34
	v_readfirstlane_b32 s34, v1
	v_add_u32_e32 v1, 0xd000, v92
	global_load_lds_dwordx4 v[2:3], off
	v_lshl_add_u64 v[2:3], v[20:21], 0, s[36:37]
	s_mov_b32 m0, s34
	v_readfirstlane_b32 s34, v1
	v_add_u32_e32 v1, 0xe000, v92
	global_load_lds_dwordx4 v[2:3], off
	v_lshl_add_u64 v[2:3], v[22:23], 0, s[36:37]
	s_mov_b32 m0, s34
	v_readfirstlane_b32 s34, v1
	v_add_u32_e32 v1, 0xf000, v92
	global_load_lds_dwordx4 v[2:3], off
	v_lshl_add_u64 v[2:3], v[24:25], 0, s[36:37]
	s_mov_b32 m0, s34
	v_readfirstlane_b32 s34, v1
	global_load_lds_dwordx4 v[2:3], off
	v_lshl_add_u64 v[2:3], v[18:19], 0, s[36:37]
	s_mov_b32 m0, s34
	v_lshlrev_b32_e32 v1, 6, v26
	global_load_lds_dwordx4 v[2:3], off
	v_lshlrev_b32_e32 v2, 2, v26
	v_and_b32_e32 v3, 48, v26
	v_bitop3_b32 v2, v2, v3, 32 bitop3:0x6c
	s_movk_i32 s34, 0x3c0
	v_and_or_b32 v2, v1, s34, v2
	s_movk_i32 s34, 0xe000
	s_add_u32 s16, s16, 0x100
	v_and_or_b32 v91, v1, s34, v2
	v_lshlrev_b32_e32 v1, 7, v26
	s_movk_i32 s34, 0x2000
	s_addc_u32 s17, s17, 0
	s_or_b32 s2, s2, s38
	v_and_or_b32 v65, v1, s34, v2
	v_lshl_add_u64 v[2:3], s[2:3], 0, v[16:17]
	v_or_b32_e32 v2, v2, v0
	v_lshl_add_u64 v[66:67], s[16:17], 0, v[2:3]
	v_lshl_add_u64 v[2:3], s[2:3], 0, v[12:13]
	v_or_b32_e32 v2, v2, v0
	v_lshl_add_u64 v[68:69], s[16:17], 0, v[2:3]
	v_lshl_add_u64 v[2:3], s[2:3], 0, v[8:9]
	v_or_b32_e32 v2, v2, v0
	v_lshl_add_u64 v[70:71], s[16:17], 0, v[2:3]
	v_lshl_add_u64 v[2:3], s[2:3], 0, v[4:5]
	v_or_b32_e32 v2, v2, v0
	s_waitcnt vmcnt(0)
	v_lshl_add_u64 v[72:73], s[16:17], 0, v[2:3]
	s_add_u32 s2, s14, 0x100
	v_lshl_add_u64 v[2:3], s[40:41], 0, v[16:17]
	s_addc_u32 s3, s15, 0
	v_or_b32_e32 v2, v2, v0
	v_lshl_add_u64 v[74:75], s[2:3], 0, v[2:3]
	v_lshl_add_u64 v[2:3], s[40:41], 0, v[12:13]
	v_or_b32_e32 v2, v2, v0
	v_lshl_add_u64 v[76:77], s[2:3], 0, v[2:3]
	v_lshl_add_u64 v[2:3], s[40:41], 0, v[8:9]
	v_or_b32_e32 v2, v2, v0
	v_lshl_add_u64 v[78:79], s[2:3], 0, v[2:3]
	v_lshl_add_u64 v[2:3], s[40:41], 0, v[4:5]
	v_or_b32_e32 v2, v2, v0
	v_mov_b32_e32 v0, 0
	s_mov_b32 s17, s41
	v_lshl_add_u64 v[82:83], s[2:3], 0, v[2:3]
	s_mov_b64 s[2:3], 0
	s_mov_b32 s14, 0
	v_mov_b32_e32 v1, v0
	v_mov_b32_e32 v2, v0
	v_mov_b32_e32 v3, v0
	v_mov_b32_e32 v4, v0
	v_mov_b32_e32 v5, v0
	v_mov_b32_e32 v6, v0
	v_mov_b32_e32 v7, v0
	v_mov_b32_e32 v8, v0
	v_mov_b32_e32 v9, v0
	v_mov_b32_e32 v10, v0
	v_mov_b32_e32 v11, v0
	v_mov_b32_e32 v12, v0
	v_mov_b32_e32 v13, v0
	v_mov_b32_e32 v14, v0
	v_mov_b32_e32 v15, v0
	v_mov_b32_e32 v16, v0
	v_mov_b32_e32 v17, v0
	v_mov_b32_e32 v18, v0
	v_mov_b32_e32 v19, v0
	v_mov_b32_e32 v20, v0
	v_mov_b32_e32 v21, v0
	v_mov_b32_e32 v22, v0
	v_mov_b32_e32 v23, v0
	v_mov_b32_e32 v24, v0
	v_mov_b32_e32 v25, v0
	v_mov_b32_e32 v26, v0
	v_mov_b32_e32 v27, v0
	v_mov_b32_e32 v28, v0
	v_mov_b32_e32 v29, v0
	v_mov_b32_e32 v30, v0
	v_mov_b32_e32 v31, v0
	v_mov_b32_e32 v32, v0
	v_mov_b32_e32 v33, v0
	v_mov_b32_e32 v34, v0
	v_mov_b32_e32 v35, v0
	v_mov_b32_e32 v36, v0
	v_mov_b32_e32 v37, v0
	v_mov_b32_e32 v38, v0
	v_mov_b32_e32 v39, v0
	v_mov_b32_e32 v40, v0
	v_mov_b32_e32 v41, v0
	v_mov_b32_e32 v42, v0
	v_mov_b32_e32 v43, v0
	v_mov_b32_e32 v44, v0
	v_mov_b32_e32 v45, v0
	v_mov_b32_e32 v46, v0
	v_mov_b32_e32 v47, v0
	v_mov_b32_e32 v48, v0
	v_mov_b32_e32 v49, v0
	v_mov_b32_e32 v50, v0
	v_mov_b32_e32 v51, v0
	v_mov_b32_e32 v52, v0
	v_mov_b32_e32 v53, v0
	v_mov_b32_e32 v54, v0
	v_mov_b32_e32 v55, v0
	v_mov_b32_e32 v56, v0
	v_mov_b32_e32 v57, v0
	v_mov_b32_e32 v58, v0
	v_mov_b32_e32 v59, v0
	v_mov_b32_e32 v60, v0
	v_mov_b32_e32 v61, v0
	v_mov_b32_e32 v62, v0
	v_mov_b32_e32 v63, v0
	v_readfirstlane_b32 s60, v92
.LBB0_353:
	s_and_b32 s15, s14, 0x8000
	s_waitcnt vmcnt(8)
	s_barrier
	v_add_u32_e32 v93, s15, v91
	v_or_b32_e32 v128, s15, v65
	s_add_u32 s61, s60, s15
	ds_read_b128 v[94:97], v93
	ds_read_b128 v[110:113], v128 offset:16384
	ds_read_b128 v[116:119], v128 offset:18432
	ds_read_b128 v[120:123], v128 offset:20480
	ds_read_b128 v[124:127], v128 offset:22528
	ds_read_b128 v[98:101], v93 offset:2048
	ds_read_b128 v[102:105], v93 offset:4096
	ds_read_b128 v[106:109], v93 offset:6144
	s_waitcnt lgkmcnt(6)
	v_mfma_f32_16x16x32_bf16 v[60:63], v[94:97], v[110:113], v[60:63]
	ds_read_b128 v[196:199], v93 offset:1024
	s_waitcnt lgkmcnt(6)
	v_mfma_f32_16x16x32_bf16 v[56:59], v[94:97], v[116:119], v[56:59]
	ds_read_b128 v[212:215], v128 offset:17408
	s_waitcnt lgkmcnt(6)
	v_mfma_f32_16x16x32_bf16 v[52:55], v[94:97], v[120:123], v[52:55]
	ds_read_b128 v[216:219], v128 offset:19456
	s_waitcnt lgkmcnt(6)
	v_mfma_f32_16x16x32_bf16 v[48:51], v[94:97], v[124:127], v[48:51]
	ds_read_b128 v[240:243], v128 offset:21504
	ds_read_b128 v[244:247], v128 offset:23552
	s_waitcnt lgkmcnt(7)
	v_mfma_f32_16x16x32_bf16 v[44:47], v[98:101], v[110:113], v[44:47]
	v_mfma_f32_16x16x32_bf16 v[40:43], v[98:101], v[116:119], v[40:43]
	v_mfma_f32_16x16x32_bf16 v[36:39], v[98:101], v[120:123], v[36:39]
	v_mfma_f32_16x16x32_bf16 v[32:35], v[98:101], v[124:127], v[32:35]
	ds_read_b128 v[200:203], v93 offset:3072
	ds_read_b128 v[204:207], v93 offset:5120
	s_waitcnt lgkmcnt(8)
	v_mfma_f32_16x16x32_bf16 v[28:31], v[102:105], v[110:113], v[28:31]
	v_mfma_f32_16x16x32_bf16 v[24:27], v[102:105], v[116:119], v[24:27]
	v_mfma_f32_16x16x32_bf16 v[20:23], v[102:105], v[120:123], v[20:23]
	v_mfma_f32_16x16x32_bf16 v[16:19], v[102:105], v[124:127], v[16:19]
	ds_read_b128 v[208:211], v93 offset:7168
	s_waitcnt lgkmcnt(8)
	v_mfma_f32_16x16x32_bf16 v[12:15], v[106:109], v[110:113], v[12:15]
	v_mfma_f32_16x16x32_bf16 v[8:11], v[106:109], v[116:119], v[8:11]
	v_mfma_f32_16x16x32_bf16 v[4:7], v[106:109], v[120:123], v[4:7]
	v_mfma_f32_16x16x32_bf16 v[0:3], v[106:109], v[124:127], v[0:3]
	s_waitcnt lgkmcnt(0)
	s_barrier
	s_mov_b32 m0, s61
	v_lshl_add_u64 v[94:95], v[82:83], 0, s[2:3]
	v_mfma_f32_16x16x32_bf16 v[60:63], v[196:199], v[212:215], v[60:63]
	global_load_lds_dwordx4 v[94:95], off
	v_mfma_f32_16x16x32_bf16 v[56:59], v[196:199], v[216:219], v[56:59]
	s_add_u32 m0, s61, 0x1000
	v_lshl_add_u64 v[96:97], v[78:79], 0, s[2:3]
	v_mfma_f32_16x16x32_bf16 v[52:55], v[196:199], v[240:243], v[52:55]
	global_load_lds_dwordx4 v[96:97], off
	v_mfma_f32_16x16x32_bf16 v[48:51], v[196:199], v[244:247], v[48:51]
	s_add_u32 m0, s61, 0x2000
	v_lshl_add_u64 v[98:99], v[76:77], 0, s[2:3]
	v_mfma_f32_16x16x32_bf16 v[44:47], v[200:203], v[212:215], v[44:47]
	global_load_lds_dwordx4 v[98:99], off
	v_mfma_f32_16x16x32_bf16 v[40:43], v[200:203], v[216:219], v[40:43]
	s_add_u32 m0, s61, 0x3000
	v_lshl_add_u64 v[100:101], v[74:75], 0, s[2:3]
	v_mfma_f32_16x16x32_bf16 v[36:39], v[200:203], v[240:243], v[36:39]
	global_load_lds_dwordx4 v[100:101], off
	v_mfma_f32_16x16x32_bf16 v[32:35], v[200:203], v[244:247], v[32:35]
	s_add_u32 m0, s61, 0x4000
	v_lshl_add_u64 v[102:103], v[72:73], 0, s[2:3]
	v_mfma_f32_16x16x32_bf16 v[28:31], v[204:207], v[212:215], v[28:31]
	global_load_lds_dwordx4 v[102:103], off
	v_mfma_f32_16x16x32_bf16 v[24:27], v[204:207], v[216:219], v[24:27]
	s_add_u32 m0, s61, 0x5000
	v_lshl_add_u64 v[104:105], v[70:71], 0, s[2:3]
	v_mfma_f32_16x16x32_bf16 v[20:23], v[204:207], v[240:243], v[20:23]
	global_load_lds_dwordx4 v[104:105], off
	v_mfma_f32_16x16x32_bf16 v[16:19], v[204:207], v[244:247], v[16:19]
	s_add_u32 m0, s61, 0x6000
	v_lshl_add_u64 v[106:107], v[68:69], 0, s[2:3]
	v_mfma_f32_16x16x32_bf16 v[12:15], v[208:211], v[212:215], v[12:15]
	global_load_lds_dwordx4 v[106:107], off
	v_mfma_f32_16x16x32_bf16 v[8:11], v[208:211], v[216:219], v[8:11]
	s_add_u32 m0, s61, 0x7000
	v_lshl_add_u64 v[108:109], v[66:67], 0, s[2:3]
	v_mfma_f32_16x16x32_bf16 v[4:7], v[208:211], v[240:243], v[4:7]
	global_load_lds_dwordx4 v[108:109], off
	v_mfma_f32_16x16x32_bf16 v[0:3], v[208:211], v[244:247], v[0:3]
	s_add_u32 s2, s2, 0x80
	s_addc_u32 s3, s3, 0
	s_add_i32 s14, s14, 0x8000
	s_cmpk_lg_i32 s2, 0x700
	s_cbranch_scc1 .LBB0_353
	s_waitcnt vmcnt(8)
	s_barrier
	ds_read_b128 v[66:69], v91
	ds_read_b128 v[70:73], v91 offset:2048
	ds_read_b128 v[74:77], v91 offset:4096
	ds_read_b128 v[92:95], v91 offset:6144
	ds_read_b128 v[96:99], v65 offset:16384
	ds_read_b128 v[100:103], v65 offset:18432
	ds_read_b128 v[104:107], v65 offset:20480
	ds_read_b128 v[108:111], v65 offset:22528
	s_waitcnt lgkmcnt(0)
	v_mfma_f32_16x16x32_bf16 v[60:63], v[66:69], v[96:99], v[60:63]
	s_lshr_b32 s16, s13, 8
	s_and_b32 s2, s31, 0x80
	s_cmpk_lt_u32 s13, 0x100
	v_mfma_f32_16x16x32_bf16 v[56:59], v[66:69], v[100:103], v[56:59]
	v_readlane_b32 s14, v249, 30
	v_readlane_b32 s15, v249, 31
	s_mov_b32 s13, s17
	v_mfma_f32_16x16x32_bf16 v[52:55], v[66:69], v[104:107], v[52:55]
	v_mfma_f32_16x16x32_bf16 v[48:51], v[66:69], v[108:111], v[48:51]
	v_mfma_f32_16x16x32_bf16 v[44:47], v[70:73], v[96:99], v[44:47]
	v_mfma_f32_16x16x32_bf16 v[40:43], v[70:73], v[100:103], v[40:43]
	v_mfma_f32_16x16x32_bf16 v[36:39], v[70:73], v[104:107], v[36:39]
	v_mfma_f32_16x16x32_bf16 v[32:35], v[70:73], v[108:111], v[32:35]
	v_mfma_f32_16x16x32_bf16 v[28:31], v[74:77], v[96:99], v[28:31]
	v_mfma_f32_16x16x32_bf16 v[24:27], v[74:77], v[100:103], v[24:27]
	v_mfma_f32_16x16x32_bf16 v[20:23], v[74:77], v[104:107], v[20:23]
	v_mfma_f32_16x16x32_bf16 v[16:19], v[74:77], v[108:111], v[16:19]
	v_mfma_f32_16x16x32_bf16 v[12:15], v[92:95], v[96:99], v[12:15]
	v_mfma_f32_16x16x32_bf16 v[8:11], v[92:95], v[100:103], v[8:11]
	v_mfma_f32_16x16x32_bf16 v[4:7], v[92:95], v[104:107], v[4:7]
	v_mfma_f32_16x16x32_bf16 v[0:3], v[92:95], v[108:111], v[0:3]
	ds_read_b128 v[66:69], v91 offset:1024
	ds_read_b128 v[70:73], v91 offset:3072
	ds_read_b128 v[74:77], v91 offset:5120
	ds_read_b128 v[92:95], v91 offset:7168
	ds_read_b128 v[96:99], v65 offset:17408
	ds_read_b128 v[100:103], v65 offset:19456
	ds_read_b128 v[104:107], v65 offset:21504
	ds_read_b128 v[108:111], v65 offset:23552
	s_waitcnt lgkmcnt(0)
	s_barrier
	s_waitcnt lgkmcnt(3)
	v_mfma_f32_16x16x32_bf16 v[60:63], v[66:69], v[96:99], v[60:63]
	s_waitcnt vmcnt(0)
	s_barrier
	s_waitcnt lgkmcnt(2)
	v_mfma_f32_16x16x32_bf16 v[56:59], v[66:69], v[100:103], v[56:59]
	s_waitcnt lgkmcnt(1)
	v_mfma_f32_16x16x32_bf16 v[52:55], v[66:69], v[104:107], v[52:55]
	s_waitcnt lgkmcnt(0)
	v_mfma_f32_16x16x32_bf16 v[48:51], v[66:69], v[108:111], v[48:51]
	v_mfma_f32_16x16x32_bf16 v[44:47], v[70:73], v[96:99], v[44:47]
	v_mfma_f32_16x16x32_bf16 v[40:43], v[70:73], v[100:103], v[40:43]
	v_mfma_f32_16x16x32_bf16 v[36:39], v[70:73], v[104:107], v[36:39]
	v_mfma_f32_16x16x32_bf16 v[32:35], v[70:73], v[108:111], v[32:35]
	v_mfma_f32_16x16x32_bf16 v[28:31], v[74:77], v[96:99], v[28:31]
	v_mfma_f32_16x16x32_bf16 v[24:27], v[74:77], v[100:103], v[24:27]
	v_mfma_f32_16x16x32_bf16 v[20:23], v[74:77], v[104:107], v[20:23]
	v_mfma_f32_16x16x32_bf16 v[16:19], v[74:77], v[108:111], v[16:19]
	v_mfma_f32_16x16x32_bf16 v[12:15], v[92:95], v[96:99], v[12:15]
	v_mfma_f32_16x16x32_bf16 v[8:11], v[92:95], v[100:103], v[8:11]
	v_mfma_f32_16x16x32_bf16 v[4:7], v[92:95], v[104:107], v[4:7]
	v_mfma_f32_16x16x32_bf16 v[0:3], v[92:95], v[108:111], v[0:3]
	ds_read_b128 v[66:69], v91 offset:32768
	ds_read_b128 v[70:73], v91 offset:34816
	ds_read_b128 v[74:77], v91 offset:36864
	ds_read_b128 v[92:95], v91 offset:38912
	ds_read_b128 v[96:99], v65 offset:49152
	ds_read_b128 v[100:103], v65 offset:51200
	ds_read_b128 v[104:107], v65 offset:53248
	ds_read_b128 v[108:111], v65 offset:55296
	s_waitcnt lgkmcnt(3)
	v_mfma_f32_16x16x32_bf16 v[60:63], v[66:69], v[96:99], v[60:63]
	s_waitcnt lgkmcnt(2)
	v_mfma_f32_16x16x32_bf16 v[56:59], v[66:69], v[100:103], v[56:59]
	s_waitcnt lgkmcnt(1)
	v_mfma_f32_16x16x32_bf16 v[52:55], v[66:69], v[104:107], v[52:55]
	s_waitcnt lgkmcnt(0)
	v_mfma_f32_16x16x32_bf16 v[48:51], v[66:69], v[108:111], v[48:51]
	v_mfma_f32_16x16x32_bf16 v[44:47], v[70:73], v[96:99], v[44:47]
	v_mfma_f32_16x16x32_bf16 v[40:43], v[70:73], v[100:103], v[40:43]
	v_mfma_f32_16x16x32_bf16 v[36:39], v[70:73], v[104:107], v[36:39]
	v_mfma_f32_16x16x32_bf16 v[32:35], v[70:73], v[108:111], v[32:35]
	v_mfma_f32_16x16x32_bf16 v[28:31], v[74:77], v[96:99], v[28:31]
	v_mfma_f32_16x16x32_bf16 v[24:27], v[74:77], v[100:103], v[24:27]
	v_mfma_f32_16x16x32_bf16 v[20:23], v[74:77], v[104:107], v[20:23]
	v_mfma_f32_16x16x32_bf16 v[16:19], v[74:77], v[108:111], v[16:19]
	v_mfma_f32_16x16x32_bf16 v[12:15], v[92:95], v[96:99], v[12:15]
	v_mfma_f32_16x16x32_bf16 v[8:11], v[92:95], v[100:103], v[8:11]
	v_mfma_f32_16x16x32_bf16 v[4:7], v[92:95], v[104:107], v[4:7]
	v_mfma_f32_16x16x32_bf16 v[0:3], v[92:95], v[108:111], v[0:3]
	ds_read_b128 v[66:69], v91 offset:33792
	ds_read_b128 v[70:73], v91 offset:35840
	ds_read_b128 v[74:77], v91 offset:37888
	ds_read_b128 v[92:95], v91 offset:39936
	ds_read_b128 v[96:99], v65 offset:50176
	ds_read_b128 v[100:103], v65 offset:52224
	ds_read_b128 v[104:107], v65 offset:54272
	ds_read_b128 v[108:111], v65 offset:56320
	s_waitcnt lgkmcnt(0)
	s_barrier
	s_waitcnt lgkmcnt(3)
	v_mfma_f32_16x16x32_bf16 v[116:119], v[66:69], v[96:99], v[60:63]
	s_waitcnt lgkmcnt(0)
	s_barrier
	s_nop 0
	v_or_b32_e32 v61, s2, v88
	s_movk_i32 s2, 0xf8
	s_cselect_b32 s2, s2, 0x100
	s_add_u32 s2, s14, s2
	s_addc_u32 s3, s15, 0
	s_load_dwordx2 s[2:3], s[2:3], 0x0
	s_nop 0
	s_load_dwordx2 s[14:15], s[14:15], 0x158
	s_lshl_b32 s12, s12, 1
	s_or_b32 s16, s12, s16
	v_writelane_b32 v249, s12, 19
	v_lshl_add_u32 v60, s30, 7, v85
	v_mfma_f32_16x16x32_bf16 v[44:47], v[70:73], v[96:99], v[44:47]
	v_writelane_b32 v249, s13, 20
	s_lshl_b64 s[12:13], s[16:17], 18
	s_waitcnt lgkmcnt(0)
	s_add_u32 s12, s14, s12
	v_mfma_f32_16x16x32_bf16 v[40:43], v[70:73], v[100:103], v[40:43]
	s_addc_u32 s13, s15, s13
	v_lshlrev_b32_e32 v62, 2, v61
	v_or_b32_e32 v82, 3, v60
	v_mfma_f32_16x16x32_bf16 v[36:39], v[70:73], v[104:107], v[36:39]
	v_ashrrev_i32_e32 v83, 31, v82
	v_mov_b32_e32 v63, v80
	v_lshl_add_u64 v[62:63], s[2:3], 0, v[62:63]
	v_mfma_f32_16x16x32_bf16 v[32:35], v[70:73], v[108:111], v[32:35]
	v_or_b32_e32 v72, 1, v60
	v_ashrrev_i32_e32 v73, 31, v72
	v_bfe_u32 v65, v116, 16, 1
	v_mfma_f32_16x16x32_bf16 v[56:59], v[66:69], v[100:103], v[56:59]
	v_add3_u32 v65, v116, v65, s33
	s_mov_b64 s[2:3], 0
	v_mfma_f32_16x16x32_bf16 v[52:55], v[66:69], v[104:107], v[52:55]
	v_mfma_f32_16x16x32_bf16 v[48:51], v[66:69], v[108:111], v[48:51]
	v_lshlrev_b32_e32 v66, 1, v61
	v_mov_b32_e32 v67, v80
	v_ashrrev_i32_e32 v61, 31, v60
	v_mfma_f32_16x16x32_bf16 v[28:31], v[74:77], v[96:99], v[28:31]
	v_lshl_add_u64 v[66:67], s[12:13], 0, v[66:67]
	v_lshl_add_u64 v[68:69], s[10:11], 0, v[60:61]
	v_lshlrev_b64 v[70:71], 9, v[60:61]
	v_mfma_f32_16x16x32_bf16 v[24:27], v[74:77], v[100:103], v[24:27]
	v_bfe_u32 v61, v117, 16, 1
	v_add3_u32 v61, v117, v61, s33
	v_lshlrev_b64 v[68:69], 10, v[68:69]
	v_mfma_f32_16x16x32_bf16 v[20:23], v[74:77], v[104:107], v[20:23]
	v_lshl_add_u64 v[68:69], v[62:63], 0, v[68:69]
	v_lshl_add_u64 v[70:71], v[66:67], 0, v[70:71]
	global_store_dword v[68:69], v116, off
	v_mfma_f32_16x16x32_bf16 v[16:19], v[74:77], v[108:111], v[16:19]
	v_lshl_add_u64 v[74:75], s[10:11], 0, v[72:73]
	v_lshlrev_b64 v[72:73], 9, v[72:73]
	v_or_b32_e32 v76, 2, v60
	v_lshl_add_u64 v[72:73], v[66:67], 0, v[72:73]
	v_ashrrev_i32_e32 v77, 31, v76
	global_store_short_d16_hi v[72:73], v61, off
	v_lshl_add_u64 v[78:79], s[10:11], 0, v[76:77]
	v_bfe_u32 v61, v118, 16, 1
	v_lshlrev_b64 v[76:77], 9, v[76:77]
	v_mfma_f32_16x16x32_bf16 v[12:15], v[92:95], v[96:99], v[12:15]
	v_add3_u32 v61, v118, v61, s33
	v_lshl_add_u64 v[76:77], v[66:67], 0, v[76:77]
	v_lshlrev_b64 v[74:75], 10, v[74:75]
	v_mfma_f32_16x16x32_bf16 v[8:11], v[92:95], v[100:103], v[8:11]
	v_lshlrev_b64 v[78:79], 10, v[78:79]
	global_store_short_d16_hi v[76:77], v61, off
	v_bfe_u32 v61, v119, 16, 1
	v_mfma_f32_16x16x32_bf16 v[4:7], v[92:95], v[104:107], v[4:7]
	v_lshl_add_u64 v[74:75], v[62:63], 0, v[74:75]
	v_lshl_add_u64 v[78:79], v[62:63], 0, v[78:79]
	v_add3_u32 v61, v119, v61, s33
	v_mfma_f32_16x16x32_bf16 v[0:3], v[92:95], v[108:111], v[0:3]
	v_lshl_add_u64 v[92:93], s[10:11], 0, v[82:83]
	v_lshlrev_b64 v[92:93], 10, v[92:93]
	v_lshlrev_b64 v[82:83], 9, v[82:83]
	v_lshl_add_u64 v[92:93], v[62:63], 0, v[92:93]
	v_lshl_add_u64 v[82:83], v[66:67], 0, v[82:83]
	global_store_short_d16_hi v[70:71], v65, off
	global_store_dword v[74:75], v117, off
	global_store_dword v[78:79], v118, off
	global_store_dword v[92:93], v119, off
	global_store_short_d16_hi v[82:83], v61, off
	global_store_dword v[68:69], v56, off offset:64
	v_bfe_u32 v61, v56, 16, 1
	v_add3_u32 v56, v56, v61, s33
	global_store_short_d16_hi v[70:71], v56, off offset:32
	global_store_dword v[74:75], v57, off offset:64
	v_bfe_u32 v56, v57, 16, 1
	v_add3_u32 v56, v57, v56, s33
	global_store_short_d16_hi v[72:73], v56, off offset:32
	global_store_dword v[78:79], v58, off offset:64
	v_bfe_u32 v56, v58, 16, 1
	v_add3_u32 v56, v58, v56, s33
	global_store_short_d16_hi v[76:77], v56, off offset:32
	global_store_dword v[92:93], v59, off offset:64
	v_bfe_u32 v56, v59, 16, 1
	v_add3_u32 v56, v59, v56, s33
	global_store_short_d16_hi v[82:83], v56, off offset:32
	global_store_dword v[68:69], v52, off offset:128
	v_bfe_u32 v56, v52, 16, 1
	v_add3_u32 v52, v52, v56, s33
	global_store_short_d16_hi v[70:71], v52, off offset:64
	global_store_dword v[74:75], v53, off offset:128
	v_bfe_u32 v52, v53, 16, 1
	v_add3_u32 v52, v53, v52, s33
	global_store_short_d16_hi v[72:73], v52, off offset:64
	global_store_dword v[78:79], v54, off offset:128
	v_bfe_u32 v52, v54, 16, 1
	v_add3_u32 v52, v54, v52, s33
	global_store_short_d16_hi v[76:77], v52, off offset:64
	global_store_dword v[92:93], v55, off offset:128
	v_bfe_u32 v52, v55, 16, 1
	v_add3_u32 v52, v55, v52, s33
	global_store_short_d16_hi v[82:83], v52, off offset:64
	global_store_dword v[68:69], v48, off offset:192
	v_bfe_u32 v52, v48, 16, 1
	v_add3_u32 v48, v48, v52, s33
	global_store_short_d16_hi v[70:71], v48, off offset:96
	global_store_dword v[74:75], v49, off offset:192
	v_bfe_u32 v48, v49, 16, 1
	v_add3_u32 v48, v49, v48, s33
	global_store_short_d16_hi v[72:73], v48, off offset:96
	global_store_dword v[78:79], v50, off offset:192
	v_bfe_u32 v48, v50, 16, 1
	v_add3_u32 v48, v50, v48, s33
	global_store_short_d16_hi v[76:77], v48, off offset:96
	global_store_dword v[92:93], v51, off offset:192
	v_bfe_u32 v48, v51, 16, 1
	v_add3_u32 v48, v51, v48, s33
	global_store_short_d16_hi v[82:83], v48, off offset:96
	v_or_b32_e32 v48, 16, v60
	v_ashrrev_i32_e32 v49, 31, v48
	v_lshl_add_u64 v[50:51], s[10:11], 0, v[48:49]
	v_lshlrev_b64 v[50:51], 10, v[50:51]
	v_lshl_add_u64 v[50:51], v[62:63], 0, v[50:51]
	v_bfe_u32 v52, v44, 16, 1
	global_store_dword v[50:51], v44, off
	v_add3_u32 v44, v44, v52, s33
	v_or_b32_e32 v52, 17, v60
	v_ashrrev_i32_e32 v53, 31, v52
	v_lshlrev_b64 v[48:49], 9, v[48:49]
	v_lshl_add_u64 v[54:55], s[10:11], 0, v[52:53]
	v_lshl_add_u64 v[48:49], v[66:67], 0, v[48:49]
	v_lshlrev_b64 v[54:55], 10, v[54:55]
	global_store_short_d16_hi v[48:49], v44, off
	v_lshl_add_u64 v[54:55], v[62:63], 0, v[54:55]
	v_bfe_u32 v44, v45, 16, 1
	global_store_dword v[54:55], v45, off
	v_add3_u32 v56, v45, v44, s33
	v_lshlrev_b64 v[44:45], 9, v[52:53]
	v_or_b32_e32 v52, 18, v60
	v_lshl_add_u64 v[44:45], v[66:67], 0, v[44:45]
	v_ashrrev_i32_e32 v53, 31, v52
	global_store_short_d16_hi v[44:45], v56, off
	v_lshl_add_u64 v[56:57], s[10:11], 0, v[52:53]
	v_lshlrev_b64 v[56:57], 10, v[56:57]
	v_lshl_add_u64 v[56:57], v[62:63], 0, v[56:57]
	v_bfe_u32 v58, v46, 16, 1
	global_store_dword v[56:57], v46, off
	v_add3_u32 v46, v46, v58, s33
	v_or_b32_e32 v58, 19, v60
	v_ashrrev_i32_e32 v59, 31, v58
	v_lshlrev_b64 v[52:53], 9, v[52:53]
	v_lshl_add_u64 v[68:69], s[10:11], 0, v[58:59]
	v_lshl_add_u64 v[52:53], v[66:67], 0, v[52:53]
	v_lshlrev_b64 v[68:69], 10, v[68:69]
	global_store_short_d16_hi v[52:53], v46, off
	v_lshl_add_u64 v[68:69], v[62:63], 0, v[68:69]
	v_bfe_u32 v46, v47, 16, 1
	global_store_dword v[68:69], v47, off
	v_add3_u32 v61, v47, v46, s33
	v_lshlrev_b64 v[46:47], 9, v[58:59]
	v_lshl_add_u64 v[46:47], v[66:67], 0, v[46:47]
	v_bfe_u32 v58, v40, 16, 1
	global_store_short_d16_hi v[46:47], v61, off
	global_store_dword v[50:51], v40, off offset:64
	v_add3_u32 v40, v40, v58, s33
	global_store_short_d16_hi v[48:49], v40, off offset:32
	global_store_dword v[54:55], v41, off offset:64
	v_bfe_u32 v40, v41, 16, 1
	v_add3_u32 v40, v41, v40, s33
	global_store_short_d16_hi v[44:45], v40, off offset:32
	global_store_dword v[56:57], v42, off offset:64
	v_bfe_u32 v40, v42, 16, 1
	v_add3_u32 v40, v42, v40, s33
	global_store_short_d16_hi v[52:53], v40, off offset:32
	global_store_dword v[68:69], v43, off offset:64
	v_bfe_u32 v40, v43, 16, 1
	v_add3_u32 v40, v43, v40, s33
	global_store_short_d16_hi v[46:47], v40, off offset:32
	global_store_dword v[50:51], v36, off offset:128
	v_bfe_u32 v40, v36, 16, 1
	v_add3_u32 v36, v36, v40, s33
	global_store_short_d16_hi v[48:49], v36, off offset:64
	global_store_dword v[54:55], v37, off offset:128
	v_bfe_u32 v36, v37, 16, 1
	v_add3_u32 v36, v37, v36, s33
	global_store_short_d16_hi v[44:45], v36, off offset:64
	global_store_dword v[56:57], v38, off offset:128
	v_bfe_u32 v36, v38, 16, 1
	v_add3_u32 v36, v38, v36, s33
	global_store_short_d16_hi v[52:53], v36, off offset:64
	global_store_dword v[68:69], v39, off offset:128
	v_bfe_u32 v36, v39, 16, 1
	v_add3_u32 v36, v39, v36, s33
	global_store_short_d16_hi v[46:47], v36, off offset:64
	global_store_dword v[50:51], v32, off offset:192
	v_bfe_u32 v36, v32, 16, 1
	v_add3_u32 v32, v32, v36, s33
	global_store_short_d16_hi v[48:49], v32, off offset:96
	global_store_dword v[54:55], v33, off offset:192
	v_bfe_u32 v32, v33, 16, 1
	v_add3_u32 v32, v33, v32, s33
	global_store_short_d16_hi v[44:45], v32, off offset:96
	global_store_dword v[56:57], v34, off offset:192
	v_bfe_u32 v32, v34, 16, 1
	v_add3_u32 v32, v34, v32, s33
	global_store_short_d16_hi v[52:53], v32, off offset:96
	global_store_dword v[68:69], v35, off offset:192
	v_bfe_u32 v32, v35, 16, 1
	v_add3_u32 v32, v35, v32, s33
	global_store_short_d16_hi v[46:47], v32, off offset:96
	v_or_b32_e32 v32, 32, v60
	v_ashrrev_i32_e32 v33, 31, v32
	v_lshl_add_u64 v[34:35], s[10:11], 0, v[32:33]
	v_lshlrev_b64 v[34:35], 10, v[34:35]
	v_lshl_add_u64 v[34:35], v[62:63], 0, v[34:35]
	v_bfe_u32 v36, v28, 16, 1
	global_store_dword v[34:35], v28, off
	v_add3_u32 v28, v28, v36, s33
	v_or_b32_e32 v36, 33, v60
	v_ashrrev_i32_e32 v37, 31, v36
	v_lshlrev_b64 v[32:33], 9, v[32:33]
	v_lshl_add_u64 v[38:39], s[10:11], 0, v[36:37]
	v_lshl_add_u64 v[32:33], v[66:67], 0, v[32:33]
	v_lshlrev_b64 v[38:39], 10, v[38:39]
	global_store_short_d16_hi v[32:33], v28, off
	v_lshl_add_u64 v[38:39], v[62:63], 0, v[38:39]
	v_bfe_u32 v28, v29, 16, 1
	global_store_dword v[38:39], v29, off
	v_add3_u32 v40, v29, v28, s33
	v_lshlrev_b64 v[28:29], 9, v[36:37]
	v_or_b32_e32 v36, 34, v60
	v_lshl_add_u64 v[28:29], v[66:67], 0, v[28:29]
	v_ashrrev_i32_e32 v37, 31, v36
	global_store_short_d16_hi v[28:29], v40, off
	v_lshl_add_u64 v[40:41], s[10:11], 0, v[36:37]
	v_lshlrev_b64 v[40:41], 10, v[40:41]
	v_lshl_add_u64 v[40:41], v[62:63], 0, v[40:41]
	v_bfe_u32 v42, v30, 16, 1
	global_store_dword v[40:41], v30, off
	v_add3_u32 v30, v30, v42, s33
	v_or_b32_e32 v42, 35, v60
	v_ashrrev_i32_e32 v43, 31, v42
	v_lshlrev_b64 v[36:37], 9, v[36:37]
	v_lshl_add_u64 v[44:45], s[10:11], 0, v[42:43]
	v_lshl_add_u64 v[36:37], v[66:67], 0, v[36:37]
	v_lshlrev_b64 v[44:45], 10, v[44:45]
	global_store_short_d16_hi v[36:37], v30, off
	v_lshl_add_u64 v[44:45], v[62:63], 0, v[44:45]
	v_bfe_u32 v30, v31, 16, 1
	global_store_dword v[44:45], v31, off
	v_add3_u32 v46, v31, v30, s33
	v_lshlrev_b64 v[30:31], 9, v[42:43]
	v_lshl_add_u64 v[30:31], v[66:67], 0, v[30:31]
	v_bfe_u32 v42, v24, 16, 1
	global_store_short_d16_hi v[30:31], v46, off
	global_store_dword v[34:35], v24, off offset:64
	v_add3_u32 v24, v24, v42, s33
	global_store_short_d16_hi v[32:33], v24, off offset:32
	global_store_dword v[38:39], v25, off offset:64
	v_bfe_u32 v24, v25, 16, 1
	v_add3_u32 v24, v25, v24, s33
	global_store_short_d16_hi v[28:29], v24, off offset:32
	global_store_dword v[40:41], v26, off offset:64
	v_bfe_u32 v24, v26, 16, 1
	v_add3_u32 v24, v26, v24, s33
	global_store_short_d16_hi v[36:37], v24, off offset:32
	global_store_dword v[44:45], v27, off offset:64
	v_bfe_u32 v24, v27, 16, 1
	v_add3_u32 v24, v27, v24, s33
	global_store_short_d16_hi v[30:31], v24, off offset:32
	global_store_dword v[34:35], v20, off offset:128
	v_bfe_u32 v24, v20, 16, 1
	v_add3_u32 v20, v20, v24, s33
	global_store_short_d16_hi v[32:33], v20, off offset:64
	global_store_dword v[38:39], v21, off offset:128
	v_bfe_u32 v20, v21, 16, 1
	v_add3_u32 v20, v21, v20, s33
	global_store_short_d16_hi v[28:29], v20, off offset:64
	global_store_dword v[40:41], v22, off offset:128
	v_bfe_u32 v20, v22, 16, 1
	v_add3_u32 v20, v22, v20, s33
	global_store_short_d16_hi v[36:37], v20, off offset:64
	global_store_dword v[44:45], v23, off offset:128
	v_bfe_u32 v20, v23, 16, 1
	v_add3_u32 v20, v23, v20, s33
	global_store_short_d16_hi v[30:31], v20, off offset:64
	global_store_dword v[34:35], v16, off offset:192
	v_bfe_u32 v20, v16, 16, 1
	v_add3_u32 v16, v16, v20, s33
	global_store_short_d16_hi v[32:33], v16, off offset:96
	global_store_dword v[38:39], v17, off offset:192
	v_bfe_u32 v16, v17, 16, 1
	v_add3_u32 v16, v17, v16, s33
	global_store_short_d16_hi v[28:29], v16, off offset:96
	global_store_dword v[40:41], v18, off offset:192
	v_bfe_u32 v16, v18, 16, 1
	v_add3_u32 v16, v18, v16, s33
	global_store_short_d16_hi v[36:37], v16, off offset:96
	global_store_dword v[44:45], v19, off offset:192
	v_bfe_u32 v16, v19, 16, 1
	v_add3_u32 v16, v19, v16, s33
	global_store_short_d16_hi v[30:31], v16, off offset:96
	v_or_b32_e32 v16, 48, v60
	v_ashrrev_i32_e32 v17, 31, v16
	v_lshl_add_u64 v[18:19], s[10:11], 0, v[16:17]
	v_lshlrev_b64 v[18:19], 10, v[18:19]
	v_lshl_add_u64 v[18:19], v[62:63], 0, v[18:19]
	v_bfe_u32 v20, v12, 16, 1
	global_store_dword v[18:19], v12, off
	v_add3_u32 v12, v12, v20, s33
	v_or_b32_e32 v20, 49, v60
	v_ashrrev_i32_e32 v21, 31, v20
	v_lshlrev_b64 v[16:17], 9, v[16:17]
	v_lshl_add_u64 v[22:23], s[10:11], 0, v[20:21]
	v_lshl_add_u64 v[16:17], v[66:67], 0, v[16:17]
	v_lshlrev_b64 v[22:23], 10, v[22:23]
	global_store_short_d16_hi v[16:17], v12, off
	v_lshl_add_u64 v[22:23], v[62:63], 0, v[22:23]
	v_bfe_u32 v12, v13, 16, 1
	global_store_dword v[22:23], v13, off
	v_add3_u32 v24, v13, v12, s33
	v_lshlrev_b64 v[12:13], 9, v[20:21]
	v_or_b32_e32 v20, 50, v60
	v_lshl_add_u64 v[12:13], v[66:67], 0, v[12:13]
	v_ashrrev_i32_e32 v21, 31, v20
	global_store_short_d16_hi v[12:13], v24, off
	v_lshl_add_u64 v[24:25], s[10:11], 0, v[20:21]
	v_lshlrev_b64 v[24:25], 10, v[24:25]
	v_lshl_add_u64 v[24:25], v[62:63], 0, v[24:25]
	v_bfe_u32 v26, v14, 16, 1
	global_store_dword v[24:25], v14, off
	v_add3_u32 v14, v14, v26, s33
	v_or_b32_e32 v26, 51, v60
	v_ashrrev_i32_e32 v27, 31, v26
	v_lshlrev_b64 v[20:21], 9, v[20:21]
	v_lshl_add_u64 v[28:29], s[10:11], 0, v[26:27]
	v_lshl_add_u64 v[20:21], v[66:67], 0, v[20:21]
	v_lshlrev_b64 v[28:29], 10, v[28:29]
	global_store_short_d16_hi v[20:21], v14, off
	v_lshl_add_u64 v[28:29], v[62:63], 0, v[28:29]
	v_bfe_u32 v14, v15, 16, 1
	global_store_dword v[28:29], v15, off
	v_add3_u32 v30, v15, v14, s33
	v_lshlrev_b64 v[14:15], 9, v[26:27]
	v_lshl_add_u64 v[14:15], v[66:67], 0, v[14:15]
	v_bfe_u32 v26, v8, 16, 1
	global_store_short_d16_hi v[14:15], v30, off
	global_store_dword v[18:19], v8, off offset:64
	v_add3_u32 v8, v8, v26, s33
	global_store_short_d16_hi v[16:17], v8, off offset:32
	global_store_dword v[22:23], v9, off offset:64
	v_bfe_u32 v8, v9, 16, 1
	v_add3_u32 v8, v9, v8, s33
	global_store_short_d16_hi v[12:13], v8, off offset:32
	global_store_dword v[24:25], v10, off offset:64
	v_bfe_u32 v8, v10, 16, 1
	v_add3_u32 v8, v10, v8, s33
	global_store_short_d16_hi v[20:21], v8, off offset:32
	global_store_dword v[28:29], v11, off offset:64
	v_bfe_u32 v8, v11, 16, 1
	v_add3_u32 v8, v11, v8, s33
	global_store_short_d16_hi v[14:15], v8, off offset:32
	global_store_dword v[18:19], v4, off offset:128
	v_bfe_u32 v8, v4, 16, 1
	v_add3_u32 v4, v4, v8, s33
	global_store_short_d16_hi v[16:17], v4, off offset:64
	global_store_dword v[22:23], v5, off offset:128
	v_bfe_u32 v4, v5, 16, 1
	v_add3_u32 v4, v5, v4, s33
	global_store_short_d16_hi v[12:13], v4, off offset:64
	global_store_dword v[24:25], v6, off offset:128
	v_bfe_u32 v4, v6, 16, 1
	v_add3_u32 v4, v6, v4, s33
	global_store_short_d16_hi v[20:21], v4, off offset:64
	global_store_dword v[28:29], v7, off offset:128
	v_bfe_u32 v4, v7, 16, 1
	v_add3_u32 v4, v7, v4, s33
	global_store_short_d16_hi v[14:15], v4, off offset:64
	global_store_dword v[18:19], v0, off offset:192
	v_bfe_u32 v4, v0, 16, 1
	v_add3_u32 v0, v0, v4, s33
	global_store_short_d16_hi v[16:17], v0, off offset:96
	global_store_dword v[22:23], v1, off offset:192
	v_bfe_u32 v0, v1, 16, 1
	v_add3_u32 v0, v1, v0, s33
	global_store_short_d16_hi v[12:13], v0, off offset:96
	global_store_dword v[24:25], v2, off offset:192
	v_bfe_u32 v0, v2, 16, 1
	v_add3_u32 v0, v2, v0, s33
	global_store_short_d16_hi v[20:21], v0, off offset:96
	global_store_dword v[28:29], v3, off offset:192
	v_bfe_u32 v0, v3, 16, 1
	v_add3_u32 v0, v3, v0, s33
	global_store_short_d16_hi v[14:15], v0, off offset:96
